# GEMM K loops: reversed priority - s_setprio 1 while a wave runs its loader segment (ds_read burst + LDS-DMA issue), 0 during its MFMA segment; hipcc's flips (1 during MFMA) deleted
# speedup vs baseline: 1.0009x; 1.0009x over previous
.LBB0_311:
	s_setprio 1
	s_add_u32 s4, s62, 0xfffc0080
	s_addc_u32 s5, s63, -1
	s_add_i32 s84, 0, 0x10000
	s_cmp_eq_u32 s82, 12
	s_cselect_b32 s65, s33, s5
	s_cselect_b32 s64, s36, s4
	s_cselect_b32 s35, s53, s79
	s_cselect_b32 s34, s55, s75
	s_add_i32 s4, 0, 0x14000
	v_add_u32_e32 v164, s84, v143
	v_add_u32_e32 v180, s4, v143
	ds_read_b128 v[138:141], v164
	ds_read_b128 v[156:159], v164 offset:1024
	ds_read_b128 v[160:163], v164 offset:2048
	ds_read_b128 v[164:167], v164 offset:3072
	ds_read_b128 v[168:171], v180
	ds_read_b128 v[172:175], v180 offset:1024
	ds_read_b128 v[176:179], v180 offset:2048
	ds_read_b128 v[204:207], v180 offset:3072
	v_lshl_add_u64 v[180:181], s[62:63], 0, v[134:135]
	s_add_i32 m0, s68, 0xc000
	ds_read_b128 v[208:211], v155
	ds_read_b128 v[212:215], v155 offset:1024
	ds_read_b128 v[216:219], v155 offset:2048
	ds_read_b128 v[220:223], v155 offset:3072
	ds_read_b128 v[224:227], v155 offset:4096
	ds_read_b128 v[228:231], v155 offset:5120
	ds_read_b128 v[232:235], v155 offset:6144
	ds_read_b128 v[236:239], v155 offset:7168
	global_load_lds_dwordx4 v[180:181], off
	v_lshl_add_u64 v[180:181], s[62:63], 0, v[136:137]
	s_add_i32 m0, s68, 0xe000
	s_nop 0
	global_load_lds_dwordx4 v[180:181], off
	s_setprio 0
	s_waitcnt vmcnt(8)
	s_waitcnt lgkmcnt(0)
	s_barrier
	s_waitcnt lgkmcnt(0)
	v_mfma_f32_16x16x32_bf16 v[124:127], v[138:141], v[208:211], v[124:127]
	v_mfma_f32_16x16x32_bf16 v[120:123], v[160:163], v[208:211], v[120:123]
	v_mfma_f32_16x16x32_bf16 v[108:111], v[138:141], v[216:219], v[108:111]
	v_mfma_f32_16x16x32_bf16 v[104:107], v[160:163], v[216:219], v[104:107]
	v_mfma_f32_16x16x32_bf16 v[92:95], v[138:141], v[224:227], v[92:95]
	v_mfma_f32_16x16x32_bf16 v[88:91], v[160:163], v[224:227], v[88:91]
	v_mfma_f32_16x16x32_bf16 v[76:79], v[138:141], v[232:235], v[76:79]
	v_mfma_f32_16x16x32_bf16 v[72:75], v[160:163], v[232:235], v[72:75]
	v_mfma_f32_16x16x32_bf16 v[124:127], v[156:159], v[212:215], v[124:127]
	v_mfma_f32_16x16x32_bf16 v[120:123], v[164:167], v[212:215], v[120:123]
	v_mfma_f32_16x16x32_bf16 v[108:111], v[156:159], v[220:223], v[108:111]
	v_mfma_f32_16x16x32_bf16 v[104:107], v[164:167], v[220:223], v[104:107]
	v_mfma_f32_16x16x32_bf16 v[92:95], v[156:159], v[228:231], v[92:95]
	v_mfma_f32_16x16x32_bf16 v[88:91], v[164:167], v[228:231], v[88:91]
	v_mfma_f32_16x16x32_bf16 v[76:79], v[156:159], v[236:239], v[76:79]
	v_mfma_f32_16x16x32_bf16 v[72:75], v[164:167], v[236:239], v[72:75]
	v_mfma_f32_16x16x32_bf16 v[116:119], v[168:171], v[208:211], v[116:119]
	v_mfma_f32_16x16x32_bf16 v[112:115], v[176:179], v[208:211], v[112:115]
	v_mfma_f32_16x16x32_bf16 v[100:103], v[168:171], v[216:219], v[100:103]
	v_mfma_f32_16x16x32_bf16 v[96:99], v[176:179], v[216:219], v[96:99]
	v_mfma_f32_16x16x32_bf16 v[84:87], v[168:171], v[224:227], v[84:87]
	v_mfma_f32_16x16x32_bf16 v[80:83], v[176:179], v[224:227], v[80:83]
	v_mfma_f32_16x16x32_bf16 v[68:71], v[168:171], v[232:235], v[68:71]
	v_mfma_f32_16x16x32_bf16 v[64:67], v[176:179], v[232:235], v[64:67]
	v_mfma_f32_16x16x32_bf16 v[116:119], v[172:175], v[212:215], v[116:119]
	v_mfma_f32_16x16x32_bf16 v[112:115], v[204:207], v[212:215], v[112:115]
	v_mfma_f32_16x16x32_bf16 v[100:103], v[172:175], v[220:223], v[100:103]
	v_mfma_f32_16x16x32_bf16 v[96:99], v[204:207], v[220:223], v[96:99]
	v_mfma_f32_16x16x32_bf16 v[84:87], v[172:175], v[228:231], v[84:87]
	v_mfma_f32_16x16x32_bf16 v[80:83], v[204:207], v[228:231], v[80:83]
	v_mfma_f32_16x16x32_bf16 v[68:71], v[172:175], v[236:239], v[68:71]
	v_mfma_f32_16x16x32_bf16 v[64:67], v[204:207], v[236:239], v[64:67]
	s_barrier
	s_setprio 1
	s_add_i32 s5, s84, s28
	v_lshl_add_u64 v[180:181], s[34:35], 0, v[144:145]
	s_mov_b32 m0, s5
	ds_read_b128 v[208:211], v155 offset:16384
	ds_read_b128 v[212:215], v155 offset:17408
	ds_read_b128 v[216:219], v155 offset:18432
	ds_read_b128 v[220:223], v155 offset:19456
	ds_read_b128 v[224:227], v155 offset:20480
	ds_read_b128 v[228:231], v155 offset:21504
	ds_read_b128 v[232:235], v155 offset:22528
	ds_read_b128 v[236:239], v155 offset:23552
	global_load_lds_dwordx4 v[180:181], off
	s_add_i32 m0, s5, 0x2000
	s_add_u32 s88, s34, 0x40000
	v_lshl_add_u64 v[240:241], s[34:35], 0, v[128:129]
	s_addc_u32 s89, s35, 0
	s_add_i32 s4, s4, s28
	global_load_lds_dwordx4 v[240:241], off
	v_lshl_add_u64 v[242:243], s[88:89], 0, v[144:145]
	s_mov_b32 m0, s4
	v_lshl_add_u64 v[244:245], s[64:65], 0, v[130:131]
	global_load_lds_dwordx4 v[242:243], off
	v_lshl_add_u64 v[242:243], s[88:89], 0, v[128:129]
	s_add_i32 m0, s4, 0x2000
	s_nop 0
	global_load_lds_dwordx4 v[242:243], off
	v_lshl_add_u64 v[242:243], s[64:65], 0, v[132:133]
	s_mov_b32 m0, s68
	s_nop 0
	global_load_lds_dwordx4 v[242:243], off
	s_mov_b32 m0, s69
	s_nop 0
	global_load_lds_dwordx4 v[244:245], off
	s_setprio 0
	s_waitcnt vmcnt(8)
	s_waitcnt lgkmcnt(0)
	s_barrier
	s_waitcnt lgkmcnt(0)
	v_mfma_f32_16x16x32_bf16 v[60:63], v[138:141], v[208:211], v[60:63]
	v_mfma_f32_16x16x32_bf16 v[56:59], v[160:163], v[208:211], v[56:59]
	v_mfma_f32_16x16x32_bf16 v[44:47], v[138:141], v[216:219], v[44:47]
	v_mfma_f32_16x16x32_bf16 v[40:43], v[160:163], v[216:219], v[40:43]
	v_mfma_f32_16x16x32_bf16 v[28:31], v[138:141], v[224:227], v[28:31]
	v_mfma_f32_16x16x32_bf16 v[24:27], v[160:163], v[224:227], v[24:27]
	v_mfma_f32_16x16x32_bf16 v[12:15], v[138:141], v[232:235], v[12:15]
	v_mfma_f32_16x16x32_bf16 v[8:11], v[160:163], v[232:235], v[8:11]
	v_mfma_f32_16x16x32_bf16 v[60:63], v[156:159], v[212:215], v[60:63]
	v_mfma_f32_16x16x32_bf16 v[56:59], v[164:167], v[212:215], v[56:59]
	v_mfma_f32_16x16x32_bf16 v[44:47], v[156:159], v[220:223], v[44:47]
	v_mfma_f32_16x16x32_bf16 v[40:43], v[164:167], v[220:223], v[40:43]
	v_mfma_f32_16x16x32_bf16 v[28:31], v[156:159], v[228:231], v[28:31]
	v_mfma_f32_16x16x32_bf16 v[24:27], v[164:167], v[228:231], v[24:27]
	v_mfma_f32_16x16x32_bf16 v[12:15], v[156:159], v[236:239], v[12:15]
	v_mfma_f32_16x16x32_bf16 v[8:11], v[164:167], v[236:239], v[8:11]
	v_mfma_f32_16x16x32_bf16 v[52:55], v[168:171], v[208:211], v[52:55]
	v_mfma_f32_16x16x32_bf16 v[48:51], v[176:179], v[208:211], v[48:51]
	v_mfma_f32_16x16x32_bf16 v[36:39], v[168:171], v[216:219], v[36:39]
	v_mfma_f32_16x16x32_bf16 v[32:35], v[176:179], v[216:219], v[32:35]
	v_mfma_f32_16x16x32_bf16 v[20:23], v[168:171], v[224:227], v[20:23]
	v_mfma_f32_16x16x32_bf16 v[16:19], v[176:179], v[224:227], v[16:19]
	v_mfma_f32_16x16x32_bf16 v[4:7], v[168:171], v[232:235], v[4:7]
	v_mfma_f32_16x16x32_bf16 v[0:3], v[176:179], v[232:235], v[0:3]
	v_mfma_f32_16x16x32_bf16 v[52:55], v[172:175], v[212:215], v[52:55]
	v_mfma_f32_16x16x32_bf16 v[48:51], v[204:207], v[212:215], v[48:51]
	v_mfma_f32_16x16x32_bf16 v[36:39], v[172:175], v[220:223], v[36:39]
	v_mfma_f32_16x16x32_bf16 v[32:35], v[204:207], v[220:223], v[32:35]
	v_mfma_f32_16x16x32_bf16 v[20:23], v[172:175], v[228:231], v[20:23]
	v_mfma_f32_16x16x32_bf16 v[16:19], v[204:207], v[228:231], v[16:19]
	v_mfma_f32_16x16x32_bf16 v[4:7], v[172:175], v[236:239], v[4:7]
	v_mfma_f32_16x16x32_bf16 v[0:3], v[204:207], v[236:239], v[0:3]
	s_barrier
	s_setprio 1
	s_add_i32 s4, 0, 0x18000
	s_add_i32 s5, 0, 0x1c000
	v_add_u32_e32 v164, s4, v143
	v_add_u32_e32 v202, s5, v143
	ds_read_b128 v[138:141], v164
	ds_read_b128 v[156:159], v164 offset:1024
	ds_read_b128 v[160:163], v164 offset:2048
	ds_read_b128 v[164:167], v164 offset:3072
	ds_read_b128 v[168:171], v202
	ds_read_b128 v[172:175], v202 offset:1024
	ds_read_b128 v[176:179], v202 offset:2048
	ds_read_b128 v[204:207], v202 offset:3072
	s_add_u32 s64, s64, 0x40000
	s_addc_u32 s65, s65, 0
	s_mov_b32 m0, s70
	v_lshl_add_u64 v[246:247], s[64:65], 0, v[132:133]
	ds_read_b128 v[208:211], v155 offset:32768
	ds_read_b128 v[212:215], v155 offset:33792
	ds_read_b128 v[216:219], v155 offset:34816
	ds_read_b128 v[220:223], v155 offset:35840
	ds_read_b128 v[224:227], v155 offset:36864
	ds_read_b128 v[228:231], v155 offset:37888
	ds_read_b128 v[232:235], v155 offset:38912
	ds_read_b128 v[236:239], v155 offset:39936
	global_load_lds_dwordx4 v[246:247], off
	v_lshl_add_u64 v[246:247], s[64:65], 0, v[130:131]
	s_mov_b32 m0, s71
	s_nop 0
	global_load_lds_dwordx4 v[246:247], off
	s_setprio 0
	s_waitcnt vmcnt(8)
	s_waitcnt lgkmcnt(0)
	s_barrier
	s_waitcnt lgkmcnt(0)
	v_mfma_f32_16x16x32_bf16 v[124:127], v[138:141], v[208:211], v[124:127]
	v_mfma_f32_16x16x32_bf16 v[120:123], v[160:163], v[208:211], v[120:123]
	v_mfma_f32_16x16x32_bf16 v[108:111], v[138:141], v[216:219], v[108:111]
	v_mfma_f32_16x16x32_bf16 v[104:107], v[160:163], v[216:219], v[104:107]
	v_mfma_f32_16x16x32_bf16 v[92:95], v[138:141], v[224:227], v[92:95]
	v_mfma_f32_16x16x32_bf16 v[88:91], v[160:163], v[224:227], v[88:91]
	v_mfma_f32_16x16x32_bf16 v[76:79], v[138:141], v[232:235], v[76:79]
	v_mfma_f32_16x16x32_bf16 v[72:75], v[160:163], v[232:235], v[72:75]
	v_mfma_f32_16x16x32_bf16 v[124:127], v[156:159], v[212:215], v[124:127]
	v_mfma_f32_16x16x32_bf16 v[120:123], v[164:167], v[212:215], v[120:123]
	v_mfma_f32_16x16x32_bf16 v[108:111], v[156:159], v[220:223], v[108:111]
	v_mfma_f32_16x16x32_bf16 v[104:107], v[164:167], v[220:223], v[104:107]
	v_mfma_f32_16x16x32_bf16 v[92:95], v[156:159], v[228:231], v[92:95]
	v_mfma_f32_16x16x32_bf16 v[88:91], v[164:167], v[228:231], v[88:91]
	v_mfma_f32_16x16x32_bf16 v[76:79], v[156:159], v[236:239], v[76:79]
	v_mfma_f32_16x16x32_bf16 v[72:75], v[164:167], v[236:239], v[72:75]
	v_mfma_f32_16x16x32_bf16 v[116:119], v[168:171], v[208:211], v[116:119]
	v_mfma_f32_16x16x32_bf16 v[112:115], v[176:179], v[208:211], v[112:115]
	v_mfma_f32_16x16x32_bf16 v[100:103], v[168:171], v[216:219], v[100:103]
	v_mfma_f32_16x16x32_bf16 v[96:99], v[176:179], v[216:219], v[96:99]
	v_mfma_f32_16x16x32_bf16 v[84:87], v[168:171], v[224:227], v[84:87]
	v_mfma_f32_16x16x32_bf16 v[80:83], v[176:179], v[224:227], v[80:83]
	v_mfma_f32_16x16x32_bf16 v[68:71], v[168:171], v[232:235], v[68:71]
	v_mfma_f32_16x16x32_bf16 v[64:67], v[176:179], v[232:235], v[64:67]
	v_mfma_f32_16x16x32_bf16 v[116:119], v[172:175], v[212:215], v[116:119]
	v_mfma_f32_16x16x32_bf16 v[112:115], v[204:207], v[212:215], v[112:115]
	v_mfma_f32_16x16x32_bf16 v[100:103], v[172:175], v[220:223], v[100:103]
	v_mfma_f32_16x16x32_bf16 v[96:99], v[204:207], v[220:223], v[96:99]
	v_mfma_f32_16x16x32_bf16 v[84:87], v[172:175], v[228:231], v[84:87]
	v_mfma_f32_16x16x32_bf16 v[80:83], v[204:207], v[228:231], v[80:83]
	v_mfma_f32_16x16x32_bf16 v[68:71], v[172:175], v[236:239], v[68:71]
	v_mfma_f32_16x16x32_bf16 v[64:67], v[204:207], v[236:239], v[64:67]
	s_barrier
	s_setprio 1
	s_add_i32 s4, s4, s28
	v_lshl_add_u64 v[180:181], v[180:181], 0, s[26:27]
	s_mov_b32 m0, s4
	ds_read_b128 v[208:211], v155 offset:49152
	ds_read_b128 v[212:215], v155 offset:50176
	ds_read_b128 v[216:219], v155 offset:51200
	ds_read_b128 v[220:223], v155 offset:52224
	ds_read_b128 v[224:227], v155 offset:53248
	ds_read_b128 v[228:231], v155 offset:54272
	ds_read_b128 v[232:235], v155 offset:55296
	ds_read_b128 v[236:239], v155 offset:56320
	global_load_lds_dwordx4 v[180:181], off
	s_add_i32 m0, s4, 0x2000
	s_add_u32 s34, s34, 0x40080
	v_lshl_add_u64 v[180:181], v[240:241], 0, s[26:27]
	s_addc_u32 s35, s35, 0
	s_add_i32 s4, s5, s28
	global_load_lds_dwordx4 v[180:181], off
	v_lshl_add_u64 v[180:181], s[34:35], 0, v[144:145]
	s_mov_b32 m0, s4
	s_nop 0
	global_load_lds_dwordx4 v[180:181], off
	v_lshl_add_u64 v[180:181], s[34:35], 0, v[128:129]
	s_add_i32 m0, s4, 0x2000
	s_nop 0
	global_load_lds_dwordx4 v[180:181], off
	v_lshl_add_u64 v[180:181], v[242:243], 0, s[26:27]
	s_mov_b32 m0, s72
	s_nop 0
	global_load_lds_dwordx4 v[180:181], off
	v_lshl_add_u64 v[180:181], v[244:245], 0, s[26:27]
	s_mov_b32 m0, s73
	s_nop 0
	global_load_lds_dwordx4 v[180:181], off
	s_setprio 0
	s_waitcnt vmcnt(8)
	s_waitcnt lgkmcnt(0)
	s_barrier
	s_waitcnt lgkmcnt(0)
	v_mfma_f32_16x16x32_bf16 v[60:63], v[138:141], v[208:211], v[60:63]
	v_mfma_f32_16x16x32_bf16 v[56:59], v[160:163], v[208:211], v[56:59]
	v_mfma_f32_16x16x32_bf16 v[44:47], v[138:141], v[216:219], v[44:47]
	v_mfma_f32_16x16x32_bf16 v[40:43], v[160:163], v[216:219], v[40:43]
	v_mfma_f32_16x16x32_bf16 v[28:31], v[138:141], v[224:227], v[28:31]
	v_mfma_f32_16x16x32_bf16 v[24:27], v[160:163], v[224:227], v[24:27]
	v_mfma_f32_16x16x32_bf16 v[12:15], v[138:141], v[232:235], v[12:15]
	v_mfma_f32_16x16x32_bf16 v[8:11], v[160:163], v[232:235], v[8:11]
	v_mfma_f32_16x16x32_bf16 v[60:63], v[156:159], v[212:215], v[60:63]
	v_mfma_f32_16x16x32_bf16 v[56:59], v[164:167], v[212:215], v[56:59]
	v_mfma_f32_16x16x32_bf16 v[44:47], v[156:159], v[220:223], v[44:47]
	v_mfma_f32_16x16x32_bf16 v[40:43], v[164:167], v[220:223], v[40:43]
	v_mfma_f32_16x16x32_bf16 v[28:31], v[156:159], v[228:231], v[28:31]
	v_mfma_f32_16x16x32_bf16 v[24:27], v[164:167], v[228:231], v[24:27]
	v_mfma_f32_16x16x32_bf16 v[12:15], v[156:159], v[236:239], v[12:15]
	v_mfma_f32_16x16x32_bf16 v[8:11], v[164:167], v[236:239], v[8:11]
	v_mfma_f32_16x16x32_bf16 v[52:55], v[168:171], v[208:211], v[52:55]
	v_mfma_f32_16x16x32_bf16 v[48:51], v[176:179], v[208:211], v[48:51]
	v_mfma_f32_16x16x32_bf16 v[36:39], v[168:171], v[216:219], v[36:39]
	v_mfma_f32_16x16x32_bf16 v[32:35], v[176:179], v[216:219], v[32:35]
	v_mfma_f32_16x16x32_bf16 v[20:23], v[168:171], v[224:227], v[20:23]
	v_mfma_f32_16x16x32_bf16 v[16:19], v[176:179], v[224:227], v[16:19]
	v_mfma_f32_16x16x32_bf16 v[4:7], v[168:171], v[232:235], v[4:7]
	v_mfma_f32_16x16x32_bf16 v[0:3], v[176:179], v[232:235], v[0:3]
	v_mfma_f32_16x16x32_bf16 v[52:55], v[172:175], v[212:215], v[52:55]
	v_mfma_f32_16x16x32_bf16 v[48:51], v[204:207], v[212:215], v[48:51]
	v_mfma_f32_16x16x32_bf16 v[36:39], v[172:175], v[220:223], v[36:39]
	v_mfma_f32_16x16x32_bf16 v[32:35], v[204:207], v[220:223], v[32:35]
	v_mfma_f32_16x16x32_bf16 v[20:23], v[172:175], v[228:231], v[20:23]
	v_mfma_f32_16x16x32_bf16 v[16:19], v[204:207], v[228:231], v[16:19]
	v_mfma_f32_16x16x32_bf16 v[4:7], v[172:175], v[236:239], v[4:7]
	v_mfma_f32_16x16x32_bf16 v[0:3], v[204:207], v[236:239], v[0:3]
	s_barrier
	s_setprio 1
	s_add_i32 s82, s82, 2
	s_add_u32 s62, s62, 0x100
	s_addc_u32 s63, s63, 0
	s_add_u32 s75, s75, 0x100
	s_addc_u32 s79, s79, 0
	s_cmp_gt_u32 s82, 13
	s_cbranch_scc0 .LBB0_311
	s_setprio 0
	v_lshl_add_u32 v140, s2, 8, v142
	v_ashrrev_i32_e32 v141, 31, v140
	v_lshl_add_u64 v[156:157], v[140:141], 4, s[48:49]
	global_load_dwordx4 v[208:211], v[156:157], off
	global_load_dwordx4 v[212:215], v[156:157], off offset:256
	global_load_dwordx4 v[216:219], v[156:157], off offset:512
	global_load_dwordx4 v[220:223], v[156:157], off offset:768
	global_load_dwordx4 v[224:227], v[156:157], off offset:2048
	global_load_dwordx4 v[228:231], v[156:157], off offset:2304
	global_load_dwordx4 v[232:235], v[156:157], off offset:2560
	global_load_dwordx4 v[236:239], v[156:157], off offset:2816
	s_and_b64 vcc, exec, s[50:51]
	s_cbranch_vccz .LBB0_314
	s_barrier

.LBB0_406:
	s_setprio 1
	s_add_u32 s62, s60, 0x100
	s_addc_u32 s63, s61, 0
	s_add_i32 s4, 0, 0x10000
	s_cmp_eq_u32 s29, 40
	s_cselect_b32 s65, s45, s63
	s_cselect_b32 s64, s44, s62
	v_add_u32_e32 v142, s4, v160
	s_cselect_b32 s35, s59, s28
	s_cselect_b32 s34, s58, s3
	s_add_i32 s5, 0, 0x14000
	ds_read_b128 v[138:141], v142
	ds_read_b128 v[154:157], v142 offset:1024
	ds_read_b128 v[172:175], v142 offset:2048
	ds_read_b128 v[176:179], v142 offset:3072
	v_add_u32_e32 v142, s5, v160
	ds_read_b128 v[204:207], v142
	ds_read_b128 v[208:211], v142 offset:1024
	ds_read_b128 v[212:215], v142 offset:2048
	ds_read_b128 v[216:219], v142 offset:3072
	v_lshl_add_u64 v[142:143], s[60:61], 0, v[134:135]
	s_add_i32 m0, s36, 0xc000
	ds_read_b128 v[220:223], v170
	ds_read_b128 v[224:227], v170 offset:1024
	ds_read_b128 v[228:231], v170 offset:2048
	ds_read_b128 v[232:235], v170 offset:3072
	ds_read_b128 v[236:239], v170 offset:4096
	ds_read_b128 v[240:243], v170 offset:5120
	ds_read_b128 v[244:247], v170 offset:6144
	ds_read_b128 v[248:251], v170 offset:7168
	global_load_lds_dwordx4 v[142:143], off
	v_lshl_add_u64 v[142:143], s[60:61], 0, v[136:137]
	s_add_i32 m0, s36, 0xe000
	s_nop 0
	global_load_lds_dwordx4 v[142:143], off
	s_setprio 0
	s_waitcnt vmcnt(8)
	s_waitcnt lgkmcnt(0)
	s_barrier
	s_waitcnt lgkmcnt(0)
	v_mfma_f32_16x16x32_bf16 v[124:127], v[138:141], v[220:223], v[124:127]
	v_mfma_f32_16x16x32_bf16 v[120:123], v[172:175], v[220:223], v[120:123]
	v_mfma_f32_16x16x32_bf16 v[108:111], v[138:141], v[228:231], v[108:111]
	v_mfma_f32_16x16x32_bf16 v[104:107], v[172:175], v[228:231], v[104:107]
	v_mfma_f32_16x16x32_bf16 v[92:95], v[138:141], v[236:239], v[92:95]
	v_mfma_f32_16x16x32_bf16 v[88:91], v[172:175], v[236:239], v[88:91]
	v_mfma_f32_16x16x32_bf16 v[76:79], v[138:141], v[244:247], v[76:79]
	v_mfma_f32_16x16x32_bf16 v[72:75], v[172:175], v[244:247], v[72:75]
	v_mfma_f32_16x16x32_bf16 v[124:127], v[154:157], v[224:227], v[124:127]
	v_mfma_f32_16x16x32_bf16 v[120:123], v[176:179], v[224:227], v[120:123]
	v_mfma_f32_16x16x32_bf16 v[108:111], v[154:157], v[232:235], v[108:111]
	v_mfma_f32_16x16x32_bf16 v[104:107], v[176:179], v[232:235], v[104:107]
	v_mfma_f32_16x16x32_bf16 v[92:95], v[154:157], v[240:243], v[92:95]
	v_mfma_f32_16x16x32_bf16 v[88:91], v[176:179], v[240:243], v[88:91]
	v_mfma_f32_16x16x32_bf16 v[76:79], v[154:157], v[248:251], v[76:79]
	v_mfma_f32_16x16x32_bf16 v[72:75], v[176:179], v[248:251], v[72:75]
	v_mfma_f32_16x16x32_bf16 v[116:119], v[204:207], v[220:223], v[116:119]
	v_mfma_f32_16x16x32_bf16 v[112:115], v[212:215], v[220:223], v[112:115]
	v_mfma_f32_16x16x32_bf16 v[100:103], v[204:207], v[228:231], v[100:103]
	v_mfma_f32_16x16x32_bf16 v[96:99], v[212:215], v[228:231], v[96:99]
	v_mfma_f32_16x16x32_bf16 v[84:87], v[204:207], v[236:239], v[84:87]
	v_mfma_f32_16x16x32_bf16 v[80:83], v[212:215], v[236:239], v[80:83]
	v_mfma_f32_16x16x32_bf16 v[68:71], v[204:207], v[244:247], v[68:71]
	v_mfma_f32_16x16x32_bf16 v[64:67], v[212:215], v[244:247], v[64:67]
	v_mfma_f32_16x16x32_bf16 v[116:119], v[208:211], v[224:227], v[116:119]
	v_mfma_f32_16x16x32_bf16 v[112:115], v[216:219], v[224:227], v[112:115]
	v_mfma_f32_16x16x32_bf16 v[100:103], v[208:211], v[232:235], v[100:103]
	v_mfma_f32_16x16x32_bf16 v[96:99], v[216:219], v[232:235], v[96:99]
	v_mfma_f32_16x16x32_bf16 v[84:87], v[208:211], v[240:243], v[84:87]
	v_mfma_f32_16x16x32_bf16 v[80:83], v[216:219], v[240:243], v[80:83]
	v_mfma_f32_16x16x32_bf16 v[68:71], v[208:211], v[248:251], v[68:71]
	v_mfma_f32_16x16x32_bf16 v[64:67], v[216:219], v[248:251], v[64:67]
	s_barrier
	s_setprio 1
	s_add_i32 s4, s4, s33
	v_lshl_add_u64 v[142:143], s[34:35], 0, v[128:129]
	s_mov_b32 m0, s4
	ds_read_b128 v[220:223], v170 offset:16384
	ds_read_b128 v[224:227], v170 offset:17408
	ds_read_b128 v[228:231], v170 offset:18432
	ds_read_b128 v[232:235], v170 offset:19456
	ds_read_b128 v[236:239], v170 offset:20480
	ds_read_b128 v[240:243], v170 offset:21504
	ds_read_b128 v[244:247], v170 offset:22528
	ds_read_b128 v[248:251], v170 offset:23552
	global_load_lds_dwordx4 v[142:143], off
	s_add_i32 m0, s4, 0x2000
	s_add_u32 s60, s34, 0xb0000
	v_lshl_add_u64 v[158:159], s[34:35], 0, v[130:131]
	s_addc_u32 s61, s35, 0
	s_add_i32 s4, s5, s33
	global_load_lds_dwordx4 v[158:159], off
	v_lshl_add_u64 v[180:181], s[60:61], 0, v[128:129]
	s_mov_b32 m0, s4
	v_lshl_add_u64 v[202:203], s[64:65], 0, v[130:131]
	global_load_lds_dwordx4 v[180:181], off
	v_lshl_add_u64 v[180:181], s[60:61], 0, v[130:131]
	s_add_i32 m0, s4, 0x2000
	s_nop 0
	global_load_lds_dwordx4 v[180:181], off
	v_lshl_add_u64 v[180:181], s[64:65], 0, v[128:129]
	s_mov_b32 m0, s36
	s_nop 0
	global_load_lds_dwordx4 v[180:181], off
	s_mov_b32 m0, s70
	s_nop 0
	global_load_lds_dwordx4 v[202:203], off
	s_setprio 0
	s_waitcnt vmcnt(8)
	s_waitcnt lgkmcnt(0)
	s_barrier
	s_waitcnt lgkmcnt(0)
	v_mfma_f32_16x16x32_bf16 v[60:63], v[138:141], v[220:223], v[60:63]
	v_mfma_f32_16x16x32_bf16 v[56:59], v[172:175], v[220:223], v[56:59]
	v_mfma_f32_16x16x32_bf16 v[44:47], v[138:141], v[228:231], v[44:47]
	v_mfma_f32_16x16x32_bf16 v[40:43], v[172:175], v[228:231], v[40:43]
	v_mfma_f32_16x16x32_bf16 v[28:31], v[138:141], v[236:239], v[28:31]
	v_mfma_f32_16x16x32_bf16 v[24:27], v[172:175], v[236:239], v[24:27]
	v_mfma_f32_16x16x32_bf16 v[12:15], v[138:141], v[244:247], v[12:15]
	v_mfma_f32_16x16x32_bf16 v[8:11], v[172:175], v[244:247], v[8:11]
	v_mfma_f32_16x16x32_bf16 v[60:63], v[154:157], v[224:227], v[60:63]
	v_mfma_f32_16x16x32_bf16 v[56:59], v[176:179], v[224:227], v[56:59]
	v_mfma_f32_16x16x32_bf16 v[44:47], v[154:157], v[232:235], v[44:47]
	v_mfma_f32_16x16x32_bf16 v[40:43], v[176:179], v[232:235], v[40:43]
	v_mfma_f32_16x16x32_bf16 v[28:31], v[154:157], v[240:243], v[28:31]
	v_mfma_f32_16x16x32_bf16 v[24:27], v[176:179], v[240:243], v[24:27]
	v_mfma_f32_16x16x32_bf16 v[12:15], v[154:157], v[248:251], v[12:15]
	v_mfma_f32_16x16x32_bf16 v[8:11], v[176:179], v[248:251], v[8:11]
	v_mfma_f32_16x16x32_bf16 v[52:55], v[204:207], v[220:223], v[52:55]
	v_mfma_f32_16x16x32_bf16 v[48:51], v[212:215], v[220:223], v[48:51]
	v_mfma_f32_16x16x32_bf16 v[36:39], v[204:207], v[228:231], v[36:39]
	v_mfma_f32_16x16x32_bf16 v[32:35], v[212:215], v[228:231], v[32:35]
	v_mfma_f32_16x16x32_bf16 v[20:23], v[204:207], v[236:239], v[20:23]
	v_mfma_f32_16x16x32_bf16 v[16:19], v[212:215], v[236:239], v[16:19]
	v_mfma_f32_16x16x32_bf16 v[4:7], v[204:207], v[244:247], v[4:7]
	v_mfma_f32_16x16x32_bf16 v[0:3], v[212:215], v[244:247], v[0:3]
	v_mfma_f32_16x16x32_bf16 v[52:55], v[208:211], v[224:227], v[52:55]
	v_mfma_f32_16x16x32_bf16 v[48:51], v[216:219], v[224:227], v[48:51]
	v_mfma_f32_16x16x32_bf16 v[36:39], v[208:211], v[232:235], v[36:39]
	v_mfma_f32_16x16x32_bf16 v[32:35], v[216:219], v[232:235], v[32:35]
	v_mfma_f32_16x16x32_bf16 v[20:23], v[208:211], v[240:243], v[20:23]
	v_mfma_f32_16x16x32_bf16 v[16:19], v[216:219], v[240:243], v[16:19]
	v_mfma_f32_16x16x32_bf16 v[4:7], v[208:211], v[248:251], v[4:7]
	v_mfma_f32_16x16x32_bf16 v[0:3], v[216:219], v[248:251], v[0:3]
	s_barrier
	s_setprio 1
	s_add_i32 s4, 0, 0x18000
	v_add_u32_e32 v144, s4, v160
	s_add_i32 s5, 0, 0x1c000
	ds_read_b128 v[138:141], v144
	ds_read_b128 v[154:157], v144 offset:1024
	ds_read_b128 v[172:175], v144 offset:2048
	ds_read_b128 v[176:179], v144 offset:3072
	v_add_u32_e32 v144, s5, v160
	ds_read_b128 v[204:207], v144
	ds_read_b128 v[208:211], v144 offset:1024
	ds_read_b128 v[212:215], v144 offset:2048
	ds_read_b128 v[216:219], v144 offset:3072
	s_add_u32 s60, s64, 0xb0000
	s_addc_u32 s61, s65, 0
	s_mov_b32 m0, s71
	v_lshl_add_u64 v[252:253], s[60:61], 0, v[128:129]
	ds_read_b128 v[220:223], v170 offset:32768
	ds_read_b128 v[224:227], v170 offset:33792
	ds_read_b128 v[228:231], v170 offset:34816
	ds_read_b128 v[232:235], v170 offset:35840
	ds_read_b128 v[236:239], v170 offset:36864
	ds_read_b128 v[240:243], v170 offset:37888
	ds_read_b128 v[244:247], v170 offset:38912
	ds_read_b128 v[248:251], v170 offset:39936
	global_load_lds_dwordx4 v[252:253], off
	v_lshl_add_u64 v[252:253], s[60:61], 0, v[130:131]
	s_mov_b32 m0, s72
	s_nop 0
	global_load_lds_dwordx4 v[252:253], off
	s_setprio 0
	s_waitcnt vmcnt(8)
	s_waitcnt lgkmcnt(0)
	s_barrier
	s_waitcnt lgkmcnt(0)
	v_mfma_f32_16x16x32_bf16 v[124:127], v[138:141], v[220:223], v[124:127]
	v_mfma_f32_16x16x32_bf16 v[120:123], v[172:175], v[220:223], v[120:123]
	v_mfma_f32_16x16x32_bf16 v[108:111], v[138:141], v[228:231], v[108:111]
	v_mfma_f32_16x16x32_bf16 v[104:107], v[172:175], v[228:231], v[104:107]
	v_mfma_f32_16x16x32_bf16 v[92:95], v[138:141], v[236:239], v[92:95]
	v_mfma_f32_16x16x32_bf16 v[88:91], v[172:175], v[236:239], v[88:91]
	v_mfma_f32_16x16x32_bf16 v[76:79], v[138:141], v[244:247], v[76:79]
	v_mfma_f32_16x16x32_bf16 v[72:75], v[172:175], v[244:247], v[72:75]
	v_mfma_f32_16x16x32_bf16 v[124:127], v[154:157], v[224:227], v[124:127]
	v_mfma_f32_16x16x32_bf16 v[120:123], v[176:179], v[224:227], v[120:123]
	v_mfma_f32_16x16x32_bf16 v[108:111], v[154:157], v[232:235], v[108:111]
	v_mfma_f32_16x16x32_bf16 v[104:107], v[176:179], v[232:235], v[104:107]
	v_mfma_f32_16x16x32_bf16 v[92:95], v[154:157], v[240:243], v[92:95]
	v_mfma_f32_16x16x32_bf16 v[88:91], v[176:179], v[240:243], v[88:91]
	v_mfma_f32_16x16x32_bf16 v[76:79], v[154:157], v[248:251], v[76:79]
	v_mfma_f32_16x16x32_bf16 v[72:75], v[176:179], v[248:251], v[72:75]
	v_mfma_f32_16x16x32_bf16 v[116:119], v[204:207], v[220:223], v[116:119]
	v_mfma_f32_16x16x32_bf16 v[112:115], v[212:215], v[220:223], v[112:115]
	v_mfma_f32_16x16x32_bf16 v[100:103], v[204:207], v[228:231], v[100:103]
	v_mfma_f32_16x16x32_bf16 v[96:99], v[212:215], v[228:231], v[96:99]
	v_mfma_f32_16x16x32_bf16 v[84:87], v[204:207], v[236:239], v[84:87]
	v_mfma_f32_16x16x32_bf16 v[80:83], v[212:215], v[236:239], v[80:83]
	v_mfma_f32_16x16x32_bf16 v[68:71], v[204:207], v[244:247], v[68:71]
	v_mfma_f32_16x16x32_bf16 v[64:67], v[212:215], v[244:247], v[64:67]
	v_mfma_f32_16x16x32_bf16 v[116:119], v[208:211], v[224:227], v[116:119]
	v_mfma_f32_16x16x32_bf16 v[112:115], v[216:219], v[224:227], v[112:115]
	v_mfma_f32_16x16x32_bf16 v[100:103], v[208:211], v[232:235], v[100:103]
	v_mfma_f32_16x16x32_bf16 v[96:99], v[216:219], v[232:235], v[96:99]
	v_mfma_f32_16x16x32_bf16 v[84:87], v[208:211], v[240:243], v[84:87]
	v_mfma_f32_16x16x32_bf16 v[80:83], v[216:219], v[240:243], v[80:83]
	v_mfma_f32_16x16x32_bf16 v[68:71], v[208:211], v[248:251], v[68:71]
	v_mfma_f32_16x16x32_bf16 v[64:67], v[216:219], v[248:251], v[64:67]
	s_barrier
	s_setprio 1
	s_add_i32 s4, s4, s33
	v_lshl_add_u64 v[142:143], v[142:143], 0, s[26:27]
	s_mov_b32 m0, s4
	ds_read_b128 v[220:223], v170 offset:49152
	ds_read_b128 v[224:227], v170 offset:50176
	ds_read_b128 v[228:231], v170 offset:51200
	ds_read_b128 v[232:235], v170 offset:52224
	ds_read_b128 v[236:239], v170 offset:53248
	ds_read_b128 v[240:243], v170 offset:54272
	ds_read_b128 v[244:247], v170 offset:55296
	ds_read_b128 v[248:251], v170 offset:56320
	global_load_lds_dwordx4 v[142:143], off
	s_add_i32 m0, s4, 0x2000
	s_add_u32 s34, s34, 0xb0080
	v_lshl_add_u64 v[142:143], v[158:159], 0, s[26:27]
	s_addc_u32 s35, s35, 0
	s_add_i32 s4, s5, s33
	global_load_lds_dwordx4 v[142:143], off
	v_lshl_add_u64 v[142:143], s[34:35], 0, v[128:129]
	s_mov_b32 m0, s4
	s_nop 0
	global_load_lds_dwordx4 v[142:143], off
	v_lshl_add_u64 v[142:143], s[34:35], 0, v[130:131]
	s_add_i32 m0, s4, 0x2000
	s_nop 0
	global_load_lds_dwordx4 v[142:143], off
	v_lshl_add_u64 v[142:143], v[180:181], 0, s[26:27]
	s_mov_b32 m0, s73
	s_nop 0
	global_load_lds_dwordx4 v[142:143], off
	v_lshl_add_u64 v[142:143], v[202:203], 0, s[26:27]
	s_mov_b32 m0, s74
	s_nop 0
	global_load_lds_dwordx4 v[142:143], off
	s_setprio 0
	s_waitcnt vmcnt(8)
	s_waitcnt lgkmcnt(0)
	s_barrier
	s_waitcnt lgkmcnt(0)
	v_mfma_f32_16x16x32_bf16 v[60:63], v[138:141], v[220:223], v[60:63]
	v_mfma_f32_16x16x32_bf16 v[56:59], v[172:175], v[220:223], v[56:59]
	v_mfma_f32_16x16x32_bf16 v[44:47], v[138:141], v[228:231], v[44:47]
	v_mfma_f32_16x16x32_bf16 v[40:43], v[172:175], v[228:231], v[40:43]
	v_mfma_f32_16x16x32_bf16 v[28:31], v[138:141], v[236:239], v[28:31]
	v_mfma_f32_16x16x32_bf16 v[24:27], v[172:175], v[236:239], v[24:27]
	v_mfma_f32_16x16x32_bf16 v[12:15], v[138:141], v[244:247], v[12:15]
	v_mfma_f32_16x16x32_bf16 v[8:11], v[172:175], v[244:247], v[8:11]
	v_mfma_f32_16x16x32_bf16 v[60:63], v[154:157], v[224:227], v[60:63]
	v_mfma_f32_16x16x32_bf16 v[56:59], v[176:179], v[224:227], v[56:59]
	v_mfma_f32_16x16x32_bf16 v[44:47], v[154:157], v[232:235], v[44:47]
	v_mfma_f32_16x16x32_bf16 v[40:43], v[176:179], v[232:235], v[40:43]
	v_mfma_f32_16x16x32_bf16 v[28:31], v[154:157], v[240:243], v[28:31]
	v_mfma_f32_16x16x32_bf16 v[24:27], v[176:179], v[240:243], v[24:27]
	v_mfma_f32_16x16x32_bf16 v[12:15], v[154:157], v[248:251], v[12:15]
	v_mfma_f32_16x16x32_bf16 v[8:11], v[176:179], v[248:251], v[8:11]
	v_mfma_f32_16x16x32_bf16 v[52:55], v[204:207], v[220:223], v[52:55]
	v_mfma_f32_16x16x32_bf16 v[48:51], v[212:215], v[220:223], v[48:51]
	v_mfma_f32_16x16x32_bf16 v[36:39], v[204:207], v[228:231], v[36:39]
	v_mfma_f32_16x16x32_bf16 v[32:35], v[212:215], v[228:231], v[32:35]
	v_mfma_f32_16x16x32_bf16 v[20:23], v[204:207], v[236:239], v[20:23]
	v_mfma_f32_16x16x32_bf16 v[16:19], v[212:215], v[236:239], v[16:19]
	v_mfma_f32_16x16x32_bf16 v[4:7], v[204:207], v[244:247], v[4:7]
	v_mfma_f32_16x16x32_bf16 v[0:3], v[212:215], v[244:247], v[0:3]
	v_mfma_f32_16x16x32_bf16 v[52:55], v[208:211], v[224:227], v[52:55]
	v_mfma_f32_16x16x32_bf16 v[48:51], v[216:219], v[224:227], v[48:51]
	v_mfma_f32_16x16x32_bf16 v[36:39], v[208:211], v[232:235], v[36:39]
	v_mfma_f32_16x16x32_bf16 v[32:35], v[216:219], v[232:235], v[32:35]
	v_mfma_f32_16x16x32_bf16 v[20:23], v[208:211], v[240:243], v[20:23]
	v_mfma_f32_16x16x32_bf16 v[16:19], v[216:219], v[240:243], v[16:19]
	v_mfma_f32_16x16x32_bf16 v[4:7], v[208:211], v[248:251], v[4:7]
	v_mfma_f32_16x16x32_bf16 v[0:3], v[216:219], v[248:251], v[0:3]
	s_barrier
	s_setprio 1
	s_add_i32 s29, s29, 2
	s_add_u32 s3, s3, 0x100
	s_addc_u32 s28, s28, 0
	s_cmp_gt_u32 s29, 41
	s_mov_b64 s[60:61], s[62:63]
	s_cbranch_scc0 .LBB0_406
	s_setprio 0
	s_and_b64 vcc, exec, s[54:55]
	s_cbranch_vccz .LBB0_409
	s_barrier

.LBB0_456:
	s_setprio 1
	s_add_u32 s60, s58, 0x100
	s_addc_u32 s61, s59, 0
	s_add_i32 s4, 0, 0x10000
	s_cmp_eq_u32 s51, 40
	s_cselect_b32 s63, s45, s61
	s_cselect_b32 s62, s44, s60
	s_cselect_b32 s35, s47, s29
	s_cselect_b32 s34, s46, s28
	s_add_i32 s5, 0, 0x14000
	v_add_u32_e32 v140, s4, v166
	v_add_u32_e32 v144, s5, v166
	ds_read_b128 v[128:131], v140
	ds_read_b128 v[132:135], v140 offset:1024
	ds_read_b128 v[136:139], v140 offset:2048
	ds_read_b128 v[140:143], v140 offset:3072
	ds_read_b128 v[178:181], v144
	ds_read_b128 v[204:207], v144 offset:1024
	ds_read_b128 v[208:211], v144 offset:2048
	ds_read_b128 v[212:215], v144 offset:3072
	v_lshl_add_u64 v[164:165], s[58:59], 0, v[160:161]
	s_add_i32 m0, s36, 0xc000
	ds_read_b128 v[216:219], v176
	ds_read_b128 v[220:223], v176 offset:1024
	ds_read_b128 v[224:227], v176 offset:2048
	ds_read_b128 v[228:231], v176 offset:3072
	ds_read_b128 v[232:235], v176 offset:4096
	ds_read_b128 v[236:239], v176 offset:5120
	ds_read_b128 v[240:243], v176 offset:6144
	ds_read_b128 v[244:247], v176 offset:7168
	global_load_lds_dwordx4 v[164:165], off
	v_lshl_add_u64 v[164:165], s[58:59], 0, v[162:163]
	s_add_i32 m0, s36, 0xe000
	s_nop 0
	global_load_lds_dwordx4 v[164:165], off
	s_setprio 0
	s_waitcnt vmcnt(8)
	s_waitcnt lgkmcnt(0)
	s_barrier
	s_waitcnt lgkmcnt(0)
	v_mfma_f32_16x16x32_bf16 v[124:127], v[128:131], v[216:219], v[124:127]
	v_mfma_f32_16x16x32_bf16 v[120:123], v[136:139], v[216:219], v[120:123]
	v_mfma_f32_16x16x32_bf16 v[108:111], v[128:131], v[224:227], v[108:111]
	v_mfma_f32_16x16x32_bf16 v[104:107], v[136:139], v[224:227], v[104:107]
	v_mfma_f32_16x16x32_bf16 v[92:95], v[128:131], v[232:235], v[92:95]
	v_mfma_f32_16x16x32_bf16 v[88:91], v[136:139], v[232:235], v[88:91]
	v_mfma_f32_16x16x32_bf16 v[76:79], v[128:131], v[240:243], v[76:79]
	v_mfma_f32_16x16x32_bf16 v[72:75], v[136:139], v[240:243], v[72:75]
	v_mfma_f32_16x16x32_bf16 v[124:127], v[132:135], v[220:223], v[124:127]
	v_mfma_f32_16x16x32_bf16 v[120:123], v[140:143], v[220:223], v[120:123]
	v_mfma_f32_16x16x32_bf16 v[108:111], v[132:135], v[228:231], v[108:111]
	v_mfma_f32_16x16x32_bf16 v[104:107], v[140:143], v[228:231], v[104:107]
	v_mfma_f32_16x16x32_bf16 v[92:95], v[132:135], v[236:239], v[92:95]
	v_mfma_f32_16x16x32_bf16 v[88:91], v[140:143], v[236:239], v[88:91]
	v_mfma_f32_16x16x32_bf16 v[76:79], v[132:135], v[244:247], v[76:79]
	v_mfma_f32_16x16x32_bf16 v[72:75], v[140:143], v[244:247], v[72:75]
	v_mfma_f32_16x16x32_bf16 v[116:119], v[178:181], v[216:219], v[116:119]
	v_mfma_f32_16x16x32_bf16 v[112:115], v[208:211], v[216:219], v[112:115]
	v_mfma_f32_16x16x32_bf16 v[100:103], v[178:181], v[224:227], v[100:103]
	v_mfma_f32_16x16x32_bf16 v[96:99], v[208:211], v[224:227], v[96:99]
	v_mfma_f32_16x16x32_bf16 v[84:87], v[178:181], v[232:235], v[84:87]
	v_mfma_f32_16x16x32_bf16 v[80:83], v[208:211], v[232:235], v[80:83]
	v_mfma_f32_16x16x32_bf16 v[68:71], v[178:181], v[240:243], v[68:71]
	v_mfma_f32_16x16x32_bf16 v[64:67], v[208:211], v[240:243], v[64:67]
	v_mfma_f32_16x16x32_bf16 v[116:119], v[204:207], v[220:223], v[116:119]
	v_mfma_f32_16x16x32_bf16 v[112:115], v[212:215], v[220:223], v[112:115]
	v_mfma_f32_16x16x32_bf16 v[100:103], v[204:207], v[228:231], v[100:103]
	v_mfma_f32_16x16x32_bf16 v[96:99], v[212:215], v[228:231], v[96:99]
	v_mfma_f32_16x16x32_bf16 v[84:87], v[204:207], v[236:239], v[84:87]
	v_mfma_f32_16x16x32_bf16 v[80:83], v[212:215], v[236:239], v[80:83]
	v_mfma_f32_16x16x32_bf16 v[68:71], v[204:207], v[244:247], v[68:71]
	v_mfma_f32_16x16x32_bf16 v[64:67], v[212:215], v[244:247], v[64:67]
	s_barrier
	s_setprio 1
	s_add_i32 s4, s4, s33
	v_lshl_add_u64 v[164:165], s[34:35], 0, v[154:155]
	s_mov_b32 m0, s4
	ds_read_b128 v[216:219], v176 offset:16384
	ds_read_b128 v[220:223], v176 offset:17408
	ds_read_b128 v[224:227], v176 offset:18432
	ds_read_b128 v[228:231], v176 offset:19456
	ds_read_b128 v[232:235], v176 offset:20480
	ds_read_b128 v[236:239], v176 offset:21504
	ds_read_b128 v[240:243], v176 offset:22528
	ds_read_b128 v[244:247], v176 offset:23552
	global_load_lds_dwordx4 v[164:165], off
	s_add_i32 m0, s4, 0x2000
	s_add_u32 s58, s34, 0xb0000
	v_lshl_add_u64 v[248:249], s[34:35], 0, v[156:157]
	s_addc_u32 s59, s35, 0
	s_add_i32 s4, s5, s33
	global_load_lds_dwordx4 v[248:249], off
	v_lshl_add_u64 v[250:251], s[58:59], 0, v[154:155]
	s_mov_b32 m0, s4
	v_lshl_add_u64 v[252:253], s[62:63], 0, v[156:157]
	global_load_lds_dwordx4 v[250:251], off
	v_lshl_add_u64 v[250:251], s[58:59], 0, v[156:157]
	s_add_i32 m0, s4, 0x2000
	s_nop 0
	global_load_lds_dwordx4 v[250:251], off
	v_lshl_add_u64 v[250:251], s[62:63], 0, v[154:155]
	s_mov_b32 m0, s36
	s_nop 0
	global_load_lds_dwordx4 v[250:251], off
	s_mov_b32 m0, s64
	s_nop 0
	global_load_lds_dwordx4 v[252:253], off
	s_setprio 0
	s_waitcnt vmcnt(8)
	s_waitcnt lgkmcnt(0)
	s_barrier
	s_waitcnt lgkmcnt(0)
	v_mfma_f32_16x16x32_bf16 v[60:63], v[128:131], v[216:219], v[60:63]
	v_mfma_f32_16x16x32_bf16 v[56:59], v[136:139], v[216:219], v[56:59]
	v_mfma_f32_16x16x32_bf16 v[44:47], v[128:131], v[224:227], v[44:47]
	v_mfma_f32_16x16x32_bf16 v[40:43], v[136:139], v[224:227], v[40:43]
	v_mfma_f32_16x16x32_bf16 v[28:31], v[128:131], v[232:235], v[28:31]
	v_mfma_f32_16x16x32_bf16 v[24:27], v[136:139], v[232:235], v[24:27]
	v_mfma_f32_16x16x32_bf16 v[12:15], v[128:131], v[240:243], v[12:15]
	v_mfma_f32_16x16x32_bf16 v[8:11], v[136:139], v[240:243], v[8:11]
	v_mfma_f32_16x16x32_bf16 v[60:63], v[132:135], v[220:223], v[60:63]
	v_mfma_f32_16x16x32_bf16 v[56:59], v[140:143], v[220:223], v[56:59]
	v_mfma_f32_16x16x32_bf16 v[44:47], v[132:135], v[228:231], v[44:47]
	v_mfma_f32_16x16x32_bf16 v[40:43], v[140:143], v[228:231], v[40:43]
	v_mfma_f32_16x16x32_bf16 v[28:31], v[132:135], v[236:239], v[28:31]
	v_mfma_f32_16x16x32_bf16 v[24:27], v[140:143], v[236:239], v[24:27]
	v_mfma_f32_16x16x32_bf16 v[12:15], v[132:135], v[244:247], v[12:15]
	v_mfma_f32_16x16x32_bf16 v[8:11], v[140:143], v[244:247], v[8:11]
	v_mfma_f32_16x16x32_bf16 v[52:55], v[178:181], v[216:219], v[52:55]
	v_mfma_f32_16x16x32_bf16 v[48:51], v[208:211], v[216:219], v[48:51]
	v_mfma_f32_16x16x32_bf16 v[36:39], v[178:181], v[224:227], v[36:39]
	v_mfma_f32_16x16x32_bf16 v[32:35], v[208:211], v[224:227], v[32:35]
	v_mfma_f32_16x16x32_bf16 v[20:23], v[178:181], v[232:235], v[20:23]
	v_mfma_f32_16x16x32_bf16 v[16:19], v[208:211], v[232:235], v[16:19]
	v_mfma_f32_16x16x32_bf16 v[4:7], v[178:181], v[240:243], v[4:7]
	v_mfma_f32_16x16x32_bf16 v[0:3], v[208:211], v[240:243], v[0:3]
	v_mfma_f32_16x16x32_bf16 v[52:55], v[204:207], v[220:223], v[52:55]
	v_mfma_f32_16x16x32_bf16 v[48:51], v[212:215], v[220:223], v[48:51]
	v_mfma_f32_16x16x32_bf16 v[36:39], v[204:207], v[228:231], v[36:39]
	v_mfma_f32_16x16x32_bf16 v[32:35], v[212:215], v[228:231], v[32:35]
	v_mfma_f32_16x16x32_bf16 v[20:23], v[204:207], v[236:239], v[20:23]
	v_mfma_f32_16x16x32_bf16 v[16:19], v[212:215], v[236:239], v[16:19]
	v_mfma_f32_16x16x32_bf16 v[4:7], v[204:207], v[244:247], v[4:7]
	v_mfma_f32_16x16x32_bf16 v[0:3], v[212:215], v[244:247], v[0:3]
	s_barrier
	s_setprio 1
	s_add_i32 s4, 0, 0x18000
	s_add_i32 s5, 0, 0x1c000
	v_add_u32_e32 v140, s4, v166
	v_add_u32_e32 v144, s5, v166
	ds_read_b128 v[128:131], v140
	ds_read_b128 v[132:135], v140 offset:1024
	ds_read_b128 v[136:139], v140 offset:2048
	ds_read_b128 v[140:143], v140 offset:3072
	ds_read_b128 v[178:181], v144
	ds_read_b128 v[204:207], v144 offset:1024
	ds_read_b128 v[208:211], v144 offset:2048
	ds_read_b128 v[212:215], v144 offset:3072
	s_add_u32 s58, s62, 0xb0000
	s_addc_u32 s59, s63, 0
	s_mov_b32 m0, s65
	v_lshl_add_u64 v[202:203], s[58:59], 0, v[154:155]
	ds_read_b128 v[216:219], v176 offset:32768
	ds_read_b128 v[220:223], v176 offset:33792
	ds_read_b128 v[224:227], v176 offset:34816
	ds_read_b128 v[228:231], v176 offset:35840
	ds_read_b128 v[232:235], v176 offset:36864
	ds_read_b128 v[236:239], v176 offset:37888
	ds_read_b128 v[240:243], v176 offset:38912
	ds_read_b128 v[244:247], v176 offset:39936
	global_load_lds_dwordx4 v[202:203], off
	v_lshl_add_u64 v[202:203], s[58:59], 0, v[156:157]
	s_mov_b32 m0, s70
	s_nop 0
	global_load_lds_dwordx4 v[202:203], off
	s_setprio 0
	s_waitcnt vmcnt(8)
	s_waitcnt lgkmcnt(0)
	s_barrier
	s_waitcnt lgkmcnt(0)
	v_mfma_f32_16x16x32_bf16 v[124:127], v[128:131], v[216:219], v[124:127]
	v_mfma_f32_16x16x32_bf16 v[120:123], v[136:139], v[216:219], v[120:123]
	v_mfma_f32_16x16x32_bf16 v[108:111], v[128:131], v[224:227], v[108:111]
	v_mfma_f32_16x16x32_bf16 v[104:107], v[136:139], v[224:227], v[104:107]
	v_mfma_f32_16x16x32_bf16 v[92:95], v[128:131], v[232:235], v[92:95]
	v_mfma_f32_16x16x32_bf16 v[88:91], v[136:139], v[232:235], v[88:91]
	v_mfma_f32_16x16x32_bf16 v[76:79], v[128:131], v[240:243], v[76:79]
	v_mfma_f32_16x16x32_bf16 v[72:75], v[136:139], v[240:243], v[72:75]
	v_mfma_f32_16x16x32_bf16 v[124:127], v[132:135], v[220:223], v[124:127]
	v_mfma_f32_16x16x32_bf16 v[120:123], v[140:143], v[220:223], v[120:123]
	v_mfma_f32_16x16x32_bf16 v[108:111], v[132:135], v[228:231], v[108:111]
	v_mfma_f32_16x16x32_bf16 v[104:107], v[140:143], v[228:231], v[104:107]
	v_mfma_f32_16x16x32_bf16 v[92:95], v[132:135], v[236:239], v[92:95]
	v_mfma_f32_16x16x32_bf16 v[88:91], v[140:143], v[236:239], v[88:91]
	v_mfma_f32_16x16x32_bf16 v[76:79], v[132:135], v[244:247], v[76:79]
	v_mfma_f32_16x16x32_bf16 v[72:75], v[140:143], v[244:247], v[72:75]
	v_mfma_f32_16x16x32_bf16 v[116:119], v[178:181], v[216:219], v[116:119]
	v_mfma_f32_16x16x32_bf16 v[112:115], v[208:211], v[216:219], v[112:115]
	v_mfma_f32_16x16x32_bf16 v[100:103], v[178:181], v[224:227], v[100:103]
	v_mfma_f32_16x16x32_bf16 v[96:99], v[208:211], v[224:227], v[96:99]
	v_mfma_f32_16x16x32_bf16 v[84:87], v[178:181], v[232:235], v[84:87]
	v_mfma_f32_16x16x32_bf16 v[80:83], v[208:211], v[232:235], v[80:83]
	v_mfma_f32_16x16x32_bf16 v[68:71], v[178:181], v[240:243], v[68:71]
	v_mfma_f32_16x16x32_bf16 v[64:67], v[208:211], v[240:243], v[64:67]
	v_mfma_f32_16x16x32_bf16 v[116:119], v[204:207], v[220:223], v[116:119]
	v_mfma_f32_16x16x32_bf16 v[112:115], v[212:215], v[220:223], v[112:115]
	v_mfma_f32_16x16x32_bf16 v[100:103], v[204:207], v[228:231], v[100:103]
	v_mfma_f32_16x16x32_bf16 v[96:99], v[212:215], v[228:231], v[96:99]
	v_mfma_f32_16x16x32_bf16 v[84:87], v[204:207], v[236:239], v[84:87]
	v_mfma_f32_16x16x32_bf16 v[80:83], v[212:215], v[236:239], v[80:83]
	v_mfma_f32_16x16x32_bf16 v[68:71], v[204:207], v[244:247], v[68:71]
	v_mfma_f32_16x16x32_bf16 v[64:67], v[212:215], v[244:247], v[64:67]
	s_barrier
	s_setprio 1
	s_add_i32 s4, s4, s33
	v_lshl_add_u64 v[164:165], v[164:165], 0, s[26:27]
	s_mov_b32 m0, s4
	ds_read_b128 v[216:219], v176 offset:49152
	ds_read_b128 v[220:223], v176 offset:50176
	ds_read_b128 v[224:227], v176 offset:51200
	ds_read_b128 v[228:231], v176 offset:52224
	ds_read_b128 v[232:235], v176 offset:53248
	ds_read_b128 v[236:239], v176 offset:54272
	ds_read_b128 v[240:243], v176 offset:55296
	ds_read_b128 v[244:247], v176 offset:56320
	global_load_lds_dwordx4 v[164:165], off
	s_add_i32 m0, s4, 0x2000
	s_add_u32 s34, s34, 0xb0080
	v_lshl_add_u64 v[164:165], v[248:249], 0, s[26:27]
	s_addc_u32 s35, s35, 0
	s_add_i32 s4, s5, s33
	global_load_lds_dwordx4 v[164:165], off
	v_lshl_add_u64 v[164:165], s[34:35], 0, v[154:155]
	s_mov_b32 m0, s4
	s_nop 0
	global_load_lds_dwordx4 v[164:165], off
	v_lshl_add_u64 v[164:165], s[34:35], 0, v[156:157]
	s_add_i32 m0, s4, 0x2000
	s_nop 0
	global_load_lds_dwordx4 v[164:165], off
	v_lshl_add_u64 v[164:165], v[250:251], 0, s[26:27]
	s_mov_b32 m0, s71
	s_nop 0
	global_load_lds_dwordx4 v[164:165], off
	v_lshl_add_u64 v[164:165], v[252:253], 0, s[26:27]
	s_mov_b32 m0, s72
	s_nop 0
	global_load_lds_dwordx4 v[164:165], off
	s_setprio 0
	s_waitcnt vmcnt(8)
	s_waitcnt lgkmcnt(0)
	s_barrier
	s_waitcnt lgkmcnt(0)
	v_mfma_f32_16x16x32_bf16 v[60:63], v[128:131], v[216:219], v[60:63]
	v_mfma_f32_16x16x32_bf16 v[56:59], v[136:139], v[216:219], v[56:59]
	v_mfma_f32_16x16x32_bf16 v[44:47], v[128:131], v[224:227], v[44:47]
	v_mfma_f32_16x16x32_bf16 v[40:43], v[136:139], v[224:227], v[40:43]
	v_mfma_f32_16x16x32_bf16 v[28:31], v[128:131], v[232:235], v[28:31]
	v_mfma_f32_16x16x32_bf16 v[24:27], v[136:139], v[232:235], v[24:27]
	v_mfma_f32_16x16x32_bf16 v[12:15], v[128:131], v[240:243], v[12:15]
	v_mfma_f32_16x16x32_bf16 v[8:11], v[136:139], v[240:243], v[8:11]
	v_mfma_f32_16x16x32_bf16 v[60:63], v[132:135], v[220:223], v[60:63]
	v_mfma_f32_16x16x32_bf16 v[56:59], v[140:143], v[220:223], v[56:59]
	v_mfma_f32_16x16x32_bf16 v[44:47], v[132:135], v[228:231], v[44:47]
	v_mfma_f32_16x16x32_bf16 v[40:43], v[140:143], v[228:231], v[40:43]
	v_mfma_f32_16x16x32_bf16 v[28:31], v[132:135], v[236:239], v[28:31]
	v_mfma_f32_16x16x32_bf16 v[24:27], v[140:143], v[236:239], v[24:27]
	v_mfma_f32_16x16x32_bf16 v[12:15], v[132:135], v[244:247], v[12:15]
	v_mfma_f32_16x16x32_bf16 v[8:11], v[140:143], v[244:247], v[8:11]
	v_mfma_f32_16x16x32_bf16 v[52:55], v[178:181], v[216:219], v[52:55]
	v_mfma_f32_16x16x32_bf16 v[48:51], v[208:211], v[216:219], v[48:51]
	v_mfma_f32_16x16x32_bf16 v[36:39], v[178:181], v[224:227], v[36:39]
	v_mfma_f32_16x16x32_bf16 v[32:35], v[208:211], v[224:227], v[32:35]
	v_mfma_f32_16x16x32_bf16 v[20:23], v[178:181], v[232:235], v[20:23]
	v_mfma_f32_16x16x32_bf16 v[16:19], v[208:211], v[232:235], v[16:19]
	v_mfma_f32_16x16x32_bf16 v[4:7], v[178:181], v[240:243], v[4:7]
	v_mfma_f32_16x16x32_bf16 v[0:3], v[208:211], v[240:243], v[0:3]
	v_mfma_f32_16x16x32_bf16 v[52:55], v[204:207], v[220:223], v[52:55]
	v_mfma_f32_16x16x32_bf16 v[48:51], v[212:215], v[220:223], v[48:51]
	v_mfma_f32_16x16x32_bf16 v[36:39], v[204:207], v[228:231], v[36:39]
	v_mfma_f32_16x16x32_bf16 v[32:35], v[212:215], v[228:231], v[32:35]
	v_mfma_f32_16x16x32_bf16 v[20:23], v[204:207], v[236:239], v[20:23]
	v_mfma_f32_16x16x32_bf16 v[16:19], v[212:215], v[236:239], v[16:19]
	v_mfma_f32_16x16x32_bf16 v[4:7], v[204:207], v[244:247], v[4:7]
	v_mfma_f32_16x16x32_bf16 v[0:3], v[212:215], v[244:247], v[0:3]
	s_barrier
	s_setprio 1
	s_add_i32 s51, s51, 2
	s_add_u32 s28, s28, 0x100
	s_addc_u32 s29, s29, 0
	s_cmp_gt_u32 s51, 41
	s_mov_b64 s[58:59], s[60:61]
	s_cbranch_scc0 .LBB0_456
	s_setprio 0
	s_and_b64 vcc, exec, s[54:55]
	s_cbranch_vccz .LBB0_459
	s_barrier

.LBB0_605:
	s_setprio 1
	s_add_u32 s4, s0, 0xfffc0080
	s_addc_u32 s5, s1, -1
	s_add_i32 s89, 0, 0x10000
	s_cmp_eq_u32 s88, 12
	s_cselect_b32 s43, s3, s5
	s_cselect_b32 s42, s36, s4
	s_cselect_b32 s35, s39, s84
	s_cselect_b32 s34, s71, s79
	s_add_i32 s4, 0, 0x14000
	v_add_u32_e32 v140, s89, v203
	v_add_u32_e32 v144, s4, v203
	ds_read_b128 v[128:131], v140
	ds_read_b128 v[132:135], v140 offset:1024
	ds_read_b128 v[136:139], v140 offset:2048
	ds_read_b128 v[140:143], v140 offset:3072
	ds_read_b128 v[168:171], v144
	ds_read_b128 v[172:175], v144 offset:1024
	ds_read_b128 v[176:179], v144 offset:2048
	ds_read_b128 v[206:209], v144 offset:3072
	v_lshl_add_u64 v[180:181], s[0:1], 0, v[164:165]
	s_add_i32 m0, s69, 0xc000
	ds_read_b128 v[210:213], v205
	ds_read_b128 v[214:217], v205 offset:1024
	ds_read_b128 v[218:221], v205 offset:2048
	ds_read_b128 v[222:225], v205 offset:3072
	ds_read_b128 v[226:229], v205 offset:4096
	ds_read_b128 v[230:233], v205 offset:5120
	ds_read_b128 v[234:237], v205 offset:6144
	ds_read_b128 v[238:241], v205 offset:7168
	global_load_lds_dwordx4 v[180:181], off
	v_lshl_add_u64 v[180:181], s[0:1], 0, v[166:167]
	s_add_i32 m0, s69, 0xe000
	s_nop 0
	global_load_lds_dwordx4 v[180:181], off
	s_setprio 0
	s_waitcnt vmcnt(8)
	s_waitcnt lgkmcnt(0)
	s_barrier
	s_waitcnt lgkmcnt(0)
	v_mfma_f32_16x16x32_bf16 v[124:127], v[128:131], v[210:213], v[124:127]
	v_mfma_f32_16x16x32_bf16 v[120:123], v[136:139], v[210:213], v[120:123]
	v_mfma_f32_16x16x32_bf16 v[112:115], v[128:131], v[218:221], v[112:115]
	v_mfma_f32_16x16x32_bf16 v[108:111], v[136:139], v[218:221], v[108:111]
	v_mfma_f32_16x16x32_bf16 v[100:103], v[128:131], v[226:229], v[100:103]
	v_mfma_f32_16x16x32_bf16 v[92:95], v[136:139], v[226:229], v[92:95]
	v_mfma_f32_16x16x32_bf16 v[84:87], v[128:131], v[234:237], v[84:87]
	v_mfma_f32_16x16x32_bf16 v[76:79], v[136:139], v[234:237], v[76:79]
	v_mfma_f32_16x16x32_bf16 v[124:127], v[132:135], v[214:217], v[124:127]
	v_mfma_f32_16x16x32_bf16 v[120:123], v[140:143], v[214:217], v[120:123]
	v_mfma_f32_16x16x32_bf16 v[112:115], v[132:135], v[222:225], v[112:115]
	v_mfma_f32_16x16x32_bf16 v[108:111], v[140:143], v[222:225], v[108:111]
	v_mfma_f32_16x16x32_bf16 v[100:103], v[132:135], v[230:233], v[100:103]
	v_mfma_f32_16x16x32_bf16 v[92:95], v[140:143], v[230:233], v[92:95]
	v_mfma_f32_16x16x32_bf16 v[84:87], v[132:135], v[238:241], v[84:87]
	v_mfma_f32_16x16x32_bf16 v[76:79], v[140:143], v[238:241], v[76:79]
	v_mfma_f32_16x16x32_bf16 v[116:119], v[168:171], v[210:213], v[116:119]
	v_mfma_f32_16x16x32_bf16 v[104:107], v[176:179], v[210:213], v[104:107]
	v_mfma_f32_16x16x32_bf16 v[96:99], v[168:171], v[218:221], v[96:99]
	v_mfma_f32_16x16x32_bf16 v[88:91], v[176:179], v[218:221], v[88:91]
	v_mfma_f32_16x16x32_bf16 v[80:83], v[168:171], v[226:229], v[80:83]
	v_mfma_f32_16x16x32_bf16 v[72:75], v[176:179], v[226:229], v[72:75]
	v_mfma_f32_16x16x32_bf16 v[68:71], v[168:171], v[234:237], v[68:71]
	v_mfma_f32_16x16x32_bf16 v[64:67], v[176:179], v[234:237], v[64:67]
	v_mfma_f32_16x16x32_bf16 v[116:119], v[172:175], v[214:217], v[116:119]
	v_mfma_f32_16x16x32_bf16 v[104:107], v[206:209], v[214:217], v[104:107]
	v_mfma_f32_16x16x32_bf16 v[96:99], v[172:175], v[222:225], v[96:99]
	v_mfma_f32_16x16x32_bf16 v[88:91], v[206:209], v[222:225], v[88:91]
	v_mfma_f32_16x16x32_bf16 v[80:83], v[172:175], v[230:233], v[80:83]
	v_mfma_f32_16x16x32_bf16 v[72:75], v[206:209], v[230:233], v[72:75]
	v_mfma_f32_16x16x32_bf16 v[68:71], v[172:175], v[238:241], v[68:71]
	v_mfma_f32_16x16x32_bf16 v[64:67], v[206:209], v[238:241], v[64:67]
	s_barrier
	s_setprio 1
	s_add_i32 s5, s89, s28
	v_lshl_add_u64 v[180:181], s[34:35], 0, v[156:157]
	s_mov_b32 m0, s5
	ds_read_b128 v[210:213], v205 offset:16384
	ds_read_b128 v[214:217], v205 offset:17408
	ds_read_b128 v[218:221], v205 offset:18432
	ds_read_b128 v[222:225], v205 offset:19456
	ds_read_b128 v[226:229], v205 offset:20480
	ds_read_b128 v[230:233], v205 offset:21504
	ds_read_b128 v[234:237], v205 offset:22528
	ds_read_b128 v[238:241], v205 offset:23552
	global_load_lds_dwordx4 v[180:181], off
	s_add_i32 m0, s5, 0x2000
	s_add_u32 s90, s34, 0x40000
	v_lshl_add_u64 v[242:243], s[34:35], 0, v[160:161]
	s_addc_u32 s91, s35, 0
	s_add_i32 s4, s4, s28
	global_load_lds_dwordx4 v[242:243], off
	v_lshl_add_u64 v[244:245], s[90:91], 0, v[156:157]
	s_mov_b32 m0, s4
	v_lshl_add_u64 v[246:247], s[42:43], 0, v[158:159]
	global_load_lds_dwordx4 v[244:245], off
	v_lshl_add_u64 v[244:245], s[90:91], 0, v[160:161]
	s_add_i32 m0, s4, 0x2000
	s_nop 0
	global_load_lds_dwordx4 v[244:245], off
	v_lshl_add_u64 v[244:245], s[42:43], 0, v[154:155]
	s_mov_b32 m0, s69
	s_nop 0
	global_load_lds_dwordx4 v[244:245], off
	s_mov_b32 m0, s62
	s_nop 0
	global_load_lds_dwordx4 v[246:247], off
	s_setprio 0
	s_waitcnt vmcnt(8)
	s_waitcnt lgkmcnt(0)
	s_barrier
	s_waitcnt lgkmcnt(0)
	v_mfma_f32_16x16x32_bf16 v[60:63], v[128:131], v[210:213], v[60:63]
	v_mfma_f32_16x16x32_bf16 v[56:59], v[136:139], v[210:213], v[56:59]
	v_mfma_f32_16x16x32_bf16 v[52:55], v[128:131], v[218:221], v[52:55]
	v_mfma_f32_16x16x32_bf16 v[44:47], v[136:139], v[218:221], v[44:47]
	v_mfma_f32_16x16x32_bf16 v[36:39], v[128:131], v[226:229], v[36:39]
	v_mfma_f32_16x16x32_bf16 v[28:31], v[136:139], v[226:229], v[28:31]
	v_mfma_f32_16x16x32_bf16 v[20:23], v[128:131], v[234:237], v[20:23]
	v_mfma_f32_16x16x32_bf16 v[12:15], v[136:139], v[234:237], v[12:15]
	v_mfma_f32_16x16x32_bf16 v[60:63], v[132:135], v[214:217], v[60:63]
	v_mfma_f32_16x16x32_bf16 v[56:59], v[140:143], v[214:217], v[56:59]
	v_mfma_f32_16x16x32_bf16 v[52:55], v[132:135], v[222:225], v[52:55]
	v_mfma_f32_16x16x32_bf16 v[44:47], v[140:143], v[222:225], v[44:47]
	v_mfma_f32_16x16x32_bf16 v[36:39], v[132:135], v[230:233], v[36:39]
	v_mfma_f32_16x16x32_bf16 v[28:31], v[140:143], v[230:233], v[28:31]
	v_mfma_f32_16x16x32_bf16 v[20:23], v[132:135], v[238:241], v[20:23]
	v_mfma_f32_16x16x32_bf16 v[12:15], v[140:143], v[238:241], v[12:15]
	v_mfma_f32_16x16x32_bf16 v[48:51], v[168:171], v[210:213], v[48:51]
	v_mfma_f32_16x16x32_bf16 v[40:43], v[176:179], v[210:213], v[40:43]
	v_mfma_f32_16x16x32_bf16 v[32:35], v[168:171], v[218:221], v[32:35]
	v_mfma_f32_16x16x32_bf16 v[24:27], v[176:179], v[218:221], v[24:27]
	v_mfma_f32_16x16x32_bf16 v[16:19], v[168:171], v[226:229], v[16:19]
	v_mfma_f32_16x16x32_bf16 v[8:11], v[176:179], v[226:229], v[8:11]
	v_mfma_f32_16x16x32_bf16 v[4:7], v[168:171], v[234:237], v[4:7]
	v_mfma_f32_16x16x32_bf16 v[0:3], v[176:179], v[234:237], v[0:3]
	v_mfma_f32_16x16x32_bf16 v[48:51], v[172:175], v[214:217], v[48:51]
	v_mfma_f32_16x16x32_bf16 v[40:43], v[206:209], v[214:217], v[40:43]
	v_mfma_f32_16x16x32_bf16 v[32:35], v[172:175], v[222:225], v[32:35]
	v_mfma_f32_16x16x32_bf16 v[24:27], v[206:209], v[222:225], v[24:27]
	v_mfma_f32_16x16x32_bf16 v[16:19], v[172:175], v[230:233], v[16:19]
	v_mfma_f32_16x16x32_bf16 v[8:11], v[206:209], v[230:233], v[8:11]
	v_mfma_f32_16x16x32_bf16 v[4:7], v[172:175], v[238:241], v[4:7]
	v_mfma_f32_16x16x32_bf16 v[0:3], v[206:209], v[238:241], v[0:3]
	s_barrier
	s_setprio 1
	s_add_i32 s4, 0, 0x18000
	s_add_i32 s5, 0, 0x1c000
	v_add_u32_e32 v140, s4, v203
	v_add_u32_e32 v144, s5, v203
	ds_read_b128 v[128:131], v140
	ds_read_b128 v[132:135], v140 offset:1024
	ds_read_b128 v[136:139], v140 offset:2048
	ds_read_b128 v[140:143], v140 offset:3072
	ds_read_b128 v[168:171], v144
	ds_read_b128 v[172:175], v144 offset:1024
	ds_read_b128 v[176:179], v144 offset:2048
	ds_read_b128 v[206:209], v144 offset:3072
	s_add_u32 s42, s42, 0x40000
	s_addc_u32 s43, s43, 0
	s_mov_b32 m0, s63
	v_lshl_add_u64 v[248:249], s[42:43], 0, v[154:155]
	ds_read_b128 v[210:213], v205 offset:32768
	ds_read_b128 v[214:217], v205 offset:33792
	ds_read_b128 v[218:221], v205 offset:34816
	ds_read_b128 v[222:225], v205 offset:35840
	ds_read_b128 v[226:229], v205 offset:36864
	ds_read_b128 v[230:233], v205 offset:37888
	ds_read_b128 v[234:237], v205 offset:38912
	ds_read_b128 v[238:241], v205 offset:39936
	global_load_lds_dwordx4 v[248:249], off
	v_lshl_add_u64 v[248:249], s[42:43], 0, v[158:159]
	s_mov_b32 m0, s50
	s_nop 0
	global_load_lds_dwordx4 v[248:249], off
	s_setprio 0
	s_waitcnt vmcnt(8)
	s_waitcnt lgkmcnt(0)
	s_barrier
	s_waitcnt lgkmcnt(0)
	v_mfma_f32_16x16x32_bf16 v[124:127], v[128:131], v[210:213], v[124:127]
	v_mfma_f32_16x16x32_bf16 v[120:123], v[136:139], v[210:213], v[120:123]
	v_mfma_f32_16x16x32_bf16 v[112:115], v[128:131], v[218:221], v[112:115]
	v_mfma_f32_16x16x32_bf16 v[108:111], v[136:139], v[218:221], v[108:111]
	v_mfma_f32_16x16x32_bf16 v[100:103], v[128:131], v[226:229], v[100:103]
	v_mfma_f32_16x16x32_bf16 v[92:95], v[136:139], v[226:229], v[92:95]
	v_mfma_f32_16x16x32_bf16 v[84:87], v[128:131], v[234:237], v[84:87]
	v_mfma_f32_16x16x32_bf16 v[76:79], v[136:139], v[234:237], v[76:79]
	v_mfma_f32_16x16x32_bf16 v[124:127], v[132:135], v[214:217], v[124:127]
	v_mfma_f32_16x16x32_bf16 v[120:123], v[140:143], v[214:217], v[120:123]
	v_mfma_f32_16x16x32_bf16 v[112:115], v[132:135], v[222:225], v[112:115]
	v_mfma_f32_16x16x32_bf16 v[108:111], v[140:143], v[222:225], v[108:111]
	v_mfma_f32_16x16x32_bf16 v[100:103], v[132:135], v[230:233], v[100:103]
	v_mfma_f32_16x16x32_bf16 v[92:95], v[140:143], v[230:233], v[92:95]
	v_mfma_f32_16x16x32_bf16 v[84:87], v[132:135], v[238:241], v[84:87]
	v_mfma_f32_16x16x32_bf16 v[76:79], v[140:143], v[238:241], v[76:79]
	v_mfma_f32_16x16x32_bf16 v[116:119], v[168:171], v[210:213], v[116:119]
	v_mfma_f32_16x16x32_bf16 v[104:107], v[176:179], v[210:213], v[104:107]
	v_mfma_f32_16x16x32_bf16 v[96:99], v[168:171], v[218:221], v[96:99]
	v_mfma_f32_16x16x32_bf16 v[88:91], v[176:179], v[218:221], v[88:91]
	v_mfma_f32_16x16x32_bf16 v[80:83], v[168:171], v[226:229], v[80:83]
	v_mfma_f32_16x16x32_bf16 v[72:75], v[176:179], v[226:229], v[72:75]
	v_mfma_f32_16x16x32_bf16 v[68:71], v[168:171], v[234:237], v[68:71]
	v_mfma_f32_16x16x32_bf16 v[64:67], v[176:179], v[234:237], v[64:67]
	v_mfma_f32_16x16x32_bf16 v[116:119], v[172:175], v[214:217], v[116:119]
	v_mfma_f32_16x16x32_bf16 v[104:107], v[206:209], v[214:217], v[104:107]
	v_mfma_f32_16x16x32_bf16 v[96:99], v[172:175], v[222:225], v[96:99]
	v_mfma_f32_16x16x32_bf16 v[88:91], v[206:209], v[222:225], v[88:91]
	v_mfma_f32_16x16x32_bf16 v[80:83], v[172:175], v[230:233], v[80:83]
	v_mfma_f32_16x16x32_bf16 v[72:75], v[206:209], v[230:233], v[72:75]
	v_mfma_f32_16x16x32_bf16 v[68:71], v[172:175], v[238:241], v[68:71]
	v_mfma_f32_16x16x32_bf16 v[64:67], v[206:209], v[238:241], v[64:67]
	s_barrier
	s_setprio 1
	s_add_i32 s4, s4, s28
	v_lshl_add_u64 v[180:181], v[180:181], 0, s[26:27]
	s_mov_b32 m0, s4
	ds_read_b128 v[210:213], v205 offset:49152
	ds_read_b128 v[214:217], v205 offset:50176
	ds_read_b128 v[218:221], v205 offset:51200
	ds_read_b128 v[222:225], v205 offset:52224
	ds_read_b128 v[226:229], v205 offset:53248
	ds_read_b128 v[230:233], v205 offset:54272
	ds_read_b128 v[234:237], v205 offset:55296
	ds_read_b128 v[238:241], v205 offset:56320
	global_load_lds_dwordx4 v[180:181], off
	s_add_i32 m0, s4, 0x2000
	s_add_u32 s34, s34, 0x40080
	v_lshl_add_u64 v[180:181], v[242:243], 0, s[26:27]
	s_addc_u32 s35, s35, 0
	s_add_i32 s4, s5, s28
	global_load_lds_dwordx4 v[180:181], off
	v_lshl_add_u64 v[180:181], s[34:35], 0, v[156:157]
	s_mov_b32 m0, s4
	s_nop 0
	global_load_lds_dwordx4 v[180:181], off
	v_lshl_add_u64 v[180:181], s[34:35], 0, v[160:161]
	s_add_i32 m0, s4, 0x2000
	s_nop 0
	global_load_lds_dwordx4 v[180:181], off
	v_lshl_add_u64 v[180:181], v[244:245], 0, s[26:27]
	s_mov_b32 m0, s51
	s_nop 0
	global_load_lds_dwordx4 v[180:181], off
	v_lshl_add_u64 v[180:181], v[246:247], 0, s[26:27]
	s_mov_b32 m0, s64
	s_nop 0
	global_load_lds_dwordx4 v[180:181], off
	s_setprio 0
	s_waitcnt vmcnt(8)
	s_waitcnt lgkmcnt(0)
	s_barrier
	s_waitcnt lgkmcnt(0)
	v_mfma_f32_16x16x32_bf16 v[60:63], v[128:131], v[210:213], v[60:63]
	v_mfma_f32_16x16x32_bf16 v[56:59], v[136:139], v[210:213], v[56:59]
	v_mfma_f32_16x16x32_bf16 v[52:55], v[128:131], v[218:221], v[52:55]
	v_mfma_f32_16x16x32_bf16 v[44:47], v[136:139], v[218:221], v[44:47]
	v_mfma_f32_16x16x32_bf16 v[36:39], v[128:131], v[226:229], v[36:39]
	v_mfma_f32_16x16x32_bf16 v[28:31], v[136:139], v[226:229], v[28:31]
	v_mfma_f32_16x16x32_bf16 v[20:23], v[128:131], v[234:237], v[20:23]
	v_mfma_f32_16x16x32_bf16 v[12:15], v[136:139], v[234:237], v[12:15]
	v_mfma_f32_16x16x32_bf16 v[60:63], v[132:135], v[214:217], v[60:63]
	v_mfma_f32_16x16x32_bf16 v[56:59], v[140:143], v[214:217], v[56:59]
	v_mfma_f32_16x16x32_bf16 v[52:55], v[132:135], v[222:225], v[52:55]
	v_mfma_f32_16x16x32_bf16 v[44:47], v[140:143], v[222:225], v[44:47]
	v_mfma_f32_16x16x32_bf16 v[36:39], v[132:135], v[230:233], v[36:39]
	v_mfma_f32_16x16x32_bf16 v[28:31], v[140:143], v[230:233], v[28:31]
	v_mfma_f32_16x16x32_bf16 v[20:23], v[132:135], v[238:241], v[20:23]
	v_mfma_f32_16x16x32_bf16 v[12:15], v[140:143], v[238:241], v[12:15]
	v_mfma_f32_16x16x32_bf16 v[48:51], v[168:171], v[210:213], v[48:51]
	v_mfma_f32_16x16x32_bf16 v[40:43], v[176:179], v[210:213], v[40:43]
	v_mfma_f32_16x16x32_bf16 v[32:35], v[168:171], v[218:221], v[32:35]
	v_mfma_f32_16x16x32_bf16 v[24:27], v[176:179], v[218:221], v[24:27]
	v_mfma_f32_16x16x32_bf16 v[16:19], v[168:171], v[226:229], v[16:19]
	v_mfma_f32_16x16x32_bf16 v[8:11], v[176:179], v[226:229], v[8:11]
	v_mfma_f32_16x16x32_bf16 v[4:7], v[168:171], v[234:237], v[4:7]
	v_mfma_f32_16x16x32_bf16 v[0:3], v[176:179], v[234:237], v[0:3]
	v_mfma_f32_16x16x32_bf16 v[48:51], v[172:175], v[214:217], v[48:51]
	v_mfma_f32_16x16x32_bf16 v[40:43], v[206:209], v[214:217], v[40:43]
	v_mfma_f32_16x16x32_bf16 v[32:35], v[172:175], v[222:225], v[32:35]
	v_mfma_f32_16x16x32_bf16 v[24:27], v[206:209], v[222:225], v[24:27]
	v_mfma_f32_16x16x32_bf16 v[16:19], v[172:175], v[230:233], v[16:19]
	v_mfma_f32_16x16x32_bf16 v[8:11], v[206:209], v[230:233], v[8:11]
	v_mfma_f32_16x16x32_bf16 v[4:7], v[172:175], v[238:241], v[4:7]
	v_mfma_f32_16x16x32_bf16 v[0:3], v[206:209], v[238:241], v[0:3]
	s_barrier
	s_setprio 1
	s_add_i32 s88, s88, 2
	s_add_u32 s0, s0, 0x100
	s_addc_u32 s1, s1, 0
	s_add_u32 s79, s79, 0x100
	s_addc_u32 s84, s84, 0
	s_cmp_gt_u32 s88, 13
	s_cbranch_scc0 .LBB0_605
	s_setprio 0
	s_and_b64 vcc, exec, s[66:67]
	s_cbranch_vccz .LBB0_608
	s_barrier

.LBB0_1005:
	s_setprio 1
	s_add_u32 s4, s54, 0xfffe0080
	s_addc_u32 s5, s55, -1
	s_add_i32 s72, 0, 0x10000
	s_cmp_eq_u32 s71, 4
	s_cselect_b32 s59, s29, s5
	s_cselect_b32 s58, s47, s4
	v_add_u32_e32 v138, s72, v141
	s_cselect_b32 s35, s45, s70
	s_cselect_b32 s34, s68, s69
	s_add_i32 s73, 0, 0x14000
	ds_read_b128 v[154:157], v138
	ds_read_b128 v[158:161], v138 offset:1024
	ds_read_b128 v[162:165], v138 offset:2048
	ds_read_b128 v[166:169], v138 offset:3072
	v_add_u32_e32 v138, s73, v141
	ds_read_b128 v[170:173], v138
	ds_read_b128 v[174:177], v138 offset:1024
	ds_read_b128 v[178:181], v138 offset:2048
	ds_read_b128 v[204:207], v138 offset:3072
	v_lshl_add_u64 v[138:139], s[54:55], 0, v[134:135]
	s_add_i32 m0, s53, 0xc000
	ds_read_b128 v[208:211], v143
	ds_read_b128 v[212:215], v143 offset:1024
	ds_read_b128 v[216:219], v143 offset:2048
	ds_read_b128 v[220:223], v143 offset:3072
	ds_read_b128 v[224:227], v143 offset:4096
	ds_read_b128 v[228:231], v143 offset:5120
	ds_read_b128 v[232:235], v143 offset:6144
	ds_read_b128 v[236:239], v143 offset:7168
	global_load_lds_dwordx4 v[138:139], off
	v_lshl_add_u64 v[138:139], s[54:55], 0, v[136:137]
	s_add_i32 m0, s53, 0xe000
	s_nop 0
	global_load_lds_dwordx4 v[138:139], off
	s_setprio 0
	s_waitcnt vmcnt(8)
	s_waitcnt lgkmcnt(0)
	s_barrier
	s_waitcnt lgkmcnt(0)
	v_mfma_f32_16x16x32_bf16 v[120:123], v[154:157], v[208:211], v[120:123]
	v_mfma_f32_16x16x32_bf16 v[124:127], v[162:165], v[208:211], v[124:127]
	v_mfma_f32_16x16x32_bf16 v[104:107], v[154:157], v[216:219], v[104:107]
	v_mfma_f32_16x16x32_bf16 v[108:111], v[162:165], v[216:219], v[108:111]
	v_mfma_f32_16x16x32_bf16 v[88:91], v[154:157], v[224:227], v[88:91]
	v_mfma_f32_16x16x32_bf16 v[92:95], v[162:165], v[224:227], v[92:95]
	v_mfma_f32_16x16x32_bf16 v[72:75], v[154:157], v[232:235], v[72:75]
	v_mfma_f32_16x16x32_bf16 v[76:79], v[162:165], v[232:235], v[76:79]
	v_mfma_f32_16x16x32_bf16 v[120:123], v[158:161], v[212:215], v[120:123]
	v_mfma_f32_16x16x32_bf16 v[124:127], v[166:169], v[212:215], v[124:127]
	v_mfma_f32_16x16x32_bf16 v[104:107], v[158:161], v[220:223], v[104:107]
	v_mfma_f32_16x16x32_bf16 v[108:111], v[166:169], v[220:223], v[108:111]
	v_mfma_f32_16x16x32_bf16 v[88:91], v[158:161], v[228:231], v[88:91]
	v_mfma_f32_16x16x32_bf16 v[92:95], v[166:169], v[228:231], v[92:95]
	v_mfma_f32_16x16x32_bf16 v[72:75], v[158:161], v[236:239], v[72:75]
	v_mfma_f32_16x16x32_bf16 v[76:79], v[166:169], v[236:239], v[76:79]
	v_mfma_f32_16x16x32_bf16 v[112:115], v[170:173], v[208:211], v[112:115]
	v_mfma_f32_16x16x32_bf16 v[116:119], v[178:181], v[208:211], v[116:119]
	v_mfma_f32_16x16x32_bf16 v[96:99], v[170:173], v[216:219], v[96:99]
	v_mfma_f32_16x16x32_bf16 v[100:103], v[178:181], v[216:219], v[100:103]
	v_mfma_f32_16x16x32_bf16 v[80:83], v[170:173], v[224:227], v[80:83]
	v_mfma_f32_16x16x32_bf16 v[84:87], v[178:181], v[224:227], v[84:87]
	v_mfma_f32_16x16x32_bf16 v[64:67], v[170:173], v[232:235], v[64:67]
	v_mfma_f32_16x16x32_bf16 v[68:71], v[178:181], v[232:235], v[68:71]
	v_mfma_f32_16x16x32_bf16 v[112:115], v[174:177], v[212:215], v[112:115]
	v_mfma_f32_16x16x32_bf16 v[116:119], v[204:207], v[212:215], v[116:119]
	v_mfma_f32_16x16x32_bf16 v[96:99], v[174:177], v[220:223], v[96:99]
	v_mfma_f32_16x16x32_bf16 v[100:103], v[204:207], v[220:223], v[100:103]
	v_mfma_f32_16x16x32_bf16 v[80:83], v[174:177], v[228:231], v[80:83]
	v_mfma_f32_16x16x32_bf16 v[84:87], v[204:207], v[228:231], v[84:87]
	v_mfma_f32_16x16x32_bf16 v[64:67], v[174:177], v[236:239], v[64:67]
	v_mfma_f32_16x16x32_bf16 v[68:71], v[204:207], v[236:239], v[68:71]
	s_barrier
	s_setprio 1
	s_add_i32 s4, s72, s30
	v_lshl_add_u64 v[138:139], s[34:35], 0, v[144:145]
	s_mov_b32 m0, s4
	ds_read_b128 v[208:211], v143 offset:16384
	ds_read_b128 v[212:215], v143 offset:17408
	ds_read_b128 v[216:219], v143 offset:18432
	ds_read_b128 v[220:223], v143 offset:19456
	ds_read_b128 v[224:227], v143 offset:20480
	ds_read_b128 v[228:231], v143 offset:21504
	ds_read_b128 v[232:235], v143 offset:22528
	ds_read_b128 v[236:239], v143 offset:23552
	global_load_lds_dwordx4 v[138:139], off
	s_add_i32 m0, s4, 0x2000
	s_add_u32 s4, s34, 0x20000
	v_lshl_add_u64 v[202:203], s[34:35], 0, v[132:133]
	s_addc_u32 s5, s35, 0
	s_add_i32 s72, s73, s30
	global_load_lds_dwordx4 v[202:203], off
	v_lshl_add_u64 v[240:241], s[4:5], 0, v[144:145]
	s_mov_b32 m0, s72
	v_lshl_add_u64 v[242:243], s[58:59], 0, v[130:131]
	global_load_lds_dwordx4 v[240:241], off
	v_lshl_add_u64 v[240:241], s[4:5], 0, v[132:133]
	s_add_i32 m0, s72, 0x2000
	s_nop 0
	global_load_lds_dwordx4 v[240:241], off
	v_lshl_add_u64 v[240:241], s[58:59], 0, v[128:129]
	s_mov_b32 m0, s53
	s_nop 0
	global_load_lds_dwordx4 v[240:241], off
	s_mov_b32 m0, s62
	s_nop 0
	global_load_lds_dwordx4 v[242:243], off
	s_setprio 0
	s_waitcnt vmcnt(8)
	s_waitcnt lgkmcnt(0)
	s_barrier
	s_waitcnt lgkmcnt(0)
	v_mfma_f32_16x16x32_bf16 v[56:59], v[154:157], v[208:211], v[56:59]
	v_mfma_f32_16x16x32_bf16 v[60:63], v[162:165], v[208:211], v[60:63]
	v_mfma_f32_16x16x32_bf16 v[40:43], v[154:157], v[216:219], v[40:43]
	v_mfma_f32_16x16x32_bf16 v[44:47], v[162:165], v[216:219], v[44:47]
	v_mfma_f32_16x16x32_bf16 v[24:27], v[154:157], v[224:227], v[24:27]
	v_mfma_f32_16x16x32_bf16 v[28:31], v[162:165], v[224:227], v[28:31]
	v_mfma_f32_16x16x32_bf16 v[8:11], v[154:157], v[232:235], v[8:11]
	v_mfma_f32_16x16x32_bf16 v[12:15], v[162:165], v[232:235], v[12:15]
	v_mfma_f32_16x16x32_bf16 v[56:59], v[158:161], v[212:215], v[56:59]
	v_mfma_f32_16x16x32_bf16 v[60:63], v[166:169], v[212:215], v[60:63]
	v_mfma_f32_16x16x32_bf16 v[40:43], v[158:161], v[220:223], v[40:43]
	v_mfma_f32_16x16x32_bf16 v[44:47], v[166:169], v[220:223], v[44:47]
	v_mfma_f32_16x16x32_bf16 v[24:27], v[158:161], v[228:231], v[24:27]
	v_mfma_f32_16x16x32_bf16 v[28:31], v[166:169], v[228:231], v[28:31]
	v_mfma_f32_16x16x32_bf16 v[8:11], v[158:161], v[236:239], v[8:11]
	v_mfma_f32_16x16x32_bf16 v[12:15], v[166:169], v[236:239], v[12:15]
	v_mfma_f32_16x16x32_bf16 v[48:51], v[170:173], v[208:211], v[48:51]
	v_mfma_f32_16x16x32_bf16 v[52:55], v[178:181], v[208:211], v[52:55]
	v_mfma_f32_16x16x32_bf16 v[32:35], v[170:173], v[216:219], v[32:35]
	v_mfma_f32_16x16x32_bf16 v[36:39], v[178:181], v[216:219], v[36:39]
	v_mfma_f32_16x16x32_bf16 v[16:19], v[170:173], v[224:227], v[16:19]
	v_mfma_f32_16x16x32_bf16 v[20:23], v[178:181], v[224:227], v[20:23]
	v_mfma_f32_16x16x32_bf16 v[0:3], v[170:173], v[232:235], v[0:3]
	v_mfma_f32_16x16x32_bf16 v[4:7], v[178:181], v[232:235], v[4:7]
	v_mfma_f32_16x16x32_bf16 v[48:51], v[174:177], v[212:215], v[48:51]
	v_mfma_f32_16x16x32_bf16 v[52:55], v[204:207], v[212:215], v[52:55]
	v_mfma_f32_16x16x32_bf16 v[32:35], v[174:177], v[220:223], v[32:35]
	v_mfma_f32_16x16x32_bf16 v[36:39], v[204:207], v[220:223], v[36:39]
	v_mfma_f32_16x16x32_bf16 v[16:19], v[174:177], v[228:231], v[16:19]
	v_mfma_f32_16x16x32_bf16 v[20:23], v[204:207], v[228:231], v[20:23]
	v_mfma_f32_16x16x32_bf16 v[0:3], v[174:177], v[236:239], v[0:3]
	v_mfma_f32_16x16x32_bf16 v[4:7], v[204:207], v[236:239], v[4:7]
	s_barrier
	s_setprio 1
	s_add_i32 s72, 0, 0x18000
	s_add_i32 s73, 0, 0x1c000
	v_add_u32_e32 v166, s72, v141
	v_add_u32_e32 v204, s73, v141
	ds_read_b128 v[154:157], v166
	ds_read_b128 v[158:161], v166 offset:1024
	ds_read_b128 v[162:165], v166 offset:2048
	ds_read_b128 v[166:169], v166 offset:3072
	ds_read_b128 v[170:173], v204
	ds_read_b128 v[174:177], v204 offset:1024
	ds_read_b128 v[178:181], v204 offset:2048
	ds_read_b128 v[204:207], v204 offset:3072
	s_add_u32 s4, s58, 0x20000
	s_addc_u32 s5, s59, 0
	s_mov_b32 m0, s63
	v_lshl_add_u64 v[244:245], s[4:5], 0, v[128:129]
	ds_read_b128 v[208:211], v143 offset:32768
	ds_read_b128 v[212:215], v143 offset:33792
	ds_read_b128 v[216:219], v143 offset:34816
	ds_read_b128 v[220:223], v143 offset:35840
	ds_read_b128 v[224:227], v143 offset:36864
	ds_read_b128 v[228:231], v143 offset:37888
	ds_read_b128 v[232:235], v143 offset:38912
	ds_read_b128 v[236:239], v143 offset:39936
	global_load_lds_dwordx4 v[244:245], off
	v_lshl_add_u64 v[244:245], s[4:5], 0, v[130:131]
	s_mov_b32 m0, s64
	s_nop 0
	global_load_lds_dwordx4 v[244:245], off
	s_setprio 0
	s_waitcnt vmcnt(8)
	s_waitcnt lgkmcnt(0)
	s_barrier
	s_waitcnt lgkmcnt(0)
	v_mfma_f32_16x16x32_bf16 v[120:123], v[154:157], v[208:211], v[120:123]
	v_mfma_f32_16x16x32_bf16 v[124:127], v[162:165], v[208:211], v[124:127]
	v_mfma_f32_16x16x32_bf16 v[104:107], v[154:157], v[216:219], v[104:107]
	v_mfma_f32_16x16x32_bf16 v[108:111], v[162:165], v[216:219], v[108:111]
	v_mfma_f32_16x16x32_bf16 v[88:91], v[154:157], v[224:227], v[88:91]
	v_mfma_f32_16x16x32_bf16 v[92:95], v[162:165], v[224:227], v[92:95]
	v_mfma_f32_16x16x32_bf16 v[72:75], v[154:157], v[232:235], v[72:75]
	v_mfma_f32_16x16x32_bf16 v[76:79], v[162:165], v[232:235], v[76:79]
	v_mfma_f32_16x16x32_bf16 v[120:123], v[158:161], v[212:215], v[120:123]
	v_mfma_f32_16x16x32_bf16 v[124:127], v[166:169], v[212:215], v[124:127]
	v_mfma_f32_16x16x32_bf16 v[104:107], v[158:161], v[220:223], v[104:107]
	v_mfma_f32_16x16x32_bf16 v[108:111], v[166:169], v[220:223], v[108:111]
	v_mfma_f32_16x16x32_bf16 v[88:91], v[158:161], v[228:231], v[88:91]
	v_mfma_f32_16x16x32_bf16 v[92:95], v[166:169], v[228:231], v[92:95]
	v_mfma_f32_16x16x32_bf16 v[72:75], v[158:161], v[236:239], v[72:75]
	v_mfma_f32_16x16x32_bf16 v[76:79], v[166:169], v[236:239], v[76:79]
	v_mfma_f32_16x16x32_bf16 v[112:115], v[170:173], v[208:211], v[112:115]
	v_mfma_f32_16x16x32_bf16 v[116:119], v[178:181], v[208:211], v[116:119]
	v_mfma_f32_16x16x32_bf16 v[96:99], v[170:173], v[216:219], v[96:99]
	v_mfma_f32_16x16x32_bf16 v[100:103], v[178:181], v[216:219], v[100:103]
	v_mfma_f32_16x16x32_bf16 v[80:83], v[170:173], v[224:227], v[80:83]
	v_mfma_f32_16x16x32_bf16 v[84:87], v[178:181], v[224:227], v[84:87]
	v_mfma_f32_16x16x32_bf16 v[64:67], v[170:173], v[232:235], v[64:67]
	v_mfma_f32_16x16x32_bf16 v[68:71], v[178:181], v[232:235], v[68:71]
	v_mfma_f32_16x16x32_bf16 v[112:115], v[174:177], v[212:215], v[112:115]
	v_mfma_f32_16x16x32_bf16 v[116:119], v[204:207], v[212:215], v[116:119]
	v_mfma_f32_16x16x32_bf16 v[96:99], v[174:177], v[220:223], v[96:99]
	v_mfma_f32_16x16x32_bf16 v[100:103], v[204:207], v[220:223], v[100:103]
	v_mfma_f32_16x16x32_bf16 v[80:83], v[174:177], v[228:231], v[80:83]
	v_mfma_f32_16x16x32_bf16 v[84:87], v[204:207], v[228:231], v[84:87]
	v_mfma_f32_16x16x32_bf16 v[64:67], v[174:177], v[236:239], v[64:67]
	v_mfma_f32_16x16x32_bf16 v[68:71], v[204:207], v[236:239], v[68:71]
	s_barrier
	s_setprio 1
	s_add_i32 s4, s72, s30
	v_lshl_add_u64 v[138:139], v[138:139], 0, s[26:27]
	s_mov_b32 m0, s4
	ds_read_b128 v[208:211], v143 offset:49152
	ds_read_b128 v[212:215], v143 offset:50176
	ds_read_b128 v[216:219], v143 offset:51200
	ds_read_b128 v[220:223], v143 offset:52224
	ds_read_b128 v[224:227], v143 offset:53248
	ds_read_b128 v[228:231], v143 offset:54272
	ds_read_b128 v[232:235], v143 offset:55296
	ds_read_b128 v[236:239], v143 offset:56320
	global_load_lds_dwordx4 v[138:139], off
	s_add_i32 m0, s4, 0x2000
	s_add_u32 s4, s34, 0x20080
	v_lshl_add_u64 v[138:139], v[202:203], 0, s[26:27]
	s_addc_u32 s5, s35, 0
	s_add_i32 s34, s73, s30
	global_load_lds_dwordx4 v[138:139], off
	v_lshl_add_u64 v[138:139], s[4:5], 0, v[144:145]
	s_mov_b32 m0, s34
	s_nop 0
	global_load_lds_dwordx4 v[138:139], off
	v_lshl_add_u64 v[138:139], s[4:5], 0, v[132:133]
	s_add_i32 m0, s34, 0x2000
	s_nop 0
	global_load_lds_dwordx4 v[138:139], off
	v_lshl_add_u64 v[138:139], v[240:241], 0, s[26:27]
	s_mov_b32 m0, s65
	s_nop 0
	global_load_lds_dwordx4 v[138:139], off
	v_lshl_add_u64 v[138:139], v[242:243], 0, s[26:27]
	s_mov_b32 m0, s66
	s_nop 0
	global_load_lds_dwordx4 v[138:139], off
	s_setprio 0
	s_waitcnt vmcnt(8)
	s_waitcnt lgkmcnt(0)
	s_barrier
	s_waitcnt lgkmcnt(0)
	v_mfma_f32_16x16x32_bf16 v[56:59], v[154:157], v[208:211], v[56:59]
	v_mfma_f32_16x16x32_bf16 v[60:63], v[162:165], v[208:211], v[60:63]
	v_mfma_f32_16x16x32_bf16 v[40:43], v[154:157], v[216:219], v[40:43]
	v_mfma_f32_16x16x32_bf16 v[44:47], v[162:165], v[216:219], v[44:47]
	v_mfma_f32_16x16x32_bf16 v[24:27], v[154:157], v[224:227], v[24:27]
	v_mfma_f32_16x16x32_bf16 v[28:31], v[162:165], v[224:227], v[28:31]
	v_mfma_f32_16x16x32_bf16 v[8:11], v[154:157], v[232:235], v[8:11]
	v_mfma_f32_16x16x32_bf16 v[12:15], v[162:165], v[232:235], v[12:15]
	v_mfma_f32_16x16x32_bf16 v[56:59], v[158:161], v[212:215], v[56:59]
	v_mfma_f32_16x16x32_bf16 v[60:63], v[166:169], v[212:215], v[60:63]
	v_mfma_f32_16x16x32_bf16 v[40:43], v[158:161], v[220:223], v[40:43]
	v_mfma_f32_16x16x32_bf16 v[44:47], v[166:169], v[220:223], v[44:47]
	v_mfma_f32_16x16x32_bf16 v[24:27], v[158:161], v[228:231], v[24:27]
	v_mfma_f32_16x16x32_bf16 v[28:31], v[166:169], v[228:231], v[28:31]
	v_mfma_f32_16x16x32_bf16 v[8:11], v[158:161], v[236:239], v[8:11]
	v_mfma_f32_16x16x32_bf16 v[12:15], v[166:169], v[236:239], v[12:15]
	v_mfma_f32_16x16x32_bf16 v[48:51], v[170:173], v[208:211], v[48:51]
	v_mfma_f32_16x16x32_bf16 v[52:55], v[178:181], v[208:211], v[52:55]
	v_mfma_f32_16x16x32_bf16 v[32:35], v[170:173], v[216:219], v[32:35]
	v_mfma_f32_16x16x32_bf16 v[36:39], v[178:181], v[216:219], v[36:39]
	v_mfma_f32_16x16x32_bf16 v[16:19], v[170:173], v[224:227], v[16:19]
	v_mfma_f32_16x16x32_bf16 v[20:23], v[178:181], v[224:227], v[20:23]
	v_mfma_f32_16x16x32_bf16 v[0:3], v[170:173], v[232:235], v[0:3]
	v_mfma_f32_16x16x32_bf16 v[4:7], v[178:181], v[232:235], v[4:7]
	v_mfma_f32_16x16x32_bf16 v[48:51], v[174:177], v[212:215], v[48:51]
	v_mfma_f32_16x16x32_bf16 v[52:55], v[204:207], v[212:215], v[52:55]
	v_mfma_f32_16x16x32_bf16 v[32:35], v[174:177], v[220:223], v[32:35]
	v_mfma_f32_16x16x32_bf16 v[36:39], v[204:207], v[220:223], v[36:39]
	v_mfma_f32_16x16x32_bf16 v[16:19], v[174:177], v[228:231], v[16:19]
	v_mfma_f32_16x16x32_bf16 v[20:23], v[204:207], v[228:231], v[20:23]
	v_mfma_f32_16x16x32_bf16 v[0:3], v[174:177], v[236:239], v[0:3]
	v_mfma_f32_16x16x32_bf16 v[4:7], v[204:207], v[236:239], v[4:7]
	s_barrier
	s_setprio 1
	s_add_i32 s71, s71, 2
	s_add_u32 s54, s54, 0x100
	s_addc_u32 s55, s55, 0
	s_add_u32 s69, s69, 0x100
	s_addc_u32 s70, s70, 0
	s_cmp_gt_u32 s71, 5
	s_cbranch_scc0 .LBB0_1005
	s_setprio 0
	v_readlane_b32 s68, v255, 7
	s_and_b64 vcc, exec, s[42:43]
	v_readlane_b32 s69, v255, 8
	s_cbranch_vccz .LBB0_1008
	s_barrier

.LBB0_1093:
	s_setprio 1
	s_add_u32 s4, s58, 0xfffe0080
	s_addc_u32 s5, s59, -1
	s_add_i32 s74, 0, 0x10000
	s_cmp_eq_u32 s73, 4
	s_cselect_b32 s61, s33, s5
	s_cselect_b32 s60, s36, s4
	s_cselect_b32 s35, s49, s72
	s_cselect_b32 s34, s51, s71
	s_add_i32 s75, 0, 0x14000
	v_add_u32_e32 v164, s74, v143
	v_add_u32_e32 v180, s75, v143
	ds_read_b128 v[138:141], v164
	ds_read_b128 v[156:159], v164 offset:1024
	ds_read_b128 v[160:163], v164 offset:2048
	ds_read_b128 v[164:167], v164 offset:3072
	ds_read_b128 v[168:171], v180
	ds_read_b128 v[172:175], v180 offset:1024
	ds_read_b128 v[176:179], v180 offset:2048
	ds_read_b128 v[204:207], v180 offset:3072
	v_lshl_add_u64 v[180:181], s[58:59], 0, v[134:135]
	s_add_i32 m0, s64, 0xc000
	ds_read_b128 v[208:211], v155
	ds_read_b128 v[212:215], v155 offset:1024
	ds_read_b128 v[216:219], v155 offset:2048
	ds_read_b128 v[220:223], v155 offset:3072
	ds_read_b128 v[224:227], v155 offset:4096
	ds_read_b128 v[228:231], v155 offset:5120
	ds_read_b128 v[232:235], v155 offset:6144
	ds_read_b128 v[236:239], v155 offset:7168
	global_load_lds_dwordx4 v[180:181], off
	v_lshl_add_u64 v[180:181], s[58:59], 0, v[136:137]
	s_add_i32 m0, s64, 0xe000
	s_nop 0
	global_load_lds_dwordx4 v[180:181], off
	s_setprio 0
	s_waitcnt vmcnt(8)
	s_waitcnt lgkmcnt(0)
	s_barrier
	s_waitcnt lgkmcnt(0)
	v_mfma_f32_16x16x32_bf16 v[124:127], v[138:141], v[208:211], v[124:127]
	v_mfma_f32_16x16x32_bf16 v[120:123], v[160:163], v[208:211], v[120:123]
	v_mfma_f32_16x16x32_bf16 v[108:111], v[138:141], v[216:219], v[108:111]
	v_mfma_f32_16x16x32_bf16 v[104:107], v[160:163], v[216:219], v[104:107]
	v_mfma_f32_16x16x32_bf16 v[92:95], v[138:141], v[224:227], v[92:95]
	v_mfma_f32_16x16x32_bf16 v[88:91], v[160:163], v[224:227], v[88:91]
	v_mfma_f32_16x16x32_bf16 v[76:79], v[138:141], v[232:235], v[76:79]
	v_mfma_f32_16x16x32_bf16 v[72:75], v[160:163], v[232:235], v[72:75]
	v_mfma_f32_16x16x32_bf16 v[124:127], v[156:159], v[212:215], v[124:127]
	v_mfma_f32_16x16x32_bf16 v[120:123], v[164:167], v[212:215], v[120:123]
	v_mfma_f32_16x16x32_bf16 v[108:111], v[156:159], v[220:223], v[108:111]
	v_mfma_f32_16x16x32_bf16 v[104:107], v[164:167], v[220:223], v[104:107]
	v_mfma_f32_16x16x32_bf16 v[92:95], v[156:159], v[228:231], v[92:95]
	v_mfma_f32_16x16x32_bf16 v[88:91], v[164:167], v[228:231], v[88:91]
	v_mfma_f32_16x16x32_bf16 v[76:79], v[156:159], v[236:239], v[76:79]
	v_mfma_f32_16x16x32_bf16 v[72:75], v[164:167], v[236:239], v[72:75]
	v_mfma_f32_16x16x32_bf16 v[116:119], v[168:171], v[208:211], v[116:119]
	v_mfma_f32_16x16x32_bf16 v[112:115], v[176:179], v[208:211], v[112:115]
	v_mfma_f32_16x16x32_bf16 v[100:103], v[168:171], v[216:219], v[100:103]
	v_mfma_f32_16x16x32_bf16 v[96:99], v[176:179], v[216:219], v[96:99]
	v_mfma_f32_16x16x32_bf16 v[84:87], v[168:171], v[224:227], v[84:87]
	v_mfma_f32_16x16x32_bf16 v[80:83], v[176:179], v[224:227], v[80:83]
	v_mfma_f32_16x16x32_bf16 v[68:71], v[168:171], v[232:235], v[68:71]
	v_mfma_f32_16x16x32_bf16 v[64:67], v[176:179], v[232:235], v[64:67]
	v_mfma_f32_16x16x32_bf16 v[116:119], v[172:175], v[212:215], v[116:119]
	v_mfma_f32_16x16x32_bf16 v[112:115], v[204:207], v[212:215], v[112:115]
	v_mfma_f32_16x16x32_bf16 v[100:103], v[172:175], v[220:223], v[100:103]
	v_mfma_f32_16x16x32_bf16 v[96:99], v[204:207], v[220:223], v[96:99]
	v_mfma_f32_16x16x32_bf16 v[84:87], v[172:175], v[228:231], v[84:87]
	v_mfma_f32_16x16x32_bf16 v[80:83], v[204:207], v[228:231], v[80:83]
	v_mfma_f32_16x16x32_bf16 v[68:71], v[172:175], v[236:239], v[68:71]
	v_mfma_f32_16x16x32_bf16 v[64:67], v[204:207], v[236:239], v[64:67]
	s_barrier
	s_setprio 1
	s_add_i32 s4, s74, s28
	v_lshl_add_u64 v[180:181], s[34:35], 0, v[144:145]
	s_mov_b32 m0, s4
	ds_read_b128 v[208:211], v155 offset:16384
	ds_read_b128 v[212:215], v155 offset:17408
	ds_read_b128 v[216:219], v155 offset:18432
	ds_read_b128 v[220:223], v155 offset:19456
	ds_read_b128 v[224:227], v155 offset:20480
	ds_read_b128 v[228:231], v155 offset:21504
	ds_read_b128 v[232:235], v155 offset:22528
	ds_read_b128 v[236:239], v155 offset:23552
	global_load_lds_dwordx4 v[180:181], off
	s_add_i32 m0, s4, 0x2000
	s_add_u32 s4, s34, 0x20000
	v_lshl_add_u64 v[202:203], s[34:35], 0, v[132:133]
	s_addc_u32 s5, s35, 0
	s_add_i32 s74, s75, s28
	global_load_lds_dwordx4 v[202:203], off
	v_lshl_add_u64 v[240:241], s[4:5], 0, v[144:145]
	s_mov_b32 m0, s74
	v_lshl_add_u64 v[242:243], s[60:61], 0, v[130:131]
	global_load_lds_dwordx4 v[240:241], off
	v_lshl_add_u64 v[240:241], s[4:5], 0, v[132:133]
	s_add_i32 m0, s74, 0x2000
	s_nop 0
	global_load_lds_dwordx4 v[240:241], off
	v_lshl_add_u64 v[240:241], s[60:61], 0, v[128:129]
	s_mov_b32 m0, s64
	s_nop 0
	global_load_lds_dwordx4 v[240:241], off
	s_mov_b32 m0, s65
	s_nop 0
	global_load_lds_dwordx4 v[242:243], off
	s_setprio 0
	s_waitcnt vmcnt(8)
	s_waitcnt lgkmcnt(0)
	s_barrier
	s_waitcnt lgkmcnt(0)
	v_mfma_f32_16x16x32_bf16 v[60:63], v[138:141], v[208:211], v[60:63]
	v_mfma_f32_16x16x32_bf16 v[56:59], v[160:163], v[208:211], v[56:59]
	v_mfma_f32_16x16x32_bf16 v[44:47], v[138:141], v[216:219], v[44:47]
	v_mfma_f32_16x16x32_bf16 v[40:43], v[160:163], v[216:219], v[40:43]
	v_mfma_f32_16x16x32_bf16 v[28:31], v[138:141], v[224:227], v[28:31]
	v_mfma_f32_16x16x32_bf16 v[24:27], v[160:163], v[224:227], v[24:27]
	v_mfma_f32_16x16x32_bf16 v[12:15], v[138:141], v[232:235], v[12:15]
	v_mfma_f32_16x16x32_bf16 v[8:11], v[160:163], v[232:235], v[8:11]
	v_mfma_f32_16x16x32_bf16 v[60:63], v[156:159], v[212:215], v[60:63]
	v_mfma_f32_16x16x32_bf16 v[56:59], v[164:167], v[212:215], v[56:59]
	v_mfma_f32_16x16x32_bf16 v[44:47], v[156:159], v[220:223], v[44:47]
	v_mfma_f32_16x16x32_bf16 v[40:43], v[164:167], v[220:223], v[40:43]
	v_mfma_f32_16x16x32_bf16 v[28:31], v[156:159], v[228:231], v[28:31]
	v_mfma_f32_16x16x32_bf16 v[24:27], v[164:167], v[228:231], v[24:27]
	v_mfma_f32_16x16x32_bf16 v[12:15], v[156:159], v[236:239], v[12:15]
	v_mfma_f32_16x16x32_bf16 v[8:11], v[164:167], v[236:239], v[8:11]
	v_mfma_f32_16x16x32_bf16 v[52:55], v[168:171], v[208:211], v[52:55]
	v_mfma_f32_16x16x32_bf16 v[48:51], v[176:179], v[208:211], v[48:51]
	v_mfma_f32_16x16x32_bf16 v[36:39], v[168:171], v[216:219], v[36:39]
	v_mfma_f32_16x16x32_bf16 v[32:35], v[176:179], v[216:219], v[32:35]
	v_mfma_f32_16x16x32_bf16 v[20:23], v[168:171], v[224:227], v[20:23]
	v_mfma_f32_16x16x32_bf16 v[16:19], v[176:179], v[224:227], v[16:19]
	v_mfma_f32_16x16x32_bf16 v[4:7], v[168:171], v[232:235], v[4:7]
	v_mfma_f32_16x16x32_bf16 v[0:3], v[176:179], v[232:235], v[0:3]
	v_mfma_f32_16x16x32_bf16 v[52:55], v[172:175], v[212:215], v[52:55]
	v_mfma_f32_16x16x32_bf16 v[48:51], v[204:207], v[212:215], v[48:51]
	v_mfma_f32_16x16x32_bf16 v[36:39], v[172:175], v[220:223], v[36:39]
	v_mfma_f32_16x16x32_bf16 v[32:35], v[204:207], v[220:223], v[32:35]
	v_mfma_f32_16x16x32_bf16 v[20:23], v[172:175], v[228:231], v[20:23]
	v_mfma_f32_16x16x32_bf16 v[16:19], v[204:207], v[228:231], v[16:19]
	v_mfma_f32_16x16x32_bf16 v[4:7], v[172:175], v[236:239], v[4:7]
	v_mfma_f32_16x16x32_bf16 v[0:3], v[204:207], v[236:239], v[0:3]
	s_barrier
	s_setprio 1
	s_add_i32 s74, 0, 0x18000
	s_add_i32 s75, 0, 0x1c000
	v_add_u32_e32 v164, s74, v143
	v_add_u32_e32 v204, s75, v143
	ds_read_b128 v[138:141], v164
	ds_read_b128 v[156:159], v164 offset:1024
	ds_read_b128 v[160:163], v164 offset:2048
	ds_read_b128 v[164:167], v164 offset:3072
	ds_read_b128 v[168:171], v204
	ds_read_b128 v[172:175], v204 offset:1024
	ds_read_b128 v[176:179], v204 offset:2048
	ds_read_b128 v[204:207], v204 offset:3072
	s_add_u32 s4, s60, 0x20000
	s_addc_u32 s5, s61, 0
	s_mov_b32 m0, s66
	v_lshl_add_u64 v[244:245], s[4:5], 0, v[128:129]
	ds_read_b128 v[208:211], v155 offset:32768
	ds_read_b128 v[212:215], v155 offset:33792
	ds_read_b128 v[216:219], v155 offset:34816
	ds_read_b128 v[220:223], v155 offset:35840
	ds_read_b128 v[224:227], v155 offset:36864
	ds_read_b128 v[228:231], v155 offset:37888
	ds_read_b128 v[232:235], v155 offset:38912
	ds_read_b128 v[236:239], v155 offset:39936
	global_load_lds_dwordx4 v[244:245], off
	v_lshl_add_u64 v[244:245], s[4:5], 0, v[130:131]
	s_mov_b32 m0, s67
	s_nop 0
	global_load_lds_dwordx4 v[244:245], off
	s_setprio 0
	s_waitcnt vmcnt(8)
	s_waitcnt lgkmcnt(0)
	s_barrier
	s_waitcnt lgkmcnt(0)
	v_mfma_f32_16x16x32_bf16 v[124:127], v[138:141], v[208:211], v[124:127]
	v_mfma_f32_16x16x32_bf16 v[120:123], v[160:163], v[208:211], v[120:123]
	v_mfma_f32_16x16x32_bf16 v[108:111], v[138:141], v[216:219], v[108:111]
	v_mfma_f32_16x16x32_bf16 v[104:107], v[160:163], v[216:219], v[104:107]
	v_mfma_f32_16x16x32_bf16 v[92:95], v[138:141], v[224:227], v[92:95]
	v_mfma_f32_16x16x32_bf16 v[88:91], v[160:163], v[224:227], v[88:91]
	v_mfma_f32_16x16x32_bf16 v[76:79], v[138:141], v[232:235], v[76:79]
	v_mfma_f32_16x16x32_bf16 v[72:75], v[160:163], v[232:235], v[72:75]
	v_mfma_f32_16x16x32_bf16 v[124:127], v[156:159], v[212:215], v[124:127]
	v_mfma_f32_16x16x32_bf16 v[120:123], v[164:167], v[212:215], v[120:123]
	v_mfma_f32_16x16x32_bf16 v[108:111], v[156:159], v[220:223], v[108:111]
	v_mfma_f32_16x16x32_bf16 v[104:107], v[164:167], v[220:223], v[104:107]
	v_mfma_f32_16x16x32_bf16 v[92:95], v[156:159], v[228:231], v[92:95]
	v_mfma_f32_16x16x32_bf16 v[88:91], v[164:167], v[228:231], v[88:91]
	v_mfma_f32_16x16x32_bf16 v[76:79], v[156:159], v[236:239], v[76:79]
	v_mfma_f32_16x16x32_bf16 v[72:75], v[164:167], v[236:239], v[72:75]
	v_mfma_f32_16x16x32_bf16 v[116:119], v[168:171], v[208:211], v[116:119]
	v_mfma_f32_16x16x32_bf16 v[112:115], v[176:179], v[208:211], v[112:115]
	v_mfma_f32_16x16x32_bf16 v[100:103], v[168:171], v[216:219], v[100:103]
	v_mfma_f32_16x16x32_bf16 v[96:99], v[176:179], v[216:219], v[96:99]
	v_mfma_f32_16x16x32_bf16 v[84:87], v[168:171], v[224:227], v[84:87]
	v_mfma_f32_16x16x32_bf16 v[80:83], v[176:179], v[224:227], v[80:83]
	v_mfma_f32_16x16x32_bf16 v[68:71], v[168:171], v[232:235], v[68:71]
	v_mfma_f32_16x16x32_bf16 v[64:67], v[176:179], v[232:235], v[64:67]
	v_mfma_f32_16x16x32_bf16 v[116:119], v[172:175], v[212:215], v[116:119]
	v_mfma_f32_16x16x32_bf16 v[112:115], v[204:207], v[212:215], v[112:115]
	v_mfma_f32_16x16x32_bf16 v[100:103], v[172:175], v[220:223], v[100:103]
	v_mfma_f32_16x16x32_bf16 v[96:99], v[204:207], v[220:223], v[96:99]
	v_mfma_f32_16x16x32_bf16 v[84:87], v[172:175], v[228:231], v[84:87]
	v_mfma_f32_16x16x32_bf16 v[80:83], v[204:207], v[228:231], v[80:83]
	v_mfma_f32_16x16x32_bf16 v[68:71], v[172:175], v[236:239], v[68:71]
	v_mfma_f32_16x16x32_bf16 v[64:67], v[204:207], v[236:239], v[64:67]
	s_barrier
	s_setprio 1
	s_add_i32 s4, s74, s28
	v_lshl_add_u64 v[180:181], v[180:181], 0, s[26:27]
	s_mov_b32 m0, s4
	ds_read_b128 v[208:211], v155 offset:49152
	ds_read_b128 v[212:215], v155 offset:50176
	ds_read_b128 v[216:219], v155 offset:51200
	ds_read_b128 v[220:223], v155 offset:52224
	ds_read_b128 v[224:227], v155 offset:53248
	ds_read_b128 v[228:231], v155 offset:54272
	ds_read_b128 v[232:235], v155 offset:55296
	ds_read_b128 v[236:239], v155 offset:56320
	global_load_lds_dwordx4 v[180:181], off
	s_add_i32 m0, s4, 0x2000
	s_add_u32 s4, s34, 0x20080
	v_lshl_add_u64 v[180:181], v[202:203], 0, s[26:27]
	s_addc_u32 s5, s35, 0
	s_add_i32 s34, s75, s28
	global_load_lds_dwordx4 v[180:181], off
	v_lshl_add_u64 v[180:181], s[4:5], 0, v[144:145]
	s_mov_b32 m0, s34
	s_nop 0
	global_load_lds_dwordx4 v[180:181], off
	v_lshl_add_u64 v[180:181], s[4:5], 0, v[132:133]
	s_add_i32 m0, s34, 0x2000
	s_nop 0
	global_load_lds_dwordx4 v[180:181], off
	v_lshl_add_u64 v[180:181], v[240:241], 0, s[26:27]
	s_mov_b32 m0, s68
	s_nop 0
	global_load_lds_dwordx4 v[180:181], off
	v_lshl_add_u64 v[180:181], v[242:243], 0, s[26:27]
	s_mov_b32 m0, s69
	s_nop 0
	global_load_lds_dwordx4 v[180:181], off
	s_setprio 0
	s_waitcnt vmcnt(8)
	s_waitcnt lgkmcnt(0)
	s_barrier
	s_waitcnt lgkmcnt(0)
	v_mfma_f32_16x16x32_bf16 v[60:63], v[138:141], v[208:211], v[60:63]
	v_mfma_f32_16x16x32_bf16 v[56:59], v[160:163], v[208:211], v[56:59]
	v_mfma_f32_16x16x32_bf16 v[44:47], v[138:141], v[216:219], v[44:47]
	v_mfma_f32_16x16x32_bf16 v[40:43], v[160:163], v[216:219], v[40:43]
	v_mfma_f32_16x16x32_bf16 v[28:31], v[138:141], v[224:227], v[28:31]
	v_mfma_f32_16x16x32_bf16 v[24:27], v[160:163], v[224:227], v[24:27]
	v_mfma_f32_16x16x32_bf16 v[12:15], v[138:141], v[232:235], v[12:15]
	v_mfma_f32_16x16x32_bf16 v[8:11], v[160:163], v[232:235], v[8:11]
	v_mfma_f32_16x16x32_bf16 v[60:63], v[156:159], v[212:215], v[60:63]
	v_mfma_f32_16x16x32_bf16 v[56:59], v[164:167], v[212:215], v[56:59]
	v_mfma_f32_16x16x32_bf16 v[44:47], v[156:159], v[220:223], v[44:47]
	v_mfma_f32_16x16x32_bf16 v[40:43], v[164:167], v[220:223], v[40:43]
	v_mfma_f32_16x16x32_bf16 v[28:31], v[156:159], v[228:231], v[28:31]
	v_mfma_f32_16x16x32_bf16 v[24:27], v[164:167], v[228:231], v[24:27]
	v_mfma_f32_16x16x32_bf16 v[12:15], v[156:159], v[236:239], v[12:15]
	v_mfma_f32_16x16x32_bf16 v[8:11], v[164:167], v[236:239], v[8:11]
	v_mfma_f32_16x16x32_bf16 v[52:55], v[168:171], v[208:211], v[52:55]
	v_mfma_f32_16x16x32_bf16 v[48:51], v[176:179], v[208:211], v[48:51]
	v_mfma_f32_16x16x32_bf16 v[36:39], v[168:171], v[216:219], v[36:39]
	v_mfma_f32_16x16x32_bf16 v[32:35], v[176:179], v[216:219], v[32:35]
	v_mfma_f32_16x16x32_bf16 v[20:23], v[168:171], v[224:227], v[20:23]
	v_mfma_f32_16x16x32_bf16 v[16:19], v[176:179], v[224:227], v[16:19]
	v_mfma_f32_16x16x32_bf16 v[4:7], v[168:171], v[232:235], v[4:7]
	v_mfma_f32_16x16x32_bf16 v[0:3], v[176:179], v[232:235], v[0:3]
	v_mfma_f32_16x16x32_bf16 v[52:55], v[172:175], v[212:215], v[52:55]
	v_mfma_f32_16x16x32_bf16 v[48:51], v[204:207], v[212:215], v[48:51]
	v_mfma_f32_16x16x32_bf16 v[36:39], v[172:175], v[220:223], v[36:39]
	v_mfma_f32_16x16x32_bf16 v[32:35], v[204:207], v[220:223], v[32:35]
	v_mfma_f32_16x16x32_bf16 v[20:23], v[172:175], v[228:231], v[20:23]
	v_mfma_f32_16x16x32_bf16 v[16:19], v[204:207], v[228:231], v[16:19]
	v_mfma_f32_16x16x32_bf16 v[4:7], v[172:175], v[236:239], v[4:7]
	v_mfma_f32_16x16x32_bf16 v[0:3], v[204:207], v[236:239], v[0:3]
	s_barrier
	s_setprio 1
	s_add_i32 s73, s73, 2
	s_add_u32 s58, s58, 0x100
	s_addc_u32 s59, s59, 0
	s_add_u32 s71, s71, 0x100
	s_addc_u32 s72, s72, 0
	s_cmp_gt_u32 s73, 5
	s_cbranch_scc0 .LBB0_1093
	s_setprio 0
	s_and_b64 vcc, exec, s[46:47]
	s_cbranch_vccz .LBB0_1096
	s_barrier

.LBB0_1117:
	s_setprio 1
	s_add_u32 s4, s54, 0xfffe0080
	s_addc_u32 s5, s55, -1
	s_add_i32 s74, 0, 0x10000
	s_cmp_eq_u32 s73, 4
	s_cselect_b32 s59, s33, s5
	s_cselect_b32 s58, s36, s4
	s_cselect_b32 s35, s47, s72
	s_cselect_b32 s34, s49, s71
	s_add_i32 s75, 0, 0x14000
	v_add_u32_e32 v164, s74, v143
	v_add_u32_e32 v180, s75, v143
	ds_read_b128 v[138:141], v164
	ds_read_b128 v[156:159], v164 offset:1024
	ds_read_b128 v[160:163], v164 offset:2048
	ds_read_b128 v[164:167], v164 offset:3072
	ds_read_b128 v[168:171], v180
	ds_read_b128 v[172:175], v180 offset:1024
	ds_read_b128 v[176:179], v180 offset:2048
	ds_read_b128 v[204:207], v180 offset:3072
	v_lshl_add_u64 v[180:181], s[54:55], 0, v[134:135]
	s_add_i32 m0, s64, 0xc000
	ds_read_b128 v[208:211], v155
	ds_read_b128 v[212:215], v155 offset:1024
	ds_read_b128 v[216:219], v155 offset:2048
	ds_read_b128 v[220:223], v155 offset:3072
	ds_read_b128 v[224:227], v155 offset:4096
	ds_read_b128 v[228:231], v155 offset:5120
	ds_read_b128 v[232:235], v155 offset:6144
	ds_read_b128 v[236:239], v155 offset:7168
	global_load_lds_dwordx4 v[180:181], off
	v_lshl_add_u64 v[180:181], s[54:55], 0, v[136:137]
	s_add_i32 m0, s64, 0xe000
	s_nop 0
	global_load_lds_dwordx4 v[180:181], off
	s_setprio 0
	s_waitcnt vmcnt(8)
	s_waitcnt lgkmcnt(0)
	s_barrier
	s_waitcnt lgkmcnt(0)
	v_mfma_f32_16x16x32_bf16 v[124:127], v[138:141], v[208:211], v[124:127]
	v_mfma_f32_16x16x32_bf16 v[120:123], v[160:163], v[208:211], v[120:123]
	v_mfma_f32_16x16x32_bf16 v[108:111], v[138:141], v[216:219], v[108:111]
	v_mfma_f32_16x16x32_bf16 v[104:107], v[160:163], v[216:219], v[104:107]
	v_mfma_f32_16x16x32_bf16 v[92:95], v[138:141], v[224:227], v[92:95]
	v_mfma_f32_16x16x32_bf16 v[88:91], v[160:163], v[224:227], v[88:91]
	v_mfma_f32_16x16x32_bf16 v[76:79], v[138:141], v[232:235], v[76:79]
	v_mfma_f32_16x16x32_bf16 v[72:75], v[160:163], v[232:235], v[72:75]
	v_mfma_f32_16x16x32_bf16 v[124:127], v[156:159], v[212:215], v[124:127]
	v_mfma_f32_16x16x32_bf16 v[120:123], v[164:167], v[212:215], v[120:123]
	v_mfma_f32_16x16x32_bf16 v[108:111], v[156:159], v[220:223], v[108:111]
	v_mfma_f32_16x16x32_bf16 v[104:107], v[164:167], v[220:223], v[104:107]
	v_mfma_f32_16x16x32_bf16 v[92:95], v[156:159], v[228:231], v[92:95]
	v_mfma_f32_16x16x32_bf16 v[88:91], v[164:167], v[228:231], v[88:91]
	v_mfma_f32_16x16x32_bf16 v[76:79], v[156:159], v[236:239], v[76:79]
	v_mfma_f32_16x16x32_bf16 v[72:75], v[164:167], v[236:239], v[72:75]
	v_mfma_f32_16x16x32_bf16 v[116:119], v[168:171], v[208:211], v[116:119]
	v_mfma_f32_16x16x32_bf16 v[112:115], v[176:179], v[208:211], v[112:115]
	v_mfma_f32_16x16x32_bf16 v[100:103], v[168:171], v[216:219], v[100:103]
	v_mfma_f32_16x16x32_bf16 v[96:99], v[176:179], v[216:219], v[96:99]
	v_mfma_f32_16x16x32_bf16 v[84:87], v[168:171], v[224:227], v[84:87]
	v_mfma_f32_16x16x32_bf16 v[80:83], v[176:179], v[224:227], v[80:83]
	v_mfma_f32_16x16x32_bf16 v[68:71], v[168:171], v[232:235], v[68:71]
	v_mfma_f32_16x16x32_bf16 v[64:67], v[176:179], v[232:235], v[64:67]
	v_mfma_f32_16x16x32_bf16 v[116:119], v[172:175], v[212:215], v[116:119]
	v_mfma_f32_16x16x32_bf16 v[112:115], v[204:207], v[212:215], v[112:115]
	v_mfma_f32_16x16x32_bf16 v[100:103], v[172:175], v[220:223], v[100:103]
	v_mfma_f32_16x16x32_bf16 v[96:99], v[204:207], v[220:223], v[96:99]
	v_mfma_f32_16x16x32_bf16 v[84:87], v[172:175], v[228:231], v[84:87]
	v_mfma_f32_16x16x32_bf16 v[80:83], v[204:207], v[228:231], v[80:83]
	v_mfma_f32_16x16x32_bf16 v[68:71], v[172:175], v[236:239], v[68:71]
	v_mfma_f32_16x16x32_bf16 v[64:67], v[204:207], v[236:239], v[64:67]
	s_barrier
	s_setprio 1
	s_add_i32 s4, s74, s63
	v_lshl_add_u64 v[180:181], s[34:35], 0, v[144:145]
	s_mov_b32 m0, s4
	ds_read_b128 v[208:211], v155 offset:16384
	ds_read_b128 v[212:215], v155 offset:17408
	ds_read_b128 v[216:219], v155 offset:18432
	ds_read_b128 v[220:223], v155 offset:19456
	ds_read_b128 v[224:227], v155 offset:20480
	ds_read_b128 v[228:231], v155 offset:21504
	ds_read_b128 v[232:235], v155 offset:22528
	ds_read_b128 v[236:239], v155 offset:23552
	global_load_lds_dwordx4 v[180:181], off
	s_add_i32 m0, s4, 0x2000
	s_add_u32 s4, s34, 0x20000
	v_lshl_add_u64 v[202:203], s[34:35], 0, v[132:133]
	s_addc_u32 s5, s35, 0
	s_add_i32 s74, s75, s63
	global_load_lds_dwordx4 v[202:203], off
	v_lshl_add_u64 v[240:241], s[4:5], 0, v[144:145]
	s_mov_b32 m0, s74
	v_lshl_add_u64 v[242:243], s[58:59], 0, v[130:131]
	global_load_lds_dwordx4 v[240:241], off
	v_lshl_add_u64 v[240:241], s[4:5], 0, v[132:133]
	s_add_i32 m0, s74, 0x2000
	s_nop 0
	global_load_lds_dwordx4 v[240:241], off
	v_lshl_add_u64 v[240:241], s[58:59], 0, v[128:129]
	s_mov_b32 m0, s64
	s_nop 0
	global_load_lds_dwordx4 v[240:241], off
	s_mov_b32 m0, s65
	s_nop 0
	global_load_lds_dwordx4 v[242:243], off
	s_setprio 0
	s_waitcnt vmcnt(8)
	s_waitcnt lgkmcnt(0)
	s_barrier
	s_waitcnt lgkmcnt(0)
	v_mfma_f32_16x16x32_bf16 v[60:63], v[138:141], v[208:211], v[60:63]
	v_mfma_f32_16x16x32_bf16 v[56:59], v[160:163], v[208:211], v[56:59]
	v_mfma_f32_16x16x32_bf16 v[44:47], v[138:141], v[216:219], v[44:47]
	v_mfma_f32_16x16x32_bf16 v[40:43], v[160:163], v[216:219], v[40:43]
	v_mfma_f32_16x16x32_bf16 v[28:31], v[138:141], v[224:227], v[28:31]
	v_mfma_f32_16x16x32_bf16 v[24:27], v[160:163], v[224:227], v[24:27]
	v_mfma_f32_16x16x32_bf16 v[12:15], v[138:141], v[232:235], v[12:15]
	v_mfma_f32_16x16x32_bf16 v[8:11], v[160:163], v[232:235], v[8:11]
	v_mfma_f32_16x16x32_bf16 v[60:63], v[156:159], v[212:215], v[60:63]
	v_mfma_f32_16x16x32_bf16 v[56:59], v[164:167], v[212:215], v[56:59]
	v_mfma_f32_16x16x32_bf16 v[44:47], v[156:159], v[220:223], v[44:47]
	v_mfma_f32_16x16x32_bf16 v[40:43], v[164:167], v[220:223], v[40:43]
	v_mfma_f32_16x16x32_bf16 v[28:31], v[156:159], v[228:231], v[28:31]
	v_mfma_f32_16x16x32_bf16 v[24:27], v[164:167], v[228:231], v[24:27]
	v_mfma_f32_16x16x32_bf16 v[12:15], v[156:159], v[236:239], v[12:15]
	v_mfma_f32_16x16x32_bf16 v[8:11], v[164:167], v[236:239], v[8:11]
	v_mfma_f32_16x16x32_bf16 v[52:55], v[168:171], v[208:211], v[52:55]
	v_mfma_f32_16x16x32_bf16 v[48:51], v[176:179], v[208:211], v[48:51]
	v_mfma_f32_16x16x32_bf16 v[36:39], v[168:171], v[216:219], v[36:39]
	v_mfma_f32_16x16x32_bf16 v[32:35], v[176:179], v[216:219], v[32:35]
	v_mfma_f32_16x16x32_bf16 v[20:23], v[168:171], v[224:227], v[20:23]
	v_mfma_f32_16x16x32_bf16 v[16:19], v[176:179], v[224:227], v[16:19]
	v_mfma_f32_16x16x32_bf16 v[4:7], v[168:171], v[232:235], v[4:7]
	v_mfma_f32_16x16x32_bf16 v[0:3], v[176:179], v[232:235], v[0:3]
	v_mfma_f32_16x16x32_bf16 v[52:55], v[172:175], v[212:215], v[52:55]
	v_mfma_f32_16x16x32_bf16 v[48:51], v[204:207], v[212:215], v[48:51]
	v_mfma_f32_16x16x32_bf16 v[36:39], v[172:175], v[220:223], v[36:39]
	v_mfma_f32_16x16x32_bf16 v[32:35], v[204:207], v[220:223], v[32:35]
	v_mfma_f32_16x16x32_bf16 v[20:23], v[172:175], v[228:231], v[20:23]
	v_mfma_f32_16x16x32_bf16 v[16:19], v[204:207], v[228:231], v[16:19]
	v_mfma_f32_16x16x32_bf16 v[4:7], v[172:175], v[236:239], v[4:7]
	v_mfma_f32_16x16x32_bf16 v[0:3], v[204:207], v[236:239], v[0:3]
	s_barrier
	s_setprio 1
	s_add_i32 s74, 0, 0x18000
	s_add_i32 s75, 0, 0x1c000
	v_add_u32_e32 v164, s74, v143
	v_add_u32_e32 v204, s75, v143
	ds_read_b128 v[138:141], v164
	ds_read_b128 v[156:159], v164 offset:1024
	ds_read_b128 v[160:163], v164 offset:2048
	ds_read_b128 v[164:167], v164 offset:3072
	ds_read_b128 v[168:171], v204
	ds_read_b128 v[172:175], v204 offset:1024
	ds_read_b128 v[176:179], v204 offset:2048
	ds_read_b128 v[204:207], v204 offset:3072
	s_add_u32 s4, s58, 0x20000
	s_addc_u32 s5, s59, 0
	s_mov_b32 m0, s66
	v_lshl_add_u64 v[244:245], s[4:5], 0, v[128:129]
	ds_read_b128 v[208:211], v155 offset:32768
	ds_read_b128 v[212:215], v155 offset:33792
	ds_read_b128 v[216:219], v155 offset:34816
	ds_read_b128 v[220:223], v155 offset:35840
	ds_read_b128 v[224:227], v155 offset:36864
	ds_read_b128 v[228:231], v155 offset:37888
	ds_read_b128 v[232:235], v155 offset:38912
	ds_read_b128 v[236:239], v155 offset:39936
	global_load_lds_dwordx4 v[244:245], off
	v_lshl_add_u64 v[244:245], s[4:5], 0, v[130:131]
	s_mov_b32 m0, s67
	s_nop 0
	global_load_lds_dwordx4 v[244:245], off
	s_setprio 0
	s_waitcnt vmcnt(8)
	s_waitcnt lgkmcnt(0)
	s_barrier
	s_waitcnt lgkmcnt(0)
	v_mfma_f32_16x16x32_bf16 v[124:127], v[138:141], v[208:211], v[124:127]
	v_mfma_f32_16x16x32_bf16 v[120:123], v[160:163], v[208:211], v[120:123]
	v_mfma_f32_16x16x32_bf16 v[108:111], v[138:141], v[216:219], v[108:111]
	v_mfma_f32_16x16x32_bf16 v[104:107], v[160:163], v[216:219], v[104:107]
	v_mfma_f32_16x16x32_bf16 v[92:95], v[138:141], v[224:227], v[92:95]
	v_mfma_f32_16x16x32_bf16 v[88:91], v[160:163], v[224:227], v[88:91]
	v_mfma_f32_16x16x32_bf16 v[76:79], v[138:141], v[232:235], v[76:79]
	v_mfma_f32_16x16x32_bf16 v[72:75], v[160:163], v[232:235], v[72:75]
	v_mfma_f32_16x16x32_bf16 v[124:127], v[156:159], v[212:215], v[124:127]
	v_mfma_f32_16x16x32_bf16 v[120:123], v[164:167], v[212:215], v[120:123]
	v_mfma_f32_16x16x32_bf16 v[108:111], v[156:159], v[220:223], v[108:111]
	v_mfma_f32_16x16x32_bf16 v[104:107], v[164:167], v[220:223], v[104:107]
	v_mfma_f32_16x16x32_bf16 v[92:95], v[156:159], v[228:231], v[92:95]
	v_mfma_f32_16x16x32_bf16 v[88:91], v[164:167], v[228:231], v[88:91]
	v_mfma_f32_16x16x32_bf16 v[76:79], v[156:159], v[236:239], v[76:79]
	v_mfma_f32_16x16x32_bf16 v[72:75], v[164:167], v[236:239], v[72:75]
	v_mfma_f32_16x16x32_bf16 v[116:119], v[168:171], v[208:211], v[116:119]
	v_mfma_f32_16x16x32_bf16 v[112:115], v[176:179], v[208:211], v[112:115]
	v_mfma_f32_16x16x32_bf16 v[100:103], v[168:171], v[216:219], v[100:103]
	v_mfma_f32_16x16x32_bf16 v[96:99], v[176:179], v[216:219], v[96:99]
	v_mfma_f32_16x16x32_bf16 v[84:87], v[168:171], v[224:227], v[84:87]
	v_mfma_f32_16x16x32_bf16 v[80:83], v[176:179], v[224:227], v[80:83]
	v_mfma_f32_16x16x32_bf16 v[68:71], v[168:171], v[232:235], v[68:71]
	v_mfma_f32_16x16x32_bf16 v[64:67], v[176:179], v[232:235], v[64:67]
	v_mfma_f32_16x16x32_bf16 v[116:119], v[172:175], v[212:215], v[116:119]
	v_mfma_f32_16x16x32_bf16 v[112:115], v[204:207], v[212:215], v[112:115]
	v_mfma_f32_16x16x32_bf16 v[100:103], v[172:175], v[220:223], v[100:103]
	v_mfma_f32_16x16x32_bf16 v[96:99], v[204:207], v[220:223], v[96:99]
	v_mfma_f32_16x16x32_bf16 v[84:87], v[172:175], v[228:231], v[84:87]
	v_mfma_f32_16x16x32_bf16 v[80:83], v[204:207], v[228:231], v[80:83]
	v_mfma_f32_16x16x32_bf16 v[68:71], v[172:175], v[236:239], v[68:71]
	v_mfma_f32_16x16x32_bf16 v[64:67], v[204:207], v[236:239], v[64:67]
	s_barrier
	s_setprio 1
	s_add_i32 s4, s74, s63
	v_lshl_add_u64 v[180:181], v[180:181], 0, s[26:27]
	s_mov_b32 m0, s4
	ds_read_b128 v[208:211], v155 offset:49152
	ds_read_b128 v[212:215], v155 offset:50176
	ds_read_b128 v[216:219], v155 offset:51200
	ds_read_b128 v[220:223], v155 offset:52224
	ds_read_b128 v[224:227], v155 offset:53248
	ds_read_b128 v[228:231], v155 offset:54272
	ds_read_b128 v[232:235], v155 offset:55296
	ds_read_b128 v[236:239], v155 offset:56320
	global_load_lds_dwordx4 v[180:181], off
	s_add_i32 m0, s4, 0x2000
	s_add_u32 s4, s34, 0x20080
	v_lshl_add_u64 v[180:181], v[202:203], 0, s[26:27]
	s_addc_u32 s5, s35, 0
	s_add_i32 s34, s75, s63
	global_load_lds_dwordx4 v[180:181], off
	v_lshl_add_u64 v[180:181], s[4:5], 0, v[144:145]
	s_mov_b32 m0, s34
	s_nop 0
	global_load_lds_dwordx4 v[180:181], off
	v_lshl_add_u64 v[180:181], s[4:5], 0, v[132:133]
	s_add_i32 m0, s34, 0x2000
	s_nop 0
	global_load_lds_dwordx4 v[180:181], off
	v_lshl_add_u64 v[180:181], v[240:241], 0, s[26:27]
	s_mov_b32 m0, s68
	s_nop 0
	global_load_lds_dwordx4 v[180:181], off
	v_lshl_add_u64 v[180:181], v[242:243], 0, s[26:27]
	s_mov_b32 m0, s69
	s_nop 0
	global_load_lds_dwordx4 v[180:181], off
	s_setprio 0
	s_waitcnt vmcnt(8)
	s_waitcnt lgkmcnt(0)
	s_barrier
	s_waitcnt lgkmcnt(0)
	v_mfma_f32_16x16x32_bf16 v[60:63], v[138:141], v[208:211], v[60:63]
	v_mfma_f32_16x16x32_bf16 v[56:59], v[160:163], v[208:211], v[56:59]
	v_mfma_f32_16x16x32_bf16 v[44:47], v[138:141], v[216:219], v[44:47]
	v_mfma_f32_16x16x32_bf16 v[40:43], v[160:163], v[216:219], v[40:43]
	v_mfma_f32_16x16x32_bf16 v[28:31], v[138:141], v[224:227], v[28:31]
	v_mfma_f32_16x16x32_bf16 v[24:27], v[160:163], v[224:227], v[24:27]
	v_mfma_f32_16x16x32_bf16 v[12:15], v[138:141], v[232:235], v[12:15]
	v_mfma_f32_16x16x32_bf16 v[8:11], v[160:163], v[232:235], v[8:11]
	v_mfma_f32_16x16x32_bf16 v[60:63], v[156:159], v[212:215], v[60:63]
	v_mfma_f32_16x16x32_bf16 v[56:59], v[164:167], v[212:215], v[56:59]
	v_mfma_f32_16x16x32_bf16 v[44:47], v[156:159], v[220:223], v[44:47]
	v_mfma_f32_16x16x32_bf16 v[40:43], v[164:167], v[220:223], v[40:43]
	v_mfma_f32_16x16x32_bf16 v[28:31], v[156:159], v[228:231], v[28:31]
	v_mfma_f32_16x16x32_bf16 v[24:27], v[164:167], v[228:231], v[24:27]
	v_mfma_f32_16x16x32_bf16 v[12:15], v[156:159], v[236:239], v[12:15]
	v_mfma_f32_16x16x32_bf16 v[8:11], v[164:167], v[236:239], v[8:11]
	v_mfma_f32_16x16x32_bf16 v[52:55], v[168:171], v[208:211], v[52:55]
	v_mfma_f32_16x16x32_bf16 v[48:51], v[176:179], v[208:211], v[48:51]
	v_mfma_f32_16x16x32_bf16 v[36:39], v[168:171], v[216:219], v[36:39]
	v_mfma_f32_16x16x32_bf16 v[32:35], v[176:179], v[216:219], v[32:35]
	v_mfma_f32_16x16x32_bf16 v[20:23], v[168:171], v[224:227], v[20:23]
	v_mfma_f32_16x16x32_bf16 v[16:19], v[176:179], v[224:227], v[16:19]
	v_mfma_f32_16x16x32_bf16 v[4:7], v[168:171], v[232:235], v[4:7]
	v_mfma_f32_16x16x32_bf16 v[0:3], v[176:179], v[232:235], v[0:3]
	v_mfma_f32_16x16x32_bf16 v[52:55], v[172:175], v[212:215], v[52:55]
	v_mfma_f32_16x16x32_bf16 v[48:51], v[204:207], v[212:215], v[48:51]
	v_mfma_f32_16x16x32_bf16 v[36:39], v[172:175], v[220:223], v[36:39]
	v_mfma_f32_16x16x32_bf16 v[32:35], v[204:207], v[220:223], v[32:35]
	v_mfma_f32_16x16x32_bf16 v[20:23], v[172:175], v[228:231], v[20:23]
	v_mfma_f32_16x16x32_bf16 v[16:19], v[204:207], v[228:231], v[16:19]
	v_mfma_f32_16x16x32_bf16 v[4:7], v[172:175], v[236:239], v[4:7]
	v_mfma_f32_16x16x32_bf16 v[0:3], v[204:207], v[236:239], v[0:3]
	s_barrier
	s_setprio 1
	s_add_i32 s73, s73, 2
	s_add_u32 s54, s54, 0x100
	s_addc_u32 s55, s55, 0
	s_add_u32 s71, s71, 0x100
	s_addc_u32 s72, s72, 0
	s_cmp_gt_u32 s73, 5
	s_cbranch_scc0 .LBB0_1117
	s_setprio 0
	s_and_b64 vcc, exec, s[44:45]
	s_cbranch_vccz .LBB0_1120
	s_barrier

.LBB0_1207:
	s_setprio 1
	s_add_u32 s62, s60, 0x100
	s_addc_u32 s63, s61, 0
	s_add_i32 s4, 0, 0x10000
	s_cmp_eq_u32 s29, 12
	s_cselect_b32 s65, s55, s63
	s_cselect_b32 s64, s54, s62
	v_add_u32_e32 v142, s4, v160
	s_cselect_b32 s35, s59, s28
	s_cselect_b32 s34, s58, s3
	s_add_i32 s45, 0, 0x14000
	ds_read_b128 v[138:141], v142
	ds_read_b128 v[154:157], v142 offset:1024
	ds_read_b128 v[172:175], v142 offset:2048
	ds_read_b128 v[176:179], v142 offset:3072
	v_add_u32_e32 v142, s45, v160
	ds_read_b128 v[204:207], v142
	ds_read_b128 v[208:211], v142 offset:1024
	ds_read_b128 v[212:215], v142 offset:2048
	ds_read_b128 v[216:219], v142 offset:3072
	v_lshl_add_u64 v[142:143], s[60:61], 0, v[134:135]
	s_add_i32 m0, s69, 0xc000
	ds_read_b128 v[220:223], v170
	ds_read_b128 v[224:227], v170 offset:1024
	ds_read_b128 v[228:231], v170 offset:2048
	ds_read_b128 v[232:235], v170 offset:3072
	ds_read_b128 v[236:239], v170 offset:4096
	ds_read_b128 v[240:243], v170 offset:5120
	ds_read_b128 v[244:247], v170 offset:6144
	ds_read_b128 v[248:251], v170 offset:7168
	global_load_lds_dwordx4 v[142:143], off
	v_lshl_add_u64 v[142:143], s[60:61], 0, v[136:137]
	s_add_i32 m0, s69, 0xe000
	s_nop 0
	global_load_lds_dwordx4 v[142:143], off
	s_setprio 0
	s_waitcnt vmcnt(8)
	s_waitcnt lgkmcnt(0)
	s_barrier
	s_waitcnt lgkmcnt(0)
	v_mfma_f32_16x16x32_bf16 v[124:127], v[138:141], v[220:223], v[124:127]
	v_mfma_f32_16x16x32_bf16 v[120:123], v[172:175], v[220:223], v[120:123]
	v_mfma_f32_16x16x32_bf16 v[108:111], v[138:141], v[228:231], v[108:111]
	v_mfma_f32_16x16x32_bf16 v[104:107], v[172:175], v[228:231], v[104:107]
	v_mfma_f32_16x16x32_bf16 v[92:95], v[138:141], v[236:239], v[92:95]
	v_mfma_f32_16x16x32_bf16 v[88:91], v[172:175], v[236:239], v[88:91]
	v_mfma_f32_16x16x32_bf16 v[76:79], v[138:141], v[244:247], v[76:79]
	v_mfma_f32_16x16x32_bf16 v[72:75], v[172:175], v[244:247], v[72:75]
	v_mfma_f32_16x16x32_bf16 v[124:127], v[154:157], v[224:227], v[124:127]
	v_mfma_f32_16x16x32_bf16 v[120:123], v[176:179], v[224:227], v[120:123]
	v_mfma_f32_16x16x32_bf16 v[108:111], v[154:157], v[232:235], v[108:111]
	v_mfma_f32_16x16x32_bf16 v[104:107], v[176:179], v[232:235], v[104:107]
	v_mfma_f32_16x16x32_bf16 v[92:95], v[154:157], v[240:243], v[92:95]
	v_mfma_f32_16x16x32_bf16 v[88:91], v[176:179], v[240:243], v[88:91]
	v_mfma_f32_16x16x32_bf16 v[76:79], v[154:157], v[248:251], v[76:79]
	v_mfma_f32_16x16x32_bf16 v[72:75], v[176:179], v[248:251], v[72:75]
	v_mfma_f32_16x16x32_bf16 v[116:119], v[204:207], v[220:223], v[116:119]
	v_mfma_f32_16x16x32_bf16 v[112:115], v[212:215], v[220:223], v[112:115]
	v_mfma_f32_16x16x32_bf16 v[100:103], v[204:207], v[228:231], v[100:103]
	v_mfma_f32_16x16x32_bf16 v[96:99], v[212:215], v[228:231], v[96:99]
	v_mfma_f32_16x16x32_bf16 v[84:87], v[204:207], v[236:239], v[84:87]
	v_mfma_f32_16x16x32_bf16 v[80:83], v[212:215], v[236:239], v[80:83]
	v_mfma_f32_16x16x32_bf16 v[68:71], v[204:207], v[244:247], v[68:71]
	v_mfma_f32_16x16x32_bf16 v[64:67], v[212:215], v[244:247], v[64:67]
	v_mfma_f32_16x16x32_bf16 v[116:119], v[208:211], v[224:227], v[116:119]
	v_mfma_f32_16x16x32_bf16 v[112:115], v[216:219], v[224:227], v[112:115]
	v_mfma_f32_16x16x32_bf16 v[100:103], v[208:211], v[232:235], v[100:103]
	v_mfma_f32_16x16x32_bf16 v[96:99], v[216:219], v[232:235], v[96:99]
	v_mfma_f32_16x16x32_bf16 v[84:87], v[208:211], v[240:243], v[84:87]
	v_mfma_f32_16x16x32_bf16 v[80:83], v[216:219], v[240:243], v[80:83]
	v_mfma_f32_16x16x32_bf16 v[68:71], v[208:211], v[248:251], v[68:71]
	v_mfma_f32_16x16x32_bf16 v[64:67], v[216:219], v[248:251], v[64:67]
	s_barrier
	s_setprio 1
	s_add_i32 s4, s4, s33
	v_lshl_add_u64 v[142:143], s[34:35], 0, v[128:129]
	s_mov_b32 m0, s4
	ds_read_b128 v[220:223], v170 offset:16384
	ds_read_b128 v[224:227], v170 offset:17408
	ds_read_b128 v[228:231], v170 offset:18432
	ds_read_b128 v[232:235], v170 offset:19456
	ds_read_b128 v[236:239], v170 offset:20480
	ds_read_b128 v[240:243], v170 offset:21504
	ds_read_b128 v[244:247], v170 offset:22528
	ds_read_b128 v[248:251], v170 offset:23552
	global_load_lds_dwordx4 v[142:143], off
	s_add_i32 m0, s4, 0x2000
	s_add_u32 s4, s34, 0x40000
	v_lshl_add_u64 v[158:159], s[34:35], 0, v[130:131]
	s_addc_u32 s5, s35, 0
	s_add_i32 s45, s45, s33
	global_load_lds_dwordx4 v[158:159], off
	v_lshl_add_u64 v[180:181], s[4:5], 0, v[128:129]
	s_mov_b32 m0, s45
	v_lshl_add_u64 v[202:203], s[64:65], 0, v[130:131]
	global_load_lds_dwordx4 v[180:181], off
	v_lshl_add_u64 v[180:181], s[4:5], 0, v[130:131]
	s_add_i32 m0, s45, 0x2000
	s_nop 0
	global_load_lds_dwordx4 v[180:181], off
	v_lshl_add_u64 v[180:181], s[64:65], 0, v[128:129]
	s_mov_b32 m0, s69
	s_nop 0
	global_load_lds_dwordx4 v[180:181], off
	s_mov_b32 m0, s70
	s_nop 0
	global_load_lds_dwordx4 v[202:203], off
	s_setprio 0
	s_waitcnt vmcnt(8)
	s_waitcnt lgkmcnt(0)
	s_barrier
	s_waitcnt lgkmcnt(0)
	v_mfma_f32_16x16x32_bf16 v[60:63], v[138:141], v[220:223], v[60:63]
	v_mfma_f32_16x16x32_bf16 v[56:59], v[172:175], v[220:223], v[56:59]
	v_mfma_f32_16x16x32_bf16 v[44:47], v[138:141], v[228:231], v[44:47]
	v_mfma_f32_16x16x32_bf16 v[40:43], v[172:175], v[228:231], v[40:43]
	v_mfma_f32_16x16x32_bf16 v[28:31], v[138:141], v[236:239], v[28:31]
	v_mfma_f32_16x16x32_bf16 v[24:27], v[172:175], v[236:239], v[24:27]
	v_mfma_f32_16x16x32_bf16 v[12:15], v[138:141], v[244:247], v[12:15]
	v_mfma_f32_16x16x32_bf16 v[8:11], v[172:175], v[244:247], v[8:11]
	v_mfma_f32_16x16x32_bf16 v[60:63], v[154:157], v[224:227], v[60:63]
	v_mfma_f32_16x16x32_bf16 v[56:59], v[176:179], v[224:227], v[56:59]
	v_mfma_f32_16x16x32_bf16 v[44:47], v[154:157], v[232:235], v[44:47]
	v_mfma_f32_16x16x32_bf16 v[40:43], v[176:179], v[232:235], v[40:43]
	v_mfma_f32_16x16x32_bf16 v[28:31], v[154:157], v[240:243], v[28:31]
	v_mfma_f32_16x16x32_bf16 v[24:27], v[176:179], v[240:243], v[24:27]
	v_mfma_f32_16x16x32_bf16 v[12:15], v[154:157], v[248:251], v[12:15]
	v_mfma_f32_16x16x32_bf16 v[8:11], v[176:179], v[248:251], v[8:11]
	v_mfma_f32_16x16x32_bf16 v[52:55], v[204:207], v[220:223], v[52:55]
	v_mfma_f32_16x16x32_bf16 v[48:51], v[212:215], v[220:223], v[48:51]
	v_mfma_f32_16x16x32_bf16 v[36:39], v[204:207], v[228:231], v[36:39]
	v_mfma_f32_16x16x32_bf16 v[32:35], v[212:215], v[228:231], v[32:35]
	v_mfma_f32_16x16x32_bf16 v[20:23], v[204:207], v[236:239], v[20:23]
	v_mfma_f32_16x16x32_bf16 v[16:19], v[212:215], v[236:239], v[16:19]
	v_mfma_f32_16x16x32_bf16 v[4:7], v[204:207], v[244:247], v[4:7]
	v_mfma_f32_16x16x32_bf16 v[0:3], v[212:215], v[244:247], v[0:3]
	v_mfma_f32_16x16x32_bf16 v[52:55], v[208:211], v[224:227], v[52:55]
	v_mfma_f32_16x16x32_bf16 v[48:51], v[216:219], v[224:227], v[48:51]
	v_mfma_f32_16x16x32_bf16 v[36:39], v[208:211], v[232:235], v[36:39]
	v_mfma_f32_16x16x32_bf16 v[32:35], v[216:219], v[232:235], v[32:35]
	v_mfma_f32_16x16x32_bf16 v[20:23], v[208:211], v[240:243], v[20:23]
	v_mfma_f32_16x16x32_bf16 v[16:19], v[216:219], v[240:243], v[16:19]
	v_mfma_f32_16x16x32_bf16 v[4:7], v[208:211], v[248:251], v[4:7]
	v_mfma_f32_16x16x32_bf16 v[0:3], v[216:219], v[248:251], v[0:3]
	s_barrier
	s_setprio 1
	s_add_i32 s45, 0, 0x18000
	v_add_u32_e32 v144, s45, v160
	s_add_i32 s51, 0, 0x1c000
	ds_read_b128 v[138:141], v144
	ds_read_b128 v[154:157], v144 offset:1024
	ds_read_b128 v[172:175], v144 offset:2048
	ds_read_b128 v[176:179], v144 offset:3072
	v_add_u32_e32 v144, s51, v160
	ds_read_b128 v[204:207], v144
	ds_read_b128 v[208:211], v144 offset:1024
	ds_read_b128 v[212:215], v144 offset:2048
	ds_read_b128 v[216:219], v144 offset:3072
	s_add_u32 s4, s64, 0x40000
	s_addc_u32 s5, s65, 0
	s_mov_b32 m0, s71
	v_lshl_add_u64 v[252:253], s[4:5], 0, v[128:129]
	ds_read_b128 v[220:223], v170 offset:32768
	ds_read_b128 v[224:227], v170 offset:33792
	ds_read_b128 v[228:231], v170 offset:34816
	ds_read_b128 v[232:235], v170 offset:35840
	ds_read_b128 v[236:239], v170 offset:36864
	ds_read_b128 v[240:243], v170 offset:37888
	ds_read_b128 v[244:247], v170 offset:38912
	ds_read_b128 v[248:251], v170 offset:39936
	global_load_lds_dwordx4 v[252:253], off
	v_lshl_add_u64 v[252:253], s[4:5], 0, v[130:131]
	s_mov_b32 m0, s72
	s_nop 0
	global_load_lds_dwordx4 v[252:253], off
	s_setprio 0
	s_waitcnt vmcnt(8)
	s_waitcnt lgkmcnt(0)
	s_barrier
	s_waitcnt lgkmcnt(0)
	v_mfma_f32_16x16x32_bf16 v[124:127], v[138:141], v[220:223], v[124:127]
	v_mfma_f32_16x16x32_bf16 v[120:123], v[172:175], v[220:223], v[120:123]
	v_mfma_f32_16x16x32_bf16 v[108:111], v[138:141], v[228:231], v[108:111]
	v_mfma_f32_16x16x32_bf16 v[104:107], v[172:175], v[228:231], v[104:107]
	v_mfma_f32_16x16x32_bf16 v[92:95], v[138:141], v[236:239], v[92:95]
	v_mfma_f32_16x16x32_bf16 v[88:91], v[172:175], v[236:239], v[88:91]
	v_mfma_f32_16x16x32_bf16 v[76:79], v[138:141], v[244:247], v[76:79]
	v_mfma_f32_16x16x32_bf16 v[72:75], v[172:175], v[244:247], v[72:75]
	v_mfma_f32_16x16x32_bf16 v[124:127], v[154:157], v[224:227], v[124:127]
	v_mfma_f32_16x16x32_bf16 v[120:123], v[176:179], v[224:227], v[120:123]
	v_mfma_f32_16x16x32_bf16 v[108:111], v[154:157], v[232:235], v[108:111]
	v_mfma_f32_16x16x32_bf16 v[104:107], v[176:179], v[232:235], v[104:107]
	v_mfma_f32_16x16x32_bf16 v[92:95], v[154:157], v[240:243], v[92:95]
	v_mfma_f32_16x16x32_bf16 v[88:91], v[176:179], v[240:243], v[88:91]
	v_mfma_f32_16x16x32_bf16 v[76:79], v[154:157], v[248:251], v[76:79]
	v_mfma_f32_16x16x32_bf16 v[72:75], v[176:179], v[248:251], v[72:75]
	v_mfma_f32_16x16x32_bf16 v[116:119], v[204:207], v[220:223], v[116:119]
	v_mfma_f32_16x16x32_bf16 v[112:115], v[212:215], v[220:223], v[112:115]
	v_mfma_f32_16x16x32_bf16 v[100:103], v[204:207], v[228:231], v[100:103]
	v_mfma_f32_16x16x32_bf16 v[96:99], v[212:215], v[228:231], v[96:99]
	v_mfma_f32_16x16x32_bf16 v[84:87], v[204:207], v[236:239], v[84:87]
	v_mfma_f32_16x16x32_bf16 v[80:83], v[212:215], v[236:239], v[80:83]
	v_mfma_f32_16x16x32_bf16 v[68:71], v[204:207], v[244:247], v[68:71]
	v_mfma_f32_16x16x32_bf16 v[64:67], v[212:215], v[244:247], v[64:67]
	v_mfma_f32_16x16x32_bf16 v[116:119], v[208:211], v[224:227], v[116:119]
	v_mfma_f32_16x16x32_bf16 v[112:115], v[216:219], v[224:227], v[112:115]
	v_mfma_f32_16x16x32_bf16 v[100:103], v[208:211], v[232:235], v[100:103]
	v_mfma_f32_16x16x32_bf16 v[96:99], v[216:219], v[232:235], v[96:99]
	v_mfma_f32_16x16x32_bf16 v[84:87], v[208:211], v[240:243], v[84:87]
	v_mfma_f32_16x16x32_bf16 v[80:83], v[216:219], v[240:243], v[80:83]
	v_mfma_f32_16x16x32_bf16 v[68:71], v[208:211], v[248:251], v[68:71]
	v_mfma_f32_16x16x32_bf16 v[64:67], v[216:219], v[248:251], v[64:67]
	s_barrier
	s_setprio 1
	s_add_i32 s4, s45, s33
	v_lshl_add_u64 v[142:143], v[142:143], 0, s[26:27]
	s_mov_b32 m0, s4
	ds_read_b128 v[220:223], v170 offset:49152
	ds_read_b128 v[224:227], v170 offset:50176
	ds_read_b128 v[228:231], v170 offset:51200
	ds_read_b128 v[232:235], v170 offset:52224
	ds_read_b128 v[236:239], v170 offset:53248
	ds_read_b128 v[240:243], v170 offset:54272
	ds_read_b128 v[244:247], v170 offset:55296
	ds_read_b128 v[248:251], v170 offset:56320
	global_load_lds_dwordx4 v[142:143], off
	s_add_i32 m0, s4, 0x2000
	s_add_u32 s4, s34, 0x40080
	v_lshl_add_u64 v[142:143], v[158:159], 0, s[26:27]
	s_addc_u32 s5, s35, 0
	s_add_i32 s34, s51, s33
	global_load_lds_dwordx4 v[142:143], off
	v_lshl_add_u64 v[142:143], s[4:5], 0, v[128:129]
	s_mov_b32 m0, s34
	s_nop 0
	global_load_lds_dwordx4 v[142:143], off
	v_lshl_add_u64 v[142:143], s[4:5], 0, v[130:131]
	s_add_i32 m0, s34, 0x2000
	s_nop 0
	global_load_lds_dwordx4 v[142:143], off
	v_lshl_add_u64 v[142:143], v[180:181], 0, s[26:27]
	s_mov_b32 m0, s73
	s_nop 0
	global_load_lds_dwordx4 v[142:143], off
	v_lshl_add_u64 v[142:143], v[202:203], 0, s[26:27]
	s_mov_b32 m0, s74
	s_nop 0
	global_load_lds_dwordx4 v[142:143], off
	s_setprio 0
	s_waitcnt vmcnt(8)
	s_waitcnt lgkmcnt(0)
	s_barrier
	s_waitcnt lgkmcnt(0)
	v_mfma_f32_16x16x32_bf16 v[60:63], v[138:141], v[220:223], v[60:63]
	v_mfma_f32_16x16x32_bf16 v[56:59], v[172:175], v[220:223], v[56:59]
	v_mfma_f32_16x16x32_bf16 v[44:47], v[138:141], v[228:231], v[44:47]
	v_mfma_f32_16x16x32_bf16 v[40:43], v[172:175], v[228:231], v[40:43]
	v_mfma_f32_16x16x32_bf16 v[28:31], v[138:141], v[236:239], v[28:31]
	v_mfma_f32_16x16x32_bf16 v[24:27], v[172:175], v[236:239], v[24:27]
	v_mfma_f32_16x16x32_bf16 v[12:15], v[138:141], v[244:247], v[12:15]
	v_mfma_f32_16x16x32_bf16 v[8:11], v[172:175], v[244:247], v[8:11]
	v_mfma_f32_16x16x32_bf16 v[60:63], v[154:157], v[224:227], v[60:63]
	v_mfma_f32_16x16x32_bf16 v[56:59], v[176:179], v[224:227], v[56:59]
	v_mfma_f32_16x16x32_bf16 v[44:47], v[154:157], v[232:235], v[44:47]
	v_mfma_f32_16x16x32_bf16 v[40:43], v[176:179], v[232:235], v[40:43]
	v_mfma_f32_16x16x32_bf16 v[28:31], v[154:157], v[240:243], v[28:31]
	v_mfma_f32_16x16x32_bf16 v[24:27], v[176:179], v[240:243], v[24:27]
	v_mfma_f32_16x16x32_bf16 v[12:15], v[154:157], v[248:251], v[12:15]
	v_mfma_f32_16x16x32_bf16 v[8:11], v[176:179], v[248:251], v[8:11]
	v_mfma_f32_16x16x32_bf16 v[52:55], v[204:207], v[220:223], v[52:55]
	v_mfma_f32_16x16x32_bf16 v[48:51], v[212:215], v[220:223], v[48:51]
	v_mfma_f32_16x16x32_bf16 v[36:39], v[204:207], v[228:231], v[36:39]
	v_mfma_f32_16x16x32_bf16 v[32:35], v[212:215], v[228:231], v[32:35]
	v_mfma_f32_16x16x32_bf16 v[20:23], v[204:207], v[236:239], v[20:23]
	v_mfma_f32_16x16x32_bf16 v[16:19], v[212:215], v[236:239], v[16:19]
	v_mfma_f32_16x16x32_bf16 v[4:7], v[204:207], v[244:247], v[4:7]
	v_mfma_f32_16x16x32_bf16 v[0:3], v[212:215], v[244:247], v[0:3]
	v_mfma_f32_16x16x32_bf16 v[52:55], v[208:211], v[224:227], v[52:55]
	v_mfma_f32_16x16x32_bf16 v[48:51], v[216:219], v[224:227], v[48:51]
	v_mfma_f32_16x16x32_bf16 v[36:39], v[208:211], v[232:235], v[36:39]
	v_mfma_f32_16x16x32_bf16 v[32:35], v[216:219], v[232:235], v[32:35]
	v_mfma_f32_16x16x32_bf16 v[20:23], v[208:211], v[240:243], v[20:23]
	v_mfma_f32_16x16x32_bf16 v[16:19], v[216:219], v[240:243], v[16:19]
	v_mfma_f32_16x16x32_bf16 v[4:7], v[208:211], v[248:251], v[4:7]
	v_mfma_f32_16x16x32_bf16 v[0:3], v[216:219], v[248:251], v[0:3]
	s_barrier
	s_setprio 1
	s_add_i32 s29, s29, 2
	s_add_u32 s3, s3, 0x100
	s_addc_u32 s28, s28, 0
	s_cmp_gt_u32 s29, 13
	s_mov_b64 s[60:61], s[62:63]
	s_cbranch_scc0 .LBB0_1207
	s_setprio 0
	s_and_b64 vcc, exec, s[48:49]
	s_cbranch_vccz .LBB0_1210
	s_barrier

.LBB0_1305:
	s_setprio 1
	s_add_u32 s4, s2, 0xfffc0080
	s_addc_u32 s5, s3, -1
	s_add_i32 s74, 0, 0x10000
	s_cmp_eq_u32 s73, 12
	s_cselect_b32 s61, s36, s5
	s_cselect_b32 s60, s51, s4
	s_cselect_b32 s35, s49, s72
	s_cselect_b32 s34, s70, s71
	s_add_i32 s75, 0, 0x14000
	v_add_u32_e32 v164, s74, v143
	v_add_u32_e32 v180, s75, v143
	ds_read_b128 v[138:141], v164
	ds_read_b128 v[156:159], v164 offset:1024
	ds_read_b128 v[160:163], v164 offset:2048
	ds_read_b128 v[164:167], v164 offset:3072
	ds_read_b128 v[168:171], v180
	ds_read_b128 v[172:175], v180 offset:1024
	ds_read_b128 v[176:179], v180 offset:2048
	ds_read_b128 v[204:207], v180 offset:3072
	v_lshl_add_u64 v[180:181], s[2:3], 0, v[134:135]
	s_add_i32 m0, s59, 0xc000
	ds_read_b128 v[208:211], v155
	ds_read_b128 v[212:215], v155 offset:1024
	ds_read_b128 v[216:219], v155 offset:2048
	ds_read_b128 v[220:223], v155 offset:3072
	ds_read_b128 v[224:227], v155 offset:4096
	ds_read_b128 v[228:231], v155 offset:5120
	ds_read_b128 v[232:235], v155 offset:6144
	ds_read_b128 v[236:239], v155 offset:7168
	global_load_lds_dwordx4 v[180:181], off
	v_lshl_add_u64 v[180:181], s[2:3], 0, v[136:137]
	s_add_i32 m0, s59, 0xe000
	s_nop 0
	global_load_lds_dwordx4 v[180:181], off
	s_setprio 0
	s_waitcnt vmcnt(8)
	s_waitcnt lgkmcnt(0)
	s_barrier
	s_waitcnt lgkmcnt(0)
	v_mfma_f32_16x16x32_bf16 v[124:127], v[138:141], v[208:211], v[124:127]
	v_mfma_f32_16x16x32_bf16 v[120:123], v[160:163], v[208:211], v[120:123]
	v_mfma_f32_16x16x32_bf16 v[108:111], v[138:141], v[216:219], v[108:111]
	v_mfma_f32_16x16x32_bf16 v[104:107], v[160:163], v[216:219], v[104:107]
	v_mfma_f32_16x16x32_bf16 v[92:95], v[138:141], v[224:227], v[92:95]
	v_mfma_f32_16x16x32_bf16 v[88:91], v[160:163], v[224:227], v[88:91]
	v_mfma_f32_16x16x32_bf16 v[76:79], v[138:141], v[232:235], v[76:79]
	v_mfma_f32_16x16x32_bf16 v[72:75], v[160:163], v[232:235], v[72:75]
	v_mfma_f32_16x16x32_bf16 v[124:127], v[156:159], v[212:215], v[124:127]
	v_mfma_f32_16x16x32_bf16 v[120:123], v[164:167], v[212:215], v[120:123]
	v_mfma_f32_16x16x32_bf16 v[108:111], v[156:159], v[220:223], v[108:111]
	v_mfma_f32_16x16x32_bf16 v[104:107], v[164:167], v[220:223], v[104:107]
	v_mfma_f32_16x16x32_bf16 v[92:95], v[156:159], v[228:231], v[92:95]
	v_mfma_f32_16x16x32_bf16 v[88:91], v[164:167], v[228:231], v[88:91]
	v_mfma_f32_16x16x32_bf16 v[76:79], v[156:159], v[236:239], v[76:79]
	v_mfma_f32_16x16x32_bf16 v[72:75], v[164:167], v[236:239], v[72:75]
	v_mfma_f32_16x16x32_bf16 v[116:119], v[168:171], v[208:211], v[116:119]
	v_mfma_f32_16x16x32_bf16 v[112:115], v[176:179], v[208:211], v[112:115]
	v_mfma_f32_16x16x32_bf16 v[100:103], v[168:171], v[216:219], v[100:103]
	v_mfma_f32_16x16x32_bf16 v[96:99], v[176:179], v[216:219], v[96:99]
	v_mfma_f32_16x16x32_bf16 v[84:87], v[168:171], v[224:227], v[84:87]
	v_mfma_f32_16x16x32_bf16 v[80:83], v[176:179], v[224:227], v[80:83]
	v_mfma_f32_16x16x32_bf16 v[68:71], v[168:171], v[232:235], v[68:71]
	v_mfma_f32_16x16x32_bf16 v[64:67], v[176:179], v[232:235], v[64:67]
	v_mfma_f32_16x16x32_bf16 v[116:119], v[172:175], v[212:215], v[116:119]
	v_mfma_f32_16x16x32_bf16 v[112:115], v[204:207], v[212:215], v[112:115]
	v_mfma_f32_16x16x32_bf16 v[100:103], v[172:175], v[220:223], v[100:103]
	v_mfma_f32_16x16x32_bf16 v[96:99], v[204:207], v[220:223], v[96:99]
	v_mfma_f32_16x16x32_bf16 v[84:87], v[172:175], v[228:231], v[84:87]
	v_mfma_f32_16x16x32_bf16 v[80:83], v[204:207], v[228:231], v[80:83]
	v_mfma_f32_16x16x32_bf16 v[68:71], v[172:175], v[236:239], v[68:71]
	v_mfma_f32_16x16x32_bf16 v[64:67], v[204:207], v[236:239], v[64:67]
	s_barrier
	s_setprio 1
	s_add_i32 s4, s74, s1
	v_lshl_add_u64 v[180:181], s[34:35], 0, v[144:145]
	s_mov_b32 m0, s4
	ds_read_b128 v[208:211], v155 offset:16384
	ds_read_b128 v[212:215], v155 offset:17408
	ds_read_b128 v[216:219], v155 offset:18432
	ds_read_b128 v[220:223], v155 offset:19456
	ds_read_b128 v[224:227], v155 offset:20480
	ds_read_b128 v[228:231], v155 offset:21504
	ds_read_b128 v[232:235], v155 offset:22528
	ds_read_b128 v[236:239], v155 offset:23552
	global_load_lds_dwordx4 v[180:181], off
	s_add_i32 m0, s4, 0x2000
	s_add_u32 s4, s34, 0x40000
	v_lshl_add_u64 v[202:203], s[34:35], 0, v[128:129]
	s_addc_u32 s5, s35, 0
	s_add_i32 s74, s75, s1
	global_load_lds_dwordx4 v[202:203], off
	v_lshl_add_u64 v[240:241], s[4:5], 0, v[144:145]
	s_mov_b32 m0, s74
	v_lshl_add_u64 v[242:243], s[60:61], 0, v[130:131]
	global_load_lds_dwordx4 v[240:241], off
	v_lshl_add_u64 v[240:241], s[4:5], 0, v[128:129]
	s_add_i32 m0, s74, 0x2000
	s_nop 0
	global_load_lds_dwordx4 v[240:241], off
	v_lshl_add_u64 v[240:241], s[60:61], 0, v[132:133]
	s_mov_b32 m0, s59
	s_nop 0
	global_load_lds_dwordx4 v[240:241], off
	s_mov_b32 m0, s64
	s_nop 0
	global_load_lds_dwordx4 v[242:243], off
	s_setprio 0
	s_waitcnt vmcnt(8)
	s_waitcnt lgkmcnt(0)
	s_barrier
	s_waitcnt lgkmcnt(0)
	v_mfma_f32_16x16x32_bf16 v[60:63], v[138:141], v[208:211], v[60:63]
	v_mfma_f32_16x16x32_bf16 v[56:59], v[160:163], v[208:211], v[56:59]
	v_mfma_f32_16x16x32_bf16 v[44:47], v[138:141], v[216:219], v[44:47]
	v_mfma_f32_16x16x32_bf16 v[40:43], v[160:163], v[216:219], v[40:43]
	v_mfma_f32_16x16x32_bf16 v[28:31], v[138:141], v[224:227], v[28:31]
	v_mfma_f32_16x16x32_bf16 v[24:27], v[160:163], v[224:227], v[24:27]
	v_mfma_f32_16x16x32_bf16 v[12:15], v[138:141], v[232:235], v[12:15]
	v_mfma_f32_16x16x32_bf16 v[8:11], v[160:163], v[232:235], v[8:11]
	v_mfma_f32_16x16x32_bf16 v[60:63], v[156:159], v[212:215], v[60:63]
	v_mfma_f32_16x16x32_bf16 v[56:59], v[164:167], v[212:215], v[56:59]
	v_mfma_f32_16x16x32_bf16 v[44:47], v[156:159], v[220:223], v[44:47]
	v_mfma_f32_16x16x32_bf16 v[40:43], v[164:167], v[220:223], v[40:43]
	v_mfma_f32_16x16x32_bf16 v[28:31], v[156:159], v[228:231], v[28:31]
	v_mfma_f32_16x16x32_bf16 v[24:27], v[164:167], v[228:231], v[24:27]
	v_mfma_f32_16x16x32_bf16 v[12:15], v[156:159], v[236:239], v[12:15]
	v_mfma_f32_16x16x32_bf16 v[8:11], v[164:167], v[236:239], v[8:11]
	v_mfma_f32_16x16x32_bf16 v[52:55], v[168:171], v[208:211], v[52:55]
	v_mfma_f32_16x16x32_bf16 v[48:51], v[176:179], v[208:211], v[48:51]
	v_mfma_f32_16x16x32_bf16 v[36:39], v[168:171], v[216:219], v[36:39]
	v_mfma_f32_16x16x32_bf16 v[32:35], v[176:179], v[216:219], v[32:35]
	v_mfma_f32_16x16x32_bf16 v[20:23], v[168:171], v[224:227], v[20:23]
	v_mfma_f32_16x16x32_bf16 v[16:19], v[176:179], v[224:227], v[16:19]
	v_mfma_f32_16x16x32_bf16 v[4:7], v[168:171], v[232:235], v[4:7]
	v_mfma_f32_16x16x32_bf16 v[0:3], v[176:179], v[232:235], v[0:3]
	v_mfma_f32_16x16x32_bf16 v[52:55], v[172:175], v[212:215], v[52:55]
	v_mfma_f32_16x16x32_bf16 v[48:51], v[204:207], v[212:215], v[48:51]
	v_mfma_f32_16x16x32_bf16 v[36:39], v[172:175], v[220:223], v[36:39]
	v_mfma_f32_16x16x32_bf16 v[32:35], v[204:207], v[220:223], v[32:35]
	v_mfma_f32_16x16x32_bf16 v[20:23], v[172:175], v[228:231], v[20:23]
	v_mfma_f32_16x16x32_bf16 v[16:19], v[204:207], v[228:231], v[16:19]
	v_mfma_f32_16x16x32_bf16 v[4:7], v[172:175], v[236:239], v[4:7]
	v_mfma_f32_16x16x32_bf16 v[0:3], v[204:207], v[236:239], v[0:3]
	s_barrier
	s_setprio 1
	s_add_i32 s74, 0, 0x18000
	s_add_i32 s75, 0, 0x1c000
	v_add_u32_e32 v164, s74, v143
	v_add_u32_e32 v204, s75, v143
	ds_read_b128 v[138:141], v164
	ds_read_b128 v[156:159], v164 offset:1024
	ds_read_b128 v[160:163], v164 offset:2048
	ds_read_b128 v[164:167], v164 offset:3072
	ds_read_b128 v[168:171], v204
	ds_read_b128 v[172:175], v204 offset:1024
	ds_read_b128 v[176:179], v204 offset:2048
	ds_read_b128 v[204:207], v204 offset:3072
	s_add_u32 s4, s60, 0x40000
	s_addc_u32 s5, s61, 0
	s_mov_b32 m0, s65
	v_lshl_add_u64 v[244:245], s[4:5], 0, v[132:133]
	ds_read_b128 v[208:211], v155 offset:32768
	ds_read_b128 v[212:215], v155 offset:33792
	ds_read_b128 v[216:219], v155 offset:34816
	ds_read_b128 v[220:223], v155 offset:35840
	ds_read_b128 v[224:227], v155 offset:36864
	ds_read_b128 v[228:231], v155 offset:37888
	ds_read_b128 v[232:235], v155 offset:38912
	ds_read_b128 v[236:239], v155 offset:39936
	global_load_lds_dwordx4 v[244:245], off
	v_lshl_add_u64 v[244:245], s[4:5], 0, v[130:131]
	s_mov_b32 m0, s66
	s_nop 0
	global_load_lds_dwordx4 v[244:245], off
	s_setprio 0
	s_waitcnt vmcnt(8)
	s_waitcnt lgkmcnt(0)
	s_barrier
	s_waitcnt lgkmcnt(0)
	v_mfma_f32_16x16x32_bf16 v[124:127], v[138:141], v[208:211], v[124:127]
	v_mfma_f32_16x16x32_bf16 v[120:123], v[160:163], v[208:211], v[120:123]
	v_mfma_f32_16x16x32_bf16 v[108:111], v[138:141], v[216:219], v[108:111]
	v_mfma_f32_16x16x32_bf16 v[104:107], v[160:163], v[216:219], v[104:107]
	v_mfma_f32_16x16x32_bf16 v[92:95], v[138:141], v[224:227], v[92:95]
	v_mfma_f32_16x16x32_bf16 v[88:91], v[160:163], v[224:227], v[88:91]
	v_mfma_f32_16x16x32_bf16 v[76:79], v[138:141], v[232:235], v[76:79]
	v_mfma_f32_16x16x32_bf16 v[72:75], v[160:163], v[232:235], v[72:75]
	v_mfma_f32_16x16x32_bf16 v[124:127], v[156:159], v[212:215], v[124:127]
	v_mfma_f32_16x16x32_bf16 v[120:123], v[164:167], v[212:215], v[120:123]
	v_mfma_f32_16x16x32_bf16 v[108:111], v[156:159], v[220:223], v[108:111]
	v_mfma_f32_16x16x32_bf16 v[104:107], v[164:167], v[220:223], v[104:107]
	v_mfma_f32_16x16x32_bf16 v[92:95], v[156:159], v[228:231], v[92:95]
	v_mfma_f32_16x16x32_bf16 v[88:91], v[164:167], v[228:231], v[88:91]
	v_mfma_f32_16x16x32_bf16 v[76:79], v[156:159], v[236:239], v[76:79]
	v_mfma_f32_16x16x32_bf16 v[72:75], v[164:167], v[236:239], v[72:75]
	v_mfma_f32_16x16x32_bf16 v[116:119], v[168:171], v[208:211], v[116:119]
	v_mfma_f32_16x16x32_bf16 v[112:115], v[176:179], v[208:211], v[112:115]
	v_mfma_f32_16x16x32_bf16 v[100:103], v[168:171], v[216:219], v[100:103]
	v_mfma_f32_16x16x32_bf16 v[96:99], v[176:179], v[216:219], v[96:99]
	v_mfma_f32_16x16x32_bf16 v[84:87], v[168:171], v[224:227], v[84:87]
	v_mfma_f32_16x16x32_bf16 v[80:83], v[176:179], v[224:227], v[80:83]
	v_mfma_f32_16x16x32_bf16 v[68:71], v[168:171], v[232:235], v[68:71]
	v_mfma_f32_16x16x32_bf16 v[64:67], v[176:179], v[232:235], v[64:67]
	v_mfma_f32_16x16x32_bf16 v[116:119], v[172:175], v[212:215], v[116:119]
	v_mfma_f32_16x16x32_bf16 v[112:115], v[204:207], v[212:215], v[112:115]
	v_mfma_f32_16x16x32_bf16 v[100:103], v[172:175], v[220:223], v[100:103]
	v_mfma_f32_16x16x32_bf16 v[96:99], v[204:207], v[220:223], v[96:99]
	v_mfma_f32_16x16x32_bf16 v[84:87], v[172:175], v[228:231], v[84:87]
	v_mfma_f32_16x16x32_bf16 v[80:83], v[204:207], v[228:231], v[80:83]
	v_mfma_f32_16x16x32_bf16 v[68:71], v[172:175], v[236:239], v[68:71]
	v_mfma_f32_16x16x32_bf16 v[64:67], v[204:207], v[236:239], v[64:67]
	s_barrier
	s_setprio 1
	s_add_i32 s4, s74, s1
	v_lshl_add_u64 v[180:181], v[180:181], 0, s[26:27]
	s_mov_b32 m0, s4
	ds_read_b128 v[208:211], v155 offset:49152
	ds_read_b128 v[212:215], v155 offset:50176
	ds_read_b128 v[216:219], v155 offset:51200
	ds_read_b128 v[220:223], v155 offset:52224
	ds_read_b128 v[224:227], v155 offset:53248
	ds_read_b128 v[228:231], v155 offset:54272
	ds_read_b128 v[232:235], v155 offset:55296
	ds_read_b128 v[236:239], v155 offset:56320
	global_load_lds_dwordx4 v[180:181], off
	s_add_i32 m0, s4, 0x2000
	s_add_u32 s4, s34, 0x40080
	v_lshl_add_u64 v[180:181], v[202:203], 0, s[26:27]
	s_addc_u32 s5, s35, 0
	s_add_i32 s34, s75, s1
	global_load_lds_dwordx4 v[180:181], off
	v_lshl_add_u64 v[180:181], s[4:5], 0, v[144:145]
	s_mov_b32 m0, s34
	s_nop 0
	global_load_lds_dwordx4 v[180:181], off
	v_lshl_add_u64 v[180:181], s[4:5], 0, v[128:129]
	s_add_i32 m0, s34, 0x2000
	s_nop 0
	global_load_lds_dwordx4 v[180:181], off
	v_lshl_add_u64 v[180:181], v[240:241], 0, s[26:27]
	s_mov_b32 m0, s67
	s_nop 0
	global_load_lds_dwordx4 v[180:181], off
	v_lshl_add_u64 v[180:181], v[242:243], 0, s[26:27]
	s_mov_b32 m0, s68
	s_nop 0
	global_load_lds_dwordx4 v[180:181], off
	s_setprio 0
	s_waitcnt vmcnt(8)
	s_waitcnt lgkmcnt(0)
	s_barrier
	s_waitcnt lgkmcnt(0)
	v_mfma_f32_16x16x32_bf16 v[60:63], v[138:141], v[208:211], v[60:63]
	v_mfma_f32_16x16x32_bf16 v[56:59], v[160:163], v[208:211], v[56:59]
	v_mfma_f32_16x16x32_bf16 v[44:47], v[138:141], v[216:219], v[44:47]
	v_mfma_f32_16x16x32_bf16 v[40:43], v[160:163], v[216:219], v[40:43]
	v_mfma_f32_16x16x32_bf16 v[28:31], v[138:141], v[224:227], v[28:31]
	v_mfma_f32_16x16x32_bf16 v[24:27], v[160:163], v[224:227], v[24:27]
	v_mfma_f32_16x16x32_bf16 v[12:15], v[138:141], v[232:235], v[12:15]
	v_mfma_f32_16x16x32_bf16 v[8:11], v[160:163], v[232:235], v[8:11]
	v_mfma_f32_16x16x32_bf16 v[60:63], v[156:159], v[212:215], v[60:63]
	v_mfma_f32_16x16x32_bf16 v[56:59], v[164:167], v[212:215], v[56:59]
	v_mfma_f32_16x16x32_bf16 v[44:47], v[156:159], v[220:223], v[44:47]
	v_mfma_f32_16x16x32_bf16 v[40:43], v[164:167], v[220:223], v[40:43]
	v_mfma_f32_16x16x32_bf16 v[28:31], v[156:159], v[228:231], v[28:31]
	v_mfma_f32_16x16x32_bf16 v[24:27], v[164:167], v[228:231], v[24:27]
	v_mfma_f32_16x16x32_bf16 v[12:15], v[156:159], v[236:239], v[12:15]
	v_mfma_f32_16x16x32_bf16 v[8:11], v[164:167], v[236:239], v[8:11]
	v_mfma_f32_16x16x32_bf16 v[52:55], v[168:171], v[208:211], v[52:55]
	v_mfma_f32_16x16x32_bf16 v[48:51], v[176:179], v[208:211], v[48:51]
	v_mfma_f32_16x16x32_bf16 v[36:39], v[168:171], v[216:219], v[36:39]
	v_mfma_f32_16x16x32_bf16 v[32:35], v[176:179], v[216:219], v[32:35]
	v_mfma_f32_16x16x32_bf16 v[20:23], v[168:171], v[224:227], v[20:23]
	v_mfma_f32_16x16x32_bf16 v[16:19], v[176:179], v[224:227], v[16:19]
	v_mfma_f32_16x16x32_bf16 v[4:7], v[168:171], v[232:235], v[4:7]
	v_mfma_f32_16x16x32_bf16 v[0:3], v[176:179], v[232:235], v[0:3]
	v_mfma_f32_16x16x32_bf16 v[52:55], v[172:175], v[212:215], v[52:55]
	v_mfma_f32_16x16x32_bf16 v[48:51], v[204:207], v[212:215], v[48:51]
	v_mfma_f32_16x16x32_bf16 v[36:39], v[172:175], v[220:223], v[36:39]
	v_mfma_f32_16x16x32_bf16 v[32:35], v[204:207], v[220:223], v[32:35]
	v_mfma_f32_16x16x32_bf16 v[20:23], v[172:175], v[228:231], v[20:23]
	v_mfma_f32_16x16x32_bf16 v[16:19], v[204:207], v[228:231], v[16:19]
	v_mfma_f32_16x16x32_bf16 v[4:7], v[172:175], v[236:239], v[4:7]
	v_mfma_f32_16x16x32_bf16 v[0:3], v[204:207], v[236:239], v[0:3]
	s_barrier
	s_setprio 1
	s_add_i32 s73, s73, 2
	s_add_u32 s2, s2, 0x100
	s_addc_u32 s3, s3, 0
	s_add_u32 s71, s71, 0x100
	s_addc_u32 s72, s72, 0
	s_cmp_gt_u32 s73, 13
	s_cbranch_scc0 .LBB0_1305
	s_setprio 0
	v_lshl_add_u32 v140, s58, 8, v142
	v_ashrrev_i32_e32 v141, 31, v140
	v_lshl_add_u64 v[156:157], v[140:141], 4, s[44:45]
	global_load_dwordx4 v[208:211], v[156:157], off
	global_load_dwordx4 v[212:215], v[156:157], off offset:256
	global_load_dwordx4 v[216:219], v[156:157], off offset:512
	global_load_dwordx4 v[220:223], v[156:157], off offset:768
	global_load_dwordx4 v[224:227], v[156:157], off offset:2048
	global_load_dwordx4 v[228:231], v[156:157], off offset:2304
	global_load_dwordx4 v[232:235], v[156:157], off offset:2560
	global_load_dwordx4 v[236:239], v[156:157], off offset:2816
	s_and_b64 vcc, exec, s[46:47]
	s_cbranch_vccz .LBB0_1308
	s_barrier

.LBB0_1399:
	s_setprio 1
	s_add_u32 s58, s54, 0x100
	s_addc_u32 s59, s55, 0
	s_add_i32 s4, 0, 0x10000
	s_cmp_eq_u32 s29, 40
	s_cselect_b32 s61, s45, s59
	s_cselect_b32 s60, s44, s58
	v_add_u32_e32 v142, s4, v160
	s_cselect_b32 s35, s53, s28
	s_cselect_b32 s34, s52, s3
	s_add_i32 s47, 0, 0x14000
	ds_read_b128 v[138:141], v142
	ds_read_b128 v[154:157], v142 offset:1024
	ds_read_b128 v[172:175], v142 offset:2048
	ds_read_b128 v[176:179], v142 offset:3072
	v_add_u32_e32 v142, s47, v160
	ds_read_b128 v[204:207], v142
	ds_read_b128 v[208:211], v142 offset:1024
	ds_read_b128 v[212:215], v142 offset:2048
	ds_read_b128 v[216:219], v142 offset:3072
	v_lshl_add_u64 v[142:143], s[54:55], 0, v[134:135]
	s_add_i32 m0, s65, 0xc000
	ds_read_b128 v[220:223], v170
	ds_read_b128 v[224:227], v170 offset:1024
	ds_read_b128 v[228:231], v170 offset:2048
	ds_read_b128 v[232:235], v170 offset:3072
	ds_read_b128 v[236:239], v170 offset:4096
	ds_read_b128 v[240:243], v170 offset:5120
	ds_read_b128 v[244:247], v170 offset:6144
	ds_read_b128 v[248:251], v170 offset:7168
	global_load_lds_dwordx4 v[142:143], off
	v_lshl_add_u64 v[142:143], s[54:55], 0, v[136:137]
	s_add_i32 m0, s65, 0xe000
	s_nop 0
	global_load_lds_dwordx4 v[142:143], off
	s_setprio 0
	s_waitcnt vmcnt(8)
	s_waitcnt lgkmcnt(0)
	s_barrier
	s_waitcnt lgkmcnt(0)
	v_mfma_f32_16x16x32_bf16 v[124:127], v[138:141], v[220:223], v[124:127]
	v_mfma_f32_16x16x32_bf16 v[120:123], v[172:175], v[220:223], v[120:123]
	v_mfma_f32_16x16x32_bf16 v[108:111], v[138:141], v[228:231], v[108:111]
	v_mfma_f32_16x16x32_bf16 v[104:107], v[172:175], v[228:231], v[104:107]
	v_mfma_f32_16x16x32_bf16 v[92:95], v[138:141], v[236:239], v[92:95]
	v_mfma_f32_16x16x32_bf16 v[88:91], v[172:175], v[236:239], v[88:91]
	v_mfma_f32_16x16x32_bf16 v[76:79], v[138:141], v[244:247], v[76:79]
	v_mfma_f32_16x16x32_bf16 v[72:75], v[172:175], v[244:247], v[72:75]
	v_mfma_f32_16x16x32_bf16 v[124:127], v[154:157], v[224:227], v[124:127]
	v_mfma_f32_16x16x32_bf16 v[120:123], v[176:179], v[224:227], v[120:123]
	v_mfma_f32_16x16x32_bf16 v[108:111], v[154:157], v[232:235], v[108:111]
	v_mfma_f32_16x16x32_bf16 v[104:107], v[176:179], v[232:235], v[104:107]
	v_mfma_f32_16x16x32_bf16 v[92:95], v[154:157], v[240:243], v[92:95]
	v_mfma_f32_16x16x32_bf16 v[88:91], v[176:179], v[240:243], v[88:91]
	v_mfma_f32_16x16x32_bf16 v[76:79], v[154:157], v[248:251], v[76:79]
	v_mfma_f32_16x16x32_bf16 v[72:75], v[176:179], v[248:251], v[72:75]
	v_mfma_f32_16x16x32_bf16 v[116:119], v[204:207], v[220:223], v[116:119]
	v_mfma_f32_16x16x32_bf16 v[112:115], v[212:215], v[220:223], v[112:115]
	v_mfma_f32_16x16x32_bf16 v[100:103], v[204:207], v[228:231], v[100:103]
	v_mfma_f32_16x16x32_bf16 v[96:99], v[212:215], v[228:231], v[96:99]
	v_mfma_f32_16x16x32_bf16 v[84:87], v[204:207], v[236:239], v[84:87]
	v_mfma_f32_16x16x32_bf16 v[80:83], v[212:215], v[236:239], v[80:83]
	v_mfma_f32_16x16x32_bf16 v[68:71], v[204:207], v[244:247], v[68:71]
	v_mfma_f32_16x16x32_bf16 v[64:67], v[212:215], v[244:247], v[64:67]
	v_mfma_f32_16x16x32_bf16 v[116:119], v[208:211], v[224:227], v[116:119]
	v_mfma_f32_16x16x32_bf16 v[112:115], v[216:219], v[224:227], v[112:115]
	v_mfma_f32_16x16x32_bf16 v[100:103], v[208:211], v[232:235], v[100:103]
	v_mfma_f32_16x16x32_bf16 v[96:99], v[216:219], v[232:235], v[96:99]
	v_mfma_f32_16x16x32_bf16 v[84:87], v[208:211], v[240:243], v[84:87]
	v_mfma_f32_16x16x32_bf16 v[80:83], v[216:219], v[240:243], v[80:83]
	v_mfma_f32_16x16x32_bf16 v[68:71], v[208:211], v[248:251], v[68:71]
	v_mfma_f32_16x16x32_bf16 v[64:67], v[216:219], v[248:251], v[64:67]
	s_barrier
	s_setprio 1
	s_add_i32 s4, s4, s33
	v_lshl_add_u64 v[142:143], s[34:35], 0, v[128:129]
	s_mov_b32 m0, s4
	ds_read_b128 v[220:223], v170 offset:16384
	ds_read_b128 v[224:227], v170 offset:17408
	ds_read_b128 v[228:231], v170 offset:18432
	ds_read_b128 v[232:235], v170 offset:19456
	ds_read_b128 v[236:239], v170 offset:20480
	ds_read_b128 v[240:243], v170 offset:21504
	ds_read_b128 v[244:247], v170 offset:22528
	ds_read_b128 v[248:251], v170 offset:23552
	global_load_lds_dwordx4 v[142:143], off
	s_add_i32 m0, s4, 0x2000
	s_add_u32 s4, s34, 0xb0000
	v_lshl_add_u64 v[158:159], s[34:35], 0, v[130:131]
	s_addc_u32 s5, s35, 0
	s_add_i32 s47, s47, s33
	global_load_lds_dwordx4 v[158:159], off
	v_lshl_add_u64 v[180:181], s[4:5], 0, v[128:129]
	s_mov_b32 m0, s47
	v_lshl_add_u64 v[202:203], s[60:61], 0, v[130:131]
	global_load_lds_dwordx4 v[180:181], off
	v_lshl_add_u64 v[180:181], s[4:5], 0, v[130:131]
	s_add_i32 m0, s47, 0x2000
	s_nop 0
	global_load_lds_dwordx4 v[180:181], off
	v_lshl_add_u64 v[180:181], s[60:61], 0, v[128:129]
	s_mov_b32 m0, s65
	s_nop 0
	global_load_lds_dwordx4 v[180:181], off
	s_mov_b32 m0, s66
	s_nop 0
	global_load_lds_dwordx4 v[202:203], off
	s_setprio 0
	s_waitcnt vmcnt(8)
	s_waitcnt lgkmcnt(0)
	s_barrier
	s_waitcnt lgkmcnt(0)
	v_mfma_f32_16x16x32_bf16 v[60:63], v[138:141], v[220:223], v[60:63]
	v_mfma_f32_16x16x32_bf16 v[56:59], v[172:175], v[220:223], v[56:59]
	v_mfma_f32_16x16x32_bf16 v[44:47], v[138:141], v[228:231], v[44:47]
	v_mfma_f32_16x16x32_bf16 v[40:43], v[172:175], v[228:231], v[40:43]
	v_mfma_f32_16x16x32_bf16 v[28:31], v[138:141], v[236:239], v[28:31]
	v_mfma_f32_16x16x32_bf16 v[24:27], v[172:175], v[236:239], v[24:27]
	v_mfma_f32_16x16x32_bf16 v[12:15], v[138:141], v[244:247], v[12:15]
	v_mfma_f32_16x16x32_bf16 v[8:11], v[172:175], v[244:247], v[8:11]
	v_mfma_f32_16x16x32_bf16 v[60:63], v[154:157], v[224:227], v[60:63]
	v_mfma_f32_16x16x32_bf16 v[56:59], v[176:179], v[224:227], v[56:59]
	v_mfma_f32_16x16x32_bf16 v[44:47], v[154:157], v[232:235], v[44:47]
	v_mfma_f32_16x16x32_bf16 v[40:43], v[176:179], v[232:235], v[40:43]
	v_mfma_f32_16x16x32_bf16 v[28:31], v[154:157], v[240:243], v[28:31]
	v_mfma_f32_16x16x32_bf16 v[24:27], v[176:179], v[240:243], v[24:27]
	v_mfma_f32_16x16x32_bf16 v[12:15], v[154:157], v[248:251], v[12:15]
	v_mfma_f32_16x16x32_bf16 v[8:11], v[176:179], v[248:251], v[8:11]
	v_mfma_f32_16x16x32_bf16 v[52:55], v[204:207], v[220:223], v[52:55]
	v_mfma_f32_16x16x32_bf16 v[48:51], v[212:215], v[220:223], v[48:51]
	v_mfma_f32_16x16x32_bf16 v[36:39], v[204:207], v[228:231], v[36:39]
	v_mfma_f32_16x16x32_bf16 v[32:35], v[212:215], v[228:231], v[32:35]
	v_mfma_f32_16x16x32_bf16 v[20:23], v[204:207], v[236:239], v[20:23]
	v_mfma_f32_16x16x32_bf16 v[16:19], v[212:215], v[236:239], v[16:19]
	v_mfma_f32_16x16x32_bf16 v[4:7], v[204:207], v[244:247], v[4:7]
	v_mfma_f32_16x16x32_bf16 v[0:3], v[212:215], v[244:247], v[0:3]
	v_mfma_f32_16x16x32_bf16 v[52:55], v[208:211], v[224:227], v[52:55]
	v_mfma_f32_16x16x32_bf16 v[48:51], v[216:219], v[224:227], v[48:51]
	v_mfma_f32_16x16x32_bf16 v[36:39], v[208:211], v[232:235], v[36:39]
	v_mfma_f32_16x16x32_bf16 v[32:35], v[216:219], v[232:235], v[32:35]
	v_mfma_f32_16x16x32_bf16 v[20:23], v[208:211], v[240:243], v[20:23]
	v_mfma_f32_16x16x32_bf16 v[16:19], v[216:219], v[240:243], v[16:19]
	v_mfma_f32_16x16x32_bf16 v[4:7], v[208:211], v[248:251], v[4:7]
	v_mfma_f32_16x16x32_bf16 v[0:3], v[216:219], v[248:251], v[0:3]
	s_barrier
	s_setprio 1
	s_add_i32 s47, 0, 0x18000
	v_add_u32_e32 v144, s47, v160
	s_add_i32 s54, 0, 0x1c000
	ds_read_b128 v[138:141], v144
	ds_read_b128 v[154:157], v144 offset:1024
	ds_read_b128 v[172:175], v144 offset:2048
	ds_read_b128 v[176:179], v144 offset:3072
	v_add_u32_e32 v144, s54, v160
	ds_read_b128 v[204:207], v144
	ds_read_b128 v[208:211], v144 offset:1024
	ds_read_b128 v[212:215], v144 offset:2048
	ds_read_b128 v[216:219], v144 offset:3072
	s_add_u32 s4, s60, 0xb0000
	s_addc_u32 s5, s61, 0
	s_mov_b32 m0, s67
	v_lshl_add_u64 v[252:253], s[4:5], 0, v[128:129]
	ds_read_b128 v[220:223], v170 offset:32768
	ds_read_b128 v[224:227], v170 offset:33792
	ds_read_b128 v[228:231], v170 offset:34816
	ds_read_b128 v[232:235], v170 offset:35840
	ds_read_b128 v[236:239], v170 offset:36864
	ds_read_b128 v[240:243], v170 offset:37888
	ds_read_b128 v[244:247], v170 offset:38912
	ds_read_b128 v[248:251], v170 offset:39936
	global_load_lds_dwordx4 v[252:253], off
	v_lshl_add_u64 v[252:253], s[4:5], 0, v[130:131]
	s_mov_b32 m0, s68
	s_nop 0
	global_load_lds_dwordx4 v[252:253], off
	s_setprio 0
	s_waitcnt vmcnt(8)
	s_waitcnt lgkmcnt(0)
	s_barrier
	s_waitcnt lgkmcnt(0)
	v_mfma_f32_16x16x32_bf16 v[124:127], v[138:141], v[220:223], v[124:127]
	v_mfma_f32_16x16x32_bf16 v[120:123], v[172:175], v[220:223], v[120:123]
	v_mfma_f32_16x16x32_bf16 v[108:111], v[138:141], v[228:231], v[108:111]
	v_mfma_f32_16x16x32_bf16 v[104:107], v[172:175], v[228:231], v[104:107]
	v_mfma_f32_16x16x32_bf16 v[92:95], v[138:141], v[236:239], v[92:95]
	v_mfma_f32_16x16x32_bf16 v[88:91], v[172:175], v[236:239], v[88:91]
	v_mfma_f32_16x16x32_bf16 v[76:79], v[138:141], v[244:247], v[76:79]
	v_mfma_f32_16x16x32_bf16 v[72:75], v[172:175], v[244:247], v[72:75]
	v_mfma_f32_16x16x32_bf16 v[124:127], v[154:157], v[224:227], v[124:127]
	v_mfma_f32_16x16x32_bf16 v[120:123], v[176:179], v[224:227], v[120:123]
	v_mfma_f32_16x16x32_bf16 v[108:111], v[154:157], v[232:235], v[108:111]
	v_mfma_f32_16x16x32_bf16 v[104:107], v[176:179], v[232:235], v[104:107]
	v_mfma_f32_16x16x32_bf16 v[92:95], v[154:157], v[240:243], v[92:95]
	v_mfma_f32_16x16x32_bf16 v[88:91], v[176:179], v[240:243], v[88:91]
	v_mfma_f32_16x16x32_bf16 v[76:79], v[154:157], v[248:251], v[76:79]
	v_mfma_f32_16x16x32_bf16 v[72:75], v[176:179], v[248:251], v[72:75]
	v_mfma_f32_16x16x32_bf16 v[116:119], v[204:207], v[220:223], v[116:119]
	v_mfma_f32_16x16x32_bf16 v[112:115], v[212:215], v[220:223], v[112:115]
	v_mfma_f32_16x16x32_bf16 v[100:103], v[204:207], v[228:231], v[100:103]
	v_mfma_f32_16x16x32_bf16 v[96:99], v[212:215], v[228:231], v[96:99]
	v_mfma_f32_16x16x32_bf16 v[84:87], v[204:207], v[236:239], v[84:87]
	v_mfma_f32_16x16x32_bf16 v[80:83], v[212:215], v[236:239], v[80:83]
	v_mfma_f32_16x16x32_bf16 v[68:71], v[204:207], v[244:247], v[68:71]
	v_mfma_f32_16x16x32_bf16 v[64:67], v[212:215], v[244:247], v[64:67]
	v_mfma_f32_16x16x32_bf16 v[116:119], v[208:211], v[224:227], v[116:119]
	v_mfma_f32_16x16x32_bf16 v[112:115], v[216:219], v[224:227], v[112:115]
	v_mfma_f32_16x16x32_bf16 v[100:103], v[208:211], v[232:235], v[100:103]
	v_mfma_f32_16x16x32_bf16 v[96:99], v[216:219], v[232:235], v[96:99]
	v_mfma_f32_16x16x32_bf16 v[84:87], v[208:211], v[240:243], v[84:87]
	v_mfma_f32_16x16x32_bf16 v[80:83], v[216:219], v[240:243], v[80:83]
	v_mfma_f32_16x16x32_bf16 v[68:71], v[208:211], v[248:251], v[68:71]
	v_mfma_f32_16x16x32_bf16 v[64:67], v[216:219], v[248:251], v[64:67]
	s_barrier
	s_setprio 1
	s_add_i32 s4, s47, s33
	v_lshl_add_u64 v[142:143], v[142:143], 0, s[26:27]
	s_mov_b32 m0, s4
	ds_read_b128 v[220:223], v170 offset:49152
	ds_read_b128 v[224:227], v170 offset:50176
	ds_read_b128 v[228:231], v170 offset:51200
	ds_read_b128 v[232:235], v170 offset:52224
	ds_read_b128 v[236:239], v170 offset:53248
	ds_read_b128 v[240:243], v170 offset:54272
	ds_read_b128 v[244:247], v170 offset:55296
	ds_read_b128 v[248:251], v170 offset:56320
	global_load_lds_dwordx4 v[142:143], off
	s_add_i32 m0, s4, 0x2000
	s_add_u32 s4, s34, 0xb0080
	v_lshl_add_u64 v[142:143], v[158:159], 0, s[26:27]
	s_addc_u32 s5, s35, 0
	s_add_i32 s34, s54, s33
	global_load_lds_dwordx4 v[142:143], off
	v_lshl_add_u64 v[142:143], s[4:5], 0, v[128:129]
	s_mov_b32 m0, s34
	s_nop 0
	global_load_lds_dwordx4 v[142:143], off
	v_lshl_add_u64 v[142:143], s[4:5], 0, v[130:131]
	s_add_i32 m0, s34, 0x2000
	s_nop 0
	global_load_lds_dwordx4 v[142:143], off
	v_lshl_add_u64 v[142:143], v[180:181], 0, s[26:27]
	s_mov_b32 m0, s69
	s_nop 0
	global_load_lds_dwordx4 v[142:143], off
	v_lshl_add_u64 v[142:143], v[202:203], 0, s[26:27]
	s_mov_b32 m0, s70
	s_nop 0
	global_load_lds_dwordx4 v[142:143], off
	s_setprio 0
	s_waitcnt vmcnt(8)
	s_waitcnt lgkmcnt(0)
	s_barrier
	s_waitcnt lgkmcnt(0)
	v_mfma_f32_16x16x32_bf16 v[60:63], v[138:141], v[220:223], v[60:63]
	v_mfma_f32_16x16x32_bf16 v[56:59], v[172:175], v[220:223], v[56:59]
	v_mfma_f32_16x16x32_bf16 v[44:47], v[138:141], v[228:231], v[44:47]
	v_mfma_f32_16x16x32_bf16 v[40:43], v[172:175], v[228:231], v[40:43]
	v_mfma_f32_16x16x32_bf16 v[28:31], v[138:141], v[236:239], v[28:31]
	v_mfma_f32_16x16x32_bf16 v[24:27], v[172:175], v[236:239], v[24:27]
	v_mfma_f32_16x16x32_bf16 v[12:15], v[138:141], v[244:247], v[12:15]
	v_mfma_f32_16x16x32_bf16 v[8:11], v[172:175], v[244:247], v[8:11]
	v_mfma_f32_16x16x32_bf16 v[60:63], v[154:157], v[224:227], v[60:63]
	v_mfma_f32_16x16x32_bf16 v[56:59], v[176:179], v[224:227], v[56:59]
	v_mfma_f32_16x16x32_bf16 v[44:47], v[154:157], v[232:235], v[44:47]
	v_mfma_f32_16x16x32_bf16 v[40:43], v[176:179], v[232:235], v[40:43]
	v_mfma_f32_16x16x32_bf16 v[28:31], v[154:157], v[240:243], v[28:31]
	v_mfma_f32_16x16x32_bf16 v[24:27], v[176:179], v[240:243], v[24:27]
	v_mfma_f32_16x16x32_bf16 v[12:15], v[154:157], v[248:251], v[12:15]
	v_mfma_f32_16x16x32_bf16 v[8:11], v[176:179], v[248:251], v[8:11]
	v_mfma_f32_16x16x32_bf16 v[52:55], v[204:207], v[220:223], v[52:55]
	v_mfma_f32_16x16x32_bf16 v[48:51], v[212:215], v[220:223], v[48:51]
	v_mfma_f32_16x16x32_bf16 v[36:39], v[204:207], v[228:231], v[36:39]
	v_mfma_f32_16x16x32_bf16 v[32:35], v[212:215], v[228:231], v[32:35]
	v_mfma_f32_16x16x32_bf16 v[20:23], v[204:207], v[236:239], v[20:23]
	v_mfma_f32_16x16x32_bf16 v[16:19], v[212:215], v[236:239], v[16:19]
	v_mfma_f32_16x16x32_bf16 v[4:7], v[204:207], v[244:247], v[4:7]
	v_mfma_f32_16x16x32_bf16 v[0:3], v[212:215], v[244:247], v[0:3]
	v_mfma_f32_16x16x32_bf16 v[52:55], v[208:211], v[224:227], v[52:55]
	v_mfma_f32_16x16x32_bf16 v[48:51], v[216:219], v[224:227], v[48:51]
	v_mfma_f32_16x16x32_bf16 v[36:39], v[208:211], v[232:235], v[36:39]
	v_mfma_f32_16x16x32_bf16 v[32:35], v[216:219], v[232:235], v[32:35]
	v_mfma_f32_16x16x32_bf16 v[20:23], v[208:211], v[240:243], v[20:23]
	v_mfma_f32_16x16x32_bf16 v[16:19], v[216:219], v[240:243], v[16:19]
	v_mfma_f32_16x16x32_bf16 v[4:7], v[208:211], v[248:251], v[4:7]
	v_mfma_f32_16x16x32_bf16 v[0:3], v[216:219], v[248:251], v[0:3]
	s_barrier
	s_setprio 1
	s_add_i32 s29, s29, 2
	s_add_u32 s3, s3, 0x100
	s_addc_u32 s28, s28, 0
	s_cmp_gt_u32 s29, 41
	s_mov_b64 s[54:55], s[58:59]
	s_cbranch_scc0 .LBB0_1399
	s_setprio 0
	s_and_b64 vcc, exec, s[50:51]
	s_cbranch_vccz .LBB0_1402
	s_barrier
